# K-loop: post-MFMA barrier moved ahead of the block's last MFMA, which issues at priority 2 after release; then priority 0 for the load segment (on top of v18)
# baseline (speedup 1.0000x reference)
.LBB0_92:
	ds_read_b128 v[146:149], v143
	ds_read_b128 v[150:153], v143 offset:1024
	ds_read_b128 v[154:157], v143 offset:2048
	ds_read_b128 v[158:161], v143 offset:3072
	ds_read_b128 v[162:165], v144
	ds_read_b128 v[166:169], v144 offset:1024
	ds_read_b128 v[170:173], v144 offset:2048
	ds_read_b128 v[178:181], v144 offset:3072
	ds_read_b128 v[182:185], v145
	ds_read_b128 v[186:189], v145 offset:1024
	ds_read_b128 v[190:193], v145 offset:2048
	ds_read_b128 v[194:197], v145 offset:3072
	ds_read_b128 v[198:201], v145 offset:4096
	ds_read_b128 v[206:209], v145 offset:5120
	ds_read_b128 v[210:213], v145 offset:6144
	ds_read_b128 v[214:217], v145 offset:7168
	s_add_i32 m0, s27, 0xc000
	v_lshl_add_u64 v[174:175], s[28:29], 0, v[136:137]
	global_load_lds_dwordx4 v[174:175], off
	s_add_i32 m0, s27, 0xe000
	v_lshl_add_u64 v[174:175], s[28:29], 0, v[138:139]
	global_load_lds_dwordx4 v[174:175], off
	s_waitcnt vmcnt(8) lgkmcnt(0)
	s_setprio 1
	s_barrier
	v_mfma_f32_16x16x32_bf16 v[124:127], v[146:149], v[182:185], v[124:127]
	v_mfma_f32_16x16x32_bf16 v[120:123], v[154:157], v[182:185], v[120:123]
	v_mfma_f32_16x16x32_bf16 v[116:119], v[146:149], v[190:193], v[116:119]
	s_add_u32 s0, s28, 0xfff80080
	v_mfma_f32_16x16x32_bf16 v[108:111], v[154:157], v[190:193], v[108:111]
	s_addc_u32 s1, s29, -1
	v_mfma_f32_16x16x32_bf16 v[100:103], v[146:149], v[198:201], v[100:103]
	s_cmp_eq_u32 s68, 28
	v_mfma_f32_16x16x32_bf16 v[92:95], v[154:157], v[198:201], v[92:95]
	s_cselect_b32 s35, s13, s1
	v_mfma_f32_16x16x32_bf16 v[84:87], v[146:149], v[210:213], v[84:87]
	s_cselect_b32 s34, s63, s0
	v_mfma_f32_16x16x32_bf16 v[76:79], v[154:157], v[210:213], v[76:79]
	s_cselect_b32 s31, s64, s67
	v_mfma_f32_16x16x32_bf16 v[124:127], v[150:153], v[186:189], v[124:127]
	s_cselect_b32 s30, s65, s66
	v_mfma_f32_16x16x32_bf16 v[120:123], v[158:161], v[186:189], v[120:123]
	v_mfma_f32_16x16x32_bf16 v[116:119], v[150:153], v[194:197], v[116:119]
	v_mfma_f32_16x16x32_bf16 v[108:111], v[158:161], v[194:197], v[108:111]
	v_mfma_f32_16x16x32_bf16 v[100:103], v[150:153], v[206:209], v[100:103]
	v_mfma_f32_16x16x32_bf16 v[92:95], v[158:161], v[206:209], v[92:95]
	v_mfma_f32_16x16x32_bf16 v[84:87], v[150:153], v[214:217], v[84:87]
	v_mfma_f32_16x16x32_bf16 v[76:79], v[158:161], v[214:217], v[76:79]
	v_mfma_f32_16x16x32_bf16 v[112:115], v[162:165], v[182:185], v[112:115]
	v_mfma_f32_16x16x32_bf16 v[104:107], v[170:173], v[182:185], v[104:107]
	v_mfma_f32_16x16x32_bf16 v[96:99], v[162:165], v[190:193], v[96:99]
	v_mfma_f32_16x16x32_bf16 v[88:91], v[170:173], v[190:193], v[88:91]
	v_mfma_f32_16x16x32_bf16 v[80:83], v[162:165], v[198:201], v[80:83]
	v_mfma_f32_16x16x32_bf16 v[72:75], v[170:173], v[198:201], v[72:75]
	v_mfma_f32_16x16x32_bf16 v[68:71], v[162:165], v[210:213], v[68:71]
	v_mfma_f32_16x16x32_bf16 v[64:67], v[170:173], v[210:213], v[64:67]
	v_mfma_f32_16x16x32_bf16 v[112:115], v[166:169], v[186:189], v[112:115]
	v_mfma_f32_16x16x32_bf16 v[104:107], v[178:181], v[186:189], v[104:107]
	v_mfma_f32_16x16x32_bf16 v[96:99], v[166:169], v[194:197], v[96:99]
	v_mfma_f32_16x16x32_bf16 v[88:91], v[178:181], v[194:197], v[88:91]
	v_mfma_f32_16x16x32_bf16 v[80:83], v[166:169], v[206:209], v[80:83]
	v_mfma_f32_16x16x32_bf16 v[72:75], v[178:181], v[206:209], v[72:75]
	v_mfma_f32_16x16x32_bf16 v[68:71], v[166:169], v[214:217], v[68:71]
	s_setprio 2
	s_barrier
	v_mfma_f32_16x16x32_bf16 v[64:67], v[178:181], v[214:217], v[64:67]
	s_setprio 0
	ds_read_b128 v[182:185], v145 offset:16384
	ds_read_b128 v[186:189], v145 offset:17408
	ds_read_b128 v[190:193], v145 offset:18432
	ds_read_b128 v[194:197], v145 offset:19456
	ds_read_b128 v[198:201], v145 offset:20480
	ds_read_b128 v[206:209], v145 offset:21504
	ds_read_b128 v[210:213], v145 offset:22528
	ds_read_b128 v[214:217], v145 offset:23552
	s_add_i32 s0, s58, s48
	s_mov_b32 m0, s0
	v_lshl_add_u64 v[174:175], s[30:31], 0, v[132:133]
	global_load_lds_dwordx4 v[174:175], off
	s_add_i32 m0, s0, 0x2000
	s_add_u32 s0, s30, 0x80000
	v_lshl_add_u64 v[202:203], s[30:31], 0, v[128:129]
	s_addc_u32 s1, s31, 0
	s_add_i32 s2, s59, s48
	global_load_lds_dwordx4 v[202:203], off
	v_lshl_add_u64 v[218:219], s[0:1], 0, v[132:133]
	s_mov_b32 m0, s2
	v_lshl_add_u64 v[220:221], s[34:35], 0, v[130:131]
	global_load_lds_dwordx4 v[218:219], off
	s_add_i32 m0, s2, 0x2000
	v_lshl_add_u64 v[218:219], s[0:1], 0, v[128:129]
	global_load_lds_dwordx4 v[218:219], off
	s_mov_b32 m0, s27
	v_lshl_add_u64 v[218:219], s[34:35], 0, v[134:135]
	global_load_lds_dwordx4 v[218:219], off
	s_mov_b32 m0, s50
	s_nop 0
	global_load_lds_dwordx4 v[220:221], off
	s_waitcnt vmcnt(8) lgkmcnt(0)
	s_setprio 1
	s_barrier
	v_mfma_f32_16x16x32_bf16 v[60:63], v[146:149], v[182:185], v[60:63]
	v_mfma_f32_16x16x32_bf16 v[56:59], v[154:157], v[182:185], v[56:59]
	v_mfma_f32_16x16x32_bf16 v[52:55], v[146:149], v[190:193], v[52:55]
	v_mfma_f32_16x16x32_bf16 v[44:47], v[154:157], v[190:193], v[44:47]
	v_mfma_f32_16x16x32_bf16 v[36:39], v[146:149], v[198:201], v[36:39]
	v_mfma_f32_16x16x32_bf16 v[28:31], v[154:157], v[198:201], v[28:31]
	v_mfma_f32_16x16x32_bf16 v[20:23], v[146:149], v[210:213], v[20:23]
	v_mfma_f32_16x16x32_bf16 v[12:15], v[154:157], v[210:213], v[12:15]
	v_mfma_f32_16x16x32_bf16 v[60:63], v[150:153], v[186:189], v[60:63]
	v_mfma_f32_16x16x32_bf16 v[56:59], v[158:161], v[186:189], v[56:59]
	v_mfma_f32_16x16x32_bf16 v[52:55], v[150:153], v[194:197], v[52:55]
	v_mfma_f32_16x16x32_bf16 v[44:47], v[158:161], v[194:197], v[44:47]
	v_mfma_f32_16x16x32_bf16 v[36:39], v[150:153], v[206:209], v[36:39]
	v_mfma_f32_16x16x32_bf16 v[28:31], v[158:161], v[206:209], v[28:31]
	v_mfma_f32_16x16x32_bf16 v[20:23], v[150:153], v[214:217], v[20:23]
	v_mfma_f32_16x16x32_bf16 v[12:15], v[158:161], v[214:217], v[12:15]
	v_mfma_f32_16x16x32_bf16 v[48:51], v[162:165], v[182:185], v[48:51]
	v_mfma_f32_16x16x32_bf16 v[40:43], v[170:173], v[182:185], v[40:43]
	v_mfma_f32_16x16x32_bf16 v[32:35], v[162:165], v[190:193], v[32:35]
	v_mfma_f32_16x16x32_bf16 v[24:27], v[170:173], v[190:193], v[24:27]
	v_mfma_f32_16x16x32_bf16 v[16:19], v[162:165], v[198:201], v[16:19]
	v_mfma_f32_16x16x32_bf16 v[8:11], v[170:173], v[198:201], v[8:11]
	v_mfma_f32_16x16x32_bf16 v[4:7], v[162:165], v[210:213], v[4:7]
	v_mfma_f32_16x16x32_bf16 v[0:3], v[170:173], v[210:213], v[0:3]
	v_mfma_f32_16x16x32_bf16 v[48:51], v[166:169], v[186:189], v[48:51]
	v_mfma_f32_16x16x32_bf16 v[40:43], v[178:181], v[186:189], v[40:43]
	v_mfma_f32_16x16x32_bf16 v[32:35], v[166:169], v[194:197], v[32:35]
	v_mfma_f32_16x16x32_bf16 v[24:27], v[178:181], v[194:197], v[24:27]
	v_mfma_f32_16x16x32_bf16 v[16:19], v[166:169], v[206:209], v[16:19]
	v_mfma_f32_16x16x32_bf16 v[8:11], v[178:181], v[206:209], v[8:11]
	v_mfma_f32_16x16x32_bf16 v[4:7], v[166:169], v[214:217], v[4:7]
	s_setprio 2
	s_barrier
	v_mfma_f32_16x16x32_bf16 v[0:3], v[178:181], v[214:217], v[0:3]
	s_setprio 0
	ds_read_b128 v[182:185], v145 offset:32768
	ds_read_b128 v[186:189], v145 offset:33792
	ds_read_b128 v[190:193], v145 offset:34816
	ds_read_b128 v[194:197], v145 offset:35840
	ds_read_b128 v[198:201], v145 offset:36864
	ds_read_b128 v[206:209], v145 offset:37888
	ds_read_b128 v[210:213], v145 offset:38912
	ds_read_b128 v[214:217], v145 offset:39936
	s_add_i32 s2, 0, 0x18000
	s_add_i32 s38, 0, 0x1c000
	v_add_u32_e32 v158, s2, v142
	v_add_u32_e32 v177, s38, v142
	ds_read_b128 v[146:149], v158
	ds_read_b128 v[150:153], v158 offset:1024
	ds_read_b128 v[154:157], v158 offset:2048
	ds_read_b128 v[158:161], v158 offset:3072
	ds_read_b128 v[162:165], v177
	ds_read_b128 v[166:169], v177 offset:1024
	ds_read_b128 v[170:173], v177 offset:2048
	ds_read_b128 v[178:181], v177 offset:3072
	s_add_u32 s0, s34, 0x80000
	s_addc_u32 s1, s35, 0
	s_mov_b32 m0, s51
	v_lshl_add_u64 v[222:223], s[0:1], 0, v[134:135]
	global_load_lds_dwordx4 v[222:223], off
	s_mov_b32 m0, s52
	v_lshl_add_u64 v[222:223], s[0:1], 0, v[130:131]
	global_load_lds_dwordx4 v[222:223], off
	s_waitcnt vmcnt(8) lgkmcnt(0)
	s_setprio 1
	s_barrier
	v_mfma_f32_16x16x32_bf16 v[124:127], v[146:149], v[182:185], v[124:127]
	v_mfma_f32_16x16x32_bf16 v[120:123], v[154:157], v[182:185], v[120:123]
	v_mfma_f32_16x16x32_bf16 v[116:119], v[146:149], v[190:193], v[116:119]
	v_mfma_f32_16x16x32_bf16 v[108:111], v[154:157], v[190:193], v[108:111]
	v_mfma_f32_16x16x32_bf16 v[100:103], v[146:149], v[198:201], v[100:103]
	v_mfma_f32_16x16x32_bf16 v[92:95], v[154:157], v[198:201], v[92:95]
	v_mfma_f32_16x16x32_bf16 v[84:87], v[146:149], v[210:213], v[84:87]
	v_mfma_f32_16x16x32_bf16 v[76:79], v[154:157], v[210:213], v[76:79]
	v_mfma_f32_16x16x32_bf16 v[124:127], v[150:153], v[186:189], v[124:127]
	v_mfma_f32_16x16x32_bf16 v[120:123], v[158:161], v[186:189], v[120:123]
	v_mfma_f32_16x16x32_bf16 v[116:119], v[150:153], v[194:197], v[116:119]
	v_mfma_f32_16x16x32_bf16 v[108:111], v[158:161], v[194:197], v[108:111]
	v_mfma_f32_16x16x32_bf16 v[100:103], v[150:153], v[206:209], v[100:103]
	v_mfma_f32_16x16x32_bf16 v[92:95], v[158:161], v[206:209], v[92:95]
	v_mfma_f32_16x16x32_bf16 v[84:87], v[150:153], v[214:217], v[84:87]
	v_mfma_f32_16x16x32_bf16 v[76:79], v[158:161], v[214:217], v[76:79]
	v_mfma_f32_16x16x32_bf16 v[112:115], v[162:165], v[182:185], v[112:115]
	v_mfma_f32_16x16x32_bf16 v[104:107], v[170:173], v[182:185], v[104:107]
	v_mfma_f32_16x16x32_bf16 v[96:99], v[162:165], v[190:193], v[96:99]
	v_mfma_f32_16x16x32_bf16 v[88:91], v[170:173], v[190:193], v[88:91]
	v_mfma_f32_16x16x32_bf16 v[80:83], v[162:165], v[198:201], v[80:83]
	v_mfma_f32_16x16x32_bf16 v[72:75], v[170:173], v[198:201], v[72:75]
	v_mfma_f32_16x16x32_bf16 v[68:71], v[162:165], v[210:213], v[68:71]
	v_mfma_f32_16x16x32_bf16 v[64:67], v[170:173], v[210:213], v[64:67]
	v_mfma_f32_16x16x32_bf16 v[112:115], v[166:169], v[186:189], v[112:115]
	v_mfma_f32_16x16x32_bf16 v[104:107], v[178:181], v[186:189], v[104:107]
	v_mfma_f32_16x16x32_bf16 v[96:99], v[166:169], v[194:197], v[96:99]
	v_mfma_f32_16x16x32_bf16 v[88:91], v[178:181], v[194:197], v[88:91]
	v_mfma_f32_16x16x32_bf16 v[80:83], v[166:169], v[206:209], v[80:83]
	v_mfma_f32_16x16x32_bf16 v[72:75], v[178:181], v[206:209], v[72:75]
	v_mfma_f32_16x16x32_bf16 v[68:71], v[166:169], v[214:217], v[68:71]
	s_setprio 2
	s_barrier
	v_mfma_f32_16x16x32_bf16 v[64:67], v[178:181], v[214:217], v[64:67]
	s_setprio 0
	ds_read_b128 v[182:185], v145 offset:49152
	ds_read_b128 v[186:189], v145 offset:50176
	ds_read_b128 v[190:193], v145 offset:51200
	ds_read_b128 v[194:197], v145 offset:52224
	ds_read_b128 v[198:201], v145 offset:53248
	ds_read_b128 v[206:209], v145 offset:54272
	ds_read_b128 v[210:213], v145 offset:55296
	ds_read_b128 v[214:217], v145 offset:56320
	s_add_i32 s0, s2, s48
	s_mov_b32 m0, s0
	v_lshl_add_u64 v[174:175], v[174:175], 0, s[8:9]
	global_load_lds_dwordx4 v[174:175], off
	s_add_i32 m0, s0, 0x2000
	s_add_u32 s0, s30, 0x80080
	v_lshl_add_u64 v[174:175], v[202:203], 0, s[8:9]
	s_addc_u32 s1, s31, 0
	s_add_i32 s2, s38, s48
	global_load_lds_dwordx4 v[174:175], off
	s_mov_b32 m0, s2
	v_lshl_add_u64 v[174:175], s[0:1], 0, v[132:133]
	global_load_lds_dwordx4 v[174:175], off
	s_add_i32 m0, s2, 0x2000
	v_lshl_add_u64 v[174:175], s[0:1], 0, v[128:129]
	global_load_lds_dwordx4 v[174:175], off
	s_mov_b32 m0, s55
	v_lshl_add_u64 v[174:175], v[218:219], 0, s[8:9]
	global_load_lds_dwordx4 v[174:175], off
	s_mov_b32 m0, s56
	v_lshl_add_u64 v[174:175], v[220:221], 0, s[8:9]
	global_load_lds_dwordx4 v[174:175], off
	s_waitcnt vmcnt(8) lgkmcnt(0)
	s_setprio 1
	s_barrier
	v_mfma_f32_16x16x32_bf16 v[60:63], v[146:149], v[182:185], v[60:63]
	v_mfma_f32_16x16x32_bf16 v[56:59], v[154:157], v[182:185], v[56:59]
	v_mfma_f32_16x16x32_bf16 v[52:55], v[146:149], v[190:193], v[52:55]
	v_mfma_f32_16x16x32_bf16 v[44:47], v[154:157], v[190:193], v[44:47]
	v_mfma_f32_16x16x32_bf16 v[36:39], v[146:149], v[198:201], v[36:39]
	v_mfma_f32_16x16x32_bf16 v[28:31], v[154:157], v[198:201], v[28:31]
	v_mfma_f32_16x16x32_bf16 v[20:23], v[146:149], v[210:213], v[20:23]
	v_mfma_f32_16x16x32_bf16 v[12:15], v[154:157], v[210:213], v[12:15]
	v_mfma_f32_16x16x32_bf16 v[60:63], v[150:153], v[186:189], v[60:63]
	v_mfma_f32_16x16x32_bf16 v[56:59], v[158:161], v[186:189], v[56:59]
	v_mfma_f32_16x16x32_bf16 v[52:55], v[150:153], v[194:197], v[52:55]
	v_mfma_f32_16x16x32_bf16 v[44:47], v[158:161], v[194:197], v[44:47]
	v_mfma_f32_16x16x32_bf16 v[36:39], v[150:153], v[206:209], v[36:39]
	v_mfma_f32_16x16x32_bf16 v[28:31], v[158:161], v[206:209], v[28:31]
	v_mfma_f32_16x16x32_bf16 v[20:23], v[150:153], v[214:217], v[20:23]
	v_mfma_f32_16x16x32_bf16 v[12:15], v[158:161], v[214:217], v[12:15]
	v_mfma_f32_16x16x32_bf16 v[48:51], v[162:165], v[182:185], v[48:51]
	v_mfma_f32_16x16x32_bf16 v[40:43], v[170:173], v[182:185], v[40:43]
	v_mfma_f32_16x16x32_bf16 v[32:35], v[162:165], v[190:193], v[32:35]
	v_mfma_f32_16x16x32_bf16 v[24:27], v[170:173], v[190:193], v[24:27]
	v_mfma_f32_16x16x32_bf16 v[16:19], v[162:165], v[198:201], v[16:19]
	v_mfma_f32_16x16x32_bf16 v[8:11], v[170:173], v[198:201], v[8:11]
	v_mfma_f32_16x16x32_bf16 v[4:7], v[162:165], v[210:213], v[4:7]
	v_mfma_f32_16x16x32_bf16 v[0:3], v[170:173], v[210:213], v[0:3]
	v_mfma_f32_16x16x32_bf16 v[48:51], v[166:169], v[186:189], v[48:51]
	s_add_i32 s68, s68, 2
	v_mfma_f32_16x16x32_bf16 v[40:43], v[178:181], v[186:189], v[40:43]
	s_add_u32 s28, s28, 0x100
	v_mfma_f32_16x16x32_bf16 v[32:35], v[166:169], v[194:197], v[32:35]
	s_addc_u32 s29, s29, 0
	v_mfma_f32_16x16x32_bf16 v[24:27], v[178:181], v[194:197], v[24:27]
	s_add_u32 s66, s66, 0x100
	v_mfma_f32_16x16x32_bf16 v[16:19], v[166:169], v[206:209], v[16:19]
	s_addc_u32 s67, s67, 0
	v_mfma_f32_16x16x32_bf16 v[8:11], v[178:181], v[206:209], v[8:11]
	s_cmp_gt_u32 s68, 29
	v_mfma_f32_16x16x32_bf16 v[4:7], v[166:169], v[214:217], v[4:7]
	s_setprio 2
	s_barrier
	v_mfma_f32_16x16x32_bf16 v[0:3], v[178:181], v[214:217], v[0:3]
	s_setprio 0
	s_cbranch_scc0 .LBB0_92
	s_and_b64 vcc, exec, s[10:11]
	s_cbranch_vccz .LBB0_95
	s_barrier

.LBB0_300:
	ds_read_b128 v[128:131], v157
	ds_read_b128 v[132:135], v157 offset:1024
	ds_read_b128 v[136:139], v157 offset:2048
	ds_read_b128 v[140:143], v157 offset:3072
	ds_read_b128 v[160:163], v158
	ds_read_b128 v[164:167], v158 offset:1024
	ds_read_b128 v[168:171], v158 offset:2048
	ds_read_b128 v[172:175], v158 offset:3072
	ds_read_b128 v[178:181], v159
	ds_read_b128 v[182:185], v159 offset:1024
	ds_read_b128 v[186:189], v159 offset:2048
	ds_read_b128 v[190:193], v159 offset:3072
	ds_read_b128 v[194:197], v159 offset:4096
	ds_read_b128 v[198:201], v159 offset:5120
	ds_read_b128 v[206:209], v159 offset:6144
	ds_read_b128 v[210:213], v159 offset:7168
	s_add_i32 m0, s72, 0xc000
	v_lshl_add_u64 v[152:153], s[62:63], 0, v[148:149]
	global_load_lds_dwordx4 v[152:153], off
	s_add_i32 m0, s72, 0xe000
	v_lshl_add_u64 v[152:153], s[62:63], 0, v[150:151]
	global_load_lds_dwordx4 v[152:153], off
	s_waitcnt vmcnt(8) lgkmcnt(0)
	s_setprio 1
	s_barrier
	v_mfma_f32_16x16x32_bf16 v[124:127], v[128:131], v[178:181], v[124:127]
	v_mfma_f32_16x16x32_bf16 v[120:123], v[136:139], v[178:181], v[120:123]
	v_mfma_f32_16x16x32_bf16 v[112:115], v[128:131], v[186:189], v[112:115]
	s_add_u32 s0, s62, 0xfff80080
	v_mfma_f32_16x16x32_bf16 v[108:111], v[136:139], v[186:189], v[108:111]
	s_addc_u32 s1, s63, -1
	v_mfma_f32_16x16x32_bf16 v[96:99], v[128:131], v[194:197], v[96:99]
	s_cmp_eq_u32 s89, 28
	v_mfma_f32_16x16x32_bf16 v[92:95], v[136:139], v[194:197], v[92:95]
	s_cselect_b32 s67, s14, s1
	v_mfma_f32_16x16x32_bf16 v[80:83], v[128:131], v[206:209], v[80:83]
	s_cselect_b32 s66, s49, s0
	v_mfma_f32_16x16x32_bf16 v[76:79], v[136:139], v[206:209], v[76:79]
	s_cselect_b32 s65, s61, s88
	v_mfma_f32_16x16x32_bf16 v[124:127], v[132:135], v[182:185], v[124:127]
	s_cselect_b32 s64, s68, s69
	v_mfma_f32_16x16x32_bf16 v[120:123], v[140:143], v[182:185], v[120:123]
	v_mfma_f32_16x16x32_bf16 v[112:115], v[132:135], v[190:193], v[112:115]
	v_mfma_f32_16x16x32_bf16 v[108:111], v[140:143], v[190:193], v[108:111]
	v_mfma_f32_16x16x32_bf16 v[96:99], v[132:135], v[198:201], v[96:99]
	v_mfma_f32_16x16x32_bf16 v[92:95], v[140:143], v[198:201], v[92:95]
	v_mfma_f32_16x16x32_bf16 v[80:83], v[132:135], v[210:213], v[80:83]
	v_mfma_f32_16x16x32_bf16 v[76:79], v[140:143], v[210:213], v[76:79]
	v_mfma_f32_16x16x32_bf16 v[116:119], v[160:163], v[178:181], v[116:119]
	v_mfma_f32_16x16x32_bf16 v[104:107], v[168:171], v[178:181], v[104:107]
	v_mfma_f32_16x16x32_bf16 v[100:103], v[160:163], v[186:189], v[100:103]
	v_mfma_f32_16x16x32_bf16 v[88:91], v[168:171], v[186:189], v[88:91]
	v_mfma_f32_16x16x32_bf16 v[84:87], v[160:163], v[194:197], v[84:87]
	v_mfma_f32_16x16x32_bf16 v[72:75], v[168:171], v[194:197], v[72:75]
	v_mfma_f32_16x16x32_bf16 v[68:71], v[160:163], v[206:209], v[68:71]
	v_mfma_f32_16x16x32_bf16 v[64:67], v[168:171], v[206:209], v[64:67]
	v_mfma_f32_16x16x32_bf16 v[116:119], v[164:167], v[182:185], v[116:119]
	v_mfma_f32_16x16x32_bf16 v[104:107], v[172:175], v[182:185], v[104:107]
	v_mfma_f32_16x16x32_bf16 v[100:103], v[164:167], v[190:193], v[100:103]
	v_mfma_f32_16x16x32_bf16 v[88:91], v[172:175], v[190:193], v[88:91]
	v_mfma_f32_16x16x32_bf16 v[84:87], v[164:167], v[198:201], v[84:87]
	v_mfma_f32_16x16x32_bf16 v[72:75], v[172:175], v[198:201], v[72:75]
	v_mfma_f32_16x16x32_bf16 v[68:71], v[164:167], v[210:213], v[68:71]
	s_setprio 2
	s_barrier
	v_mfma_f32_16x16x32_bf16 v[64:67], v[172:175], v[210:213], v[64:67]
	s_setprio 0
	ds_read_b128 v[178:181], v159 offset:16384
	ds_read_b128 v[182:185], v159 offset:17408
	ds_read_b128 v[186:189], v159 offset:18432
	ds_read_b128 v[190:193], v159 offset:19456
	ds_read_b128 v[194:197], v159 offset:20480
	ds_read_b128 v[198:201], v159 offset:21504
	ds_read_b128 v[206:209], v159 offset:22528
	ds_read_b128 v[210:213], v159 offset:23552
	s_add_i32 s0, s83, s71
	s_mov_b32 m0, s0
	v_lshl_add_u64 v[152:153], s[64:65], 0, v[146:147]
	global_load_lds_dwordx4 v[152:153], off
	s_add_i32 m0, s0, 0x2000
	s_add_u32 s0, s64, 0x80000
	v_lshl_add_u64 v[202:203], s[64:65], 0, v[144:145]
	s_addc_u32 s1, s65, 0
	s_add_i32 s2, s84, s71
	global_load_lds_dwordx4 v[202:203], off
	v_lshl_add_u64 v[214:215], s[0:1], 0, v[146:147]
	s_mov_b32 m0, s2
	v_lshl_add_u64 v[216:217], s[66:67], 0, v[144:145]
	global_load_lds_dwordx4 v[214:215], off
	s_add_i32 m0, s2, 0x2000
	v_lshl_add_u64 v[214:215], s[0:1], 0, v[144:145]
	global_load_lds_dwordx4 v[214:215], off
	s_mov_b32 m0, s72
	v_lshl_add_u64 v[214:215], s[66:67], 0, v[146:147]
	global_load_lds_dwordx4 v[214:215], off
	s_mov_b32 m0, s73
	s_nop 0
	global_load_lds_dwordx4 v[216:217], off
	s_waitcnt vmcnt(8) lgkmcnt(0)
	s_setprio 1
	s_barrier
	v_mfma_f32_16x16x32_bf16 v[60:63], v[128:131], v[178:181], v[60:63]
	v_mfma_f32_16x16x32_bf16 v[56:59], v[136:139], v[178:181], v[56:59]
	v_mfma_f32_16x16x32_bf16 v[48:51], v[128:131], v[186:189], v[48:51]
	v_mfma_f32_16x16x32_bf16 v[44:47], v[136:139], v[186:189], v[44:47]
	v_mfma_f32_16x16x32_bf16 v[32:35], v[128:131], v[194:197], v[32:35]
	v_mfma_f32_16x16x32_bf16 v[28:31], v[136:139], v[194:197], v[28:31]
	v_mfma_f32_16x16x32_bf16 v[16:19], v[128:131], v[206:209], v[16:19]
	v_mfma_f32_16x16x32_bf16 v[12:15], v[136:139], v[206:209], v[12:15]
	v_mfma_f32_16x16x32_bf16 v[60:63], v[132:135], v[182:185], v[60:63]
	v_mfma_f32_16x16x32_bf16 v[56:59], v[140:143], v[182:185], v[56:59]
	v_mfma_f32_16x16x32_bf16 v[48:51], v[132:135], v[190:193], v[48:51]
	v_mfma_f32_16x16x32_bf16 v[44:47], v[140:143], v[190:193], v[44:47]
	v_mfma_f32_16x16x32_bf16 v[32:35], v[132:135], v[198:201], v[32:35]
	v_mfma_f32_16x16x32_bf16 v[28:31], v[140:143], v[198:201], v[28:31]
	v_mfma_f32_16x16x32_bf16 v[16:19], v[132:135], v[210:213], v[16:19]
	v_mfma_f32_16x16x32_bf16 v[12:15], v[140:143], v[210:213], v[12:15]
	v_mfma_f32_16x16x32_bf16 v[52:55], v[160:163], v[178:181], v[52:55]
	v_mfma_f32_16x16x32_bf16 v[40:43], v[168:171], v[178:181], v[40:43]
	v_mfma_f32_16x16x32_bf16 v[36:39], v[160:163], v[186:189], v[36:39]
	v_mfma_f32_16x16x32_bf16 v[24:27], v[168:171], v[186:189], v[24:27]
	v_mfma_f32_16x16x32_bf16 v[20:23], v[160:163], v[194:197], v[20:23]
	v_mfma_f32_16x16x32_bf16 v[8:11], v[168:171], v[194:197], v[8:11]
	v_mfma_f32_16x16x32_bf16 v[4:7], v[160:163], v[206:209], v[4:7]
	v_mfma_f32_16x16x32_bf16 v[0:3], v[168:171], v[206:209], v[0:3]
	v_mfma_f32_16x16x32_bf16 v[52:55], v[164:167], v[182:185], v[52:55]
	v_mfma_f32_16x16x32_bf16 v[40:43], v[172:175], v[182:185], v[40:43]
	v_mfma_f32_16x16x32_bf16 v[36:39], v[164:167], v[190:193], v[36:39]
	v_mfma_f32_16x16x32_bf16 v[24:27], v[172:175], v[190:193], v[24:27]
	v_mfma_f32_16x16x32_bf16 v[20:23], v[164:167], v[198:201], v[20:23]
	v_mfma_f32_16x16x32_bf16 v[8:11], v[172:175], v[198:201], v[8:11]
	v_mfma_f32_16x16x32_bf16 v[4:7], v[164:167], v[210:213], v[4:7]
	s_setprio 2
	s_barrier
	v_mfma_f32_16x16x32_bf16 v[0:3], v[172:175], v[210:213], v[0:3]
	s_setprio 0
	ds_read_b128 v[178:181], v159 offset:32768
	ds_read_b128 v[182:185], v159 offset:33792
	ds_read_b128 v[186:189], v159 offset:34816
	ds_read_b128 v[190:193], v159 offset:35840
	ds_read_b128 v[194:197], v159 offset:36864
	ds_read_b128 v[198:201], v159 offset:37888
	ds_read_b128 v[206:209], v159 offset:38912
	ds_read_b128 v[210:213], v159 offset:39936
	s_add_i32 s2, 0, 0x18000
	s_add_i32 s3, 0, 0x1c000
	v_add_u32_e32 v140, s2, v156
	v_add_u32_e32 v172, s3, v156
	ds_read_b128 v[128:131], v140
	ds_read_b128 v[132:135], v140 offset:1024
	ds_read_b128 v[136:139], v140 offset:2048
	ds_read_b128 v[140:143], v140 offset:3072
	ds_read_b128 v[160:163], v172
	ds_read_b128 v[164:167], v172 offset:1024
	ds_read_b128 v[168:171], v172 offset:2048
	ds_read_b128 v[172:175], v172 offset:3072
	s_add_u32 s0, s66, 0x80000
	s_addc_u32 s1, s67, 0
	s_mov_b32 m0, s74
	v_lshl_add_u64 v[218:219], s[0:1], 0, v[146:147]
	global_load_lds_dwordx4 v[218:219], off
	s_mov_b32 m0, s75
	v_lshl_add_u64 v[218:219], s[0:1], 0, v[144:145]
	global_load_lds_dwordx4 v[218:219], off
	s_waitcnt vmcnt(8) lgkmcnt(0)
	s_setprio 1
	s_barrier
	v_mfma_f32_16x16x32_bf16 v[124:127], v[128:131], v[178:181], v[124:127]
	v_mfma_f32_16x16x32_bf16 v[120:123], v[136:139], v[178:181], v[120:123]
	v_mfma_f32_16x16x32_bf16 v[112:115], v[128:131], v[186:189], v[112:115]
	v_mfma_f32_16x16x32_bf16 v[108:111], v[136:139], v[186:189], v[108:111]
	v_mfma_f32_16x16x32_bf16 v[96:99], v[128:131], v[194:197], v[96:99]
	v_mfma_f32_16x16x32_bf16 v[92:95], v[136:139], v[194:197], v[92:95]
	v_mfma_f32_16x16x32_bf16 v[80:83], v[128:131], v[206:209], v[80:83]
	v_mfma_f32_16x16x32_bf16 v[76:79], v[136:139], v[206:209], v[76:79]
	v_mfma_f32_16x16x32_bf16 v[124:127], v[132:135], v[182:185], v[124:127]
	v_mfma_f32_16x16x32_bf16 v[120:123], v[140:143], v[182:185], v[120:123]
	v_mfma_f32_16x16x32_bf16 v[112:115], v[132:135], v[190:193], v[112:115]
	v_mfma_f32_16x16x32_bf16 v[108:111], v[140:143], v[190:193], v[108:111]
	v_mfma_f32_16x16x32_bf16 v[96:99], v[132:135], v[198:201], v[96:99]
	v_mfma_f32_16x16x32_bf16 v[92:95], v[140:143], v[198:201], v[92:95]
	v_mfma_f32_16x16x32_bf16 v[80:83], v[132:135], v[210:213], v[80:83]
	v_mfma_f32_16x16x32_bf16 v[76:79], v[140:143], v[210:213], v[76:79]
	v_mfma_f32_16x16x32_bf16 v[116:119], v[160:163], v[178:181], v[116:119]
	v_mfma_f32_16x16x32_bf16 v[104:107], v[168:171], v[178:181], v[104:107]
	v_mfma_f32_16x16x32_bf16 v[100:103], v[160:163], v[186:189], v[100:103]
	v_mfma_f32_16x16x32_bf16 v[88:91], v[168:171], v[186:189], v[88:91]
	v_mfma_f32_16x16x32_bf16 v[84:87], v[160:163], v[194:197], v[84:87]
	v_mfma_f32_16x16x32_bf16 v[72:75], v[168:171], v[194:197], v[72:75]
	v_mfma_f32_16x16x32_bf16 v[68:71], v[160:163], v[206:209], v[68:71]
	v_mfma_f32_16x16x32_bf16 v[64:67], v[168:171], v[206:209], v[64:67]
	v_mfma_f32_16x16x32_bf16 v[116:119], v[164:167], v[182:185], v[116:119]
	v_mfma_f32_16x16x32_bf16 v[104:107], v[172:175], v[182:185], v[104:107]
	v_mfma_f32_16x16x32_bf16 v[100:103], v[164:167], v[190:193], v[100:103]
	v_mfma_f32_16x16x32_bf16 v[88:91], v[172:175], v[190:193], v[88:91]
	v_mfma_f32_16x16x32_bf16 v[84:87], v[164:167], v[198:201], v[84:87]
	v_mfma_f32_16x16x32_bf16 v[72:75], v[172:175], v[198:201], v[72:75]
	v_mfma_f32_16x16x32_bf16 v[68:71], v[164:167], v[210:213], v[68:71]
	s_setprio 2
	s_barrier
	v_mfma_f32_16x16x32_bf16 v[64:67], v[172:175], v[210:213], v[64:67]
	s_setprio 0
	ds_read_b128 v[178:181], v159 offset:49152
	ds_read_b128 v[182:185], v159 offset:50176
	ds_read_b128 v[186:189], v159 offset:51200
	ds_read_b128 v[190:193], v159 offset:52224
	ds_read_b128 v[194:197], v159 offset:53248
	ds_read_b128 v[198:201], v159 offset:54272
	ds_read_b128 v[206:209], v159 offset:55296
	ds_read_b128 v[210:213], v159 offset:56320
	s_add_i32 s0, s2, s71
	s_mov_b32 m0, s0
	v_lshl_add_u64 v[152:153], v[152:153], 0, s[12:13]
	global_load_lds_dwordx4 v[152:153], off
	s_add_i32 m0, s0, 0x2000
	s_add_u32 s0, s64, 0x80080
	v_lshl_add_u64 v[152:153], v[202:203], 0, s[12:13]
	s_addc_u32 s1, s65, 0
	s_add_i32 s2, s3, s71
	global_load_lds_dwordx4 v[152:153], off
	s_mov_b32 m0, s2
	v_lshl_add_u64 v[152:153], s[0:1], 0, v[146:147]
	global_load_lds_dwordx4 v[152:153], off
	s_add_i32 m0, s2, 0x2000
	v_lshl_add_u64 v[152:153], s[0:1], 0, v[144:145]
	global_load_lds_dwordx4 v[152:153], off
	s_mov_b32 m0, s81
	v_lshl_add_u64 v[152:153], v[214:215], 0, s[12:13]
	global_load_lds_dwordx4 v[152:153], off
	s_mov_b32 m0, s82
	v_lshl_add_u64 v[152:153], v[216:217], 0, s[12:13]
	global_load_lds_dwordx4 v[152:153], off
	s_waitcnt vmcnt(8) lgkmcnt(0)
	s_setprio 1
	s_barrier
	v_mfma_f32_16x16x32_bf16 v[60:63], v[128:131], v[178:181], v[60:63]
	v_mfma_f32_16x16x32_bf16 v[56:59], v[136:139], v[178:181], v[56:59]
	v_mfma_f32_16x16x32_bf16 v[48:51], v[128:131], v[186:189], v[48:51]
	v_mfma_f32_16x16x32_bf16 v[44:47], v[136:139], v[186:189], v[44:47]
	v_mfma_f32_16x16x32_bf16 v[32:35], v[128:131], v[194:197], v[32:35]
	v_mfma_f32_16x16x32_bf16 v[28:31], v[136:139], v[194:197], v[28:31]
	v_mfma_f32_16x16x32_bf16 v[16:19], v[128:131], v[206:209], v[16:19]
	v_mfma_f32_16x16x32_bf16 v[12:15], v[136:139], v[206:209], v[12:15]
	v_mfma_f32_16x16x32_bf16 v[60:63], v[132:135], v[182:185], v[60:63]
	v_mfma_f32_16x16x32_bf16 v[56:59], v[140:143], v[182:185], v[56:59]
	v_mfma_f32_16x16x32_bf16 v[48:51], v[132:135], v[190:193], v[48:51]
	v_mfma_f32_16x16x32_bf16 v[44:47], v[140:143], v[190:193], v[44:47]
	v_mfma_f32_16x16x32_bf16 v[32:35], v[132:135], v[198:201], v[32:35]
	v_mfma_f32_16x16x32_bf16 v[28:31], v[140:143], v[198:201], v[28:31]
	v_mfma_f32_16x16x32_bf16 v[16:19], v[132:135], v[210:213], v[16:19]
	v_mfma_f32_16x16x32_bf16 v[12:15], v[140:143], v[210:213], v[12:15]
	v_mfma_f32_16x16x32_bf16 v[52:55], v[160:163], v[178:181], v[52:55]
	v_mfma_f32_16x16x32_bf16 v[40:43], v[168:171], v[178:181], v[40:43]
	v_mfma_f32_16x16x32_bf16 v[36:39], v[160:163], v[186:189], v[36:39]
	v_mfma_f32_16x16x32_bf16 v[24:27], v[168:171], v[186:189], v[24:27]
	v_mfma_f32_16x16x32_bf16 v[20:23], v[160:163], v[194:197], v[20:23]
	v_mfma_f32_16x16x32_bf16 v[8:11], v[168:171], v[194:197], v[8:11]
	v_mfma_f32_16x16x32_bf16 v[4:7], v[160:163], v[206:209], v[4:7]
	v_mfma_f32_16x16x32_bf16 v[0:3], v[168:171], v[206:209], v[0:3]
	v_mfma_f32_16x16x32_bf16 v[52:55], v[164:167], v[182:185], v[52:55]
	s_add_i32 s89, s89, 2
	v_mfma_f32_16x16x32_bf16 v[40:43], v[172:175], v[182:185], v[40:43]
	s_add_u32 s62, s62, 0x100
	v_mfma_f32_16x16x32_bf16 v[36:39], v[164:167], v[190:193], v[36:39]
	s_addc_u32 s63, s63, 0
	v_mfma_f32_16x16x32_bf16 v[24:27], v[172:175], v[190:193], v[24:27]
	s_add_u32 s69, s69, 0x100
	v_mfma_f32_16x16x32_bf16 v[20:23], v[164:167], v[198:201], v[20:23]
	s_addc_u32 s88, s88, 0
	v_mfma_f32_16x16x32_bf16 v[8:11], v[172:175], v[198:201], v[8:11]
	s_cmp_gt_u32 s89, 29
	v_mfma_f32_16x16x32_bf16 v[4:7], v[164:167], v[210:213], v[4:7]
	s_setprio 2
	s_barrier
	v_mfma_f32_16x16x32_bf16 v[0:3], v[172:175], v[210:213], v[0:3]
	s_setprio 0
	s_cbranch_scc0 .LBB0_300
	s_and_b64 vcc, exec, s[16:17]
	s_cbranch_vccz .LBB0_303
	s_barrier

.LBB0_399:
	ds_read_b128 v[128:131], v207
	ds_read_b128 v[132:135], v207 offset:1024
	ds_read_b128 v[136:139], v207 offset:2048
	ds_read_b128 v[140:143], v207 offset:3072
	ds_read_b128 v[144:147], v208
	ds_read_b128 v[148:151], v208 offset:1024
	ds_read_b128 v[152:155], v208 offset:2048
	ds_read_b128 v[156:159], v208 offset:3072
	ds_read_b128 v[160:163], v209
	ds_read_b128 v[164:167], v209 offset:1024
	ds_read_b128 v[168:171], v209 offset:2048
	ds_read_b128 v[172:175], v209 offset:3072
	ds_read_b128 v[190:193], v209 offset:4096
	ds_read_b128 v[194:197], v209 offset:5120
	ds_read_b128 v[198:201], v209 offset:6144
	ds_read_b128 v[210:213], v209 offset:7168
	s_add_i32 m0, s81, 0xc000
	v_lshl_add_u64 v[202:203], s[4:5], 0, v[186:187]
	global_load_lds_dwordx4 v[202:203], off
	s_add_i32 m0, s81, 0xe000
	v_lshl_add_u64 v[202:203], s[4:5], 0, v[188:189]
	global_load_lds_dwordx4 v[202:203], off
	s_waitcnt vmcnt(8) lgkmcnt(0)
	s_setprio 1
	s_barrier
	v_mfma_f32_16x16x32_bf16 v[124:127], v[128:131], v[160:163], v[124:127]
	v_mfma_f32_16x16x32_bf16 v[56:59], v[136:139], v[160:163], v[56:59]
	v_mfma_f32_16x16x32_bf16 v[116:119], v[128:131], v[168:171], v[116:119]
	s_add_u32 s0, s4, 0xfff80080
	v_mfma_f32_16x16x32_bf16 v[52:55], v[136:139], v[168:171], v[52:55]
	s_addc_u32 s1, s5, -1
	v_mfma_f32_16x16x32_bf16 v[108:111], v[128:131], v[190:193], v[108:111]
	s_cmp_eq_u32 vcc_hi, 28
	v_mfma_f32_16x16x32_bf16 v[44:47], v[136:139], v[190:193], v[44:47]
	s_cselect_b32 s11, s7, s1
	v_mfma_f32_16x16x32_bf16 v[104:107], v[128:131], v[198:201], v[104:107]
	s_cselect_b32 s10, s12, s0
	v_mfma_f32_16x16x32_bf16 v[32:35], v[136:139], v[198:201], v[32:35]
	s_cselect_b32 s9, s13, vcc_lo
	v_mfma_f32_16x16x32_bf16 v[124:127], v[132:135], v[164:167], v[124:127]
	s_cselect_b32 s8, s15, s65
	v_mfma_f32_16x16x32_bf16 v[56:59], v[140:143], v[164:167], v[56:59]
	v_mfma_f32_16x16x32_bf16 v[116:119], v[132:135], v[172:175], v[116:119]
	v_mfma_f32_16x16x32_bf16 v[52:55], v[140:143], v[172:175], v[52:55]
	v_mfma_f32_16x16x32_bf16 v[108:111], v[132:135], v[194:197], v[108:111]
	v_mfma_f32_16x16x32_bf16 v[44:47], v[140:143], v[194:197], v[44:47]
	v_mfma_f32_16x16x32_bf16 v[104:107], v[132:135], v[210:213], v[104:107]
	v_mfma_f32_16x16x32_bf16 v[32:35], v[140:143], v[210:213], v[32:35]
	v_mfma_f32_16x16x32_bf16 v[120:123], v[144:147], v[160:163], v[120:123]
	v_mfma_f32_16x16x32_bf16 v[60:63], v[152:155], v[160:163], v[60:63]
	v_mfma_f32_16x16x32_bf16 v[112:115], v[144:147], v[168:171], v[112:115]
	v_mfma_f32_16x16x32_bf16 v[48:51], v[152:155], v[168:171], v[48:51]
	v_mfma_f32_16x16x32_bf16 v[100:103], v[144:147], v[190:193], v[100:103]
	v_mfma_f32_16x16x32_bf16 v[40:43], v[152:155], v[190:193], v[40:43]
	v_mfma_f32_16x16x32_bf16 v[96:99], v[144:147], v[198:201], v[96:99]
	v_mfma_f32_16x16x32_bf16 v[36:39], v[152:155], v[198:201], v[36:39]
	v_mfma_f32_16x16x32_bf16 v[120:123], v[148:151], v[164:167], v[120:123]
	v_mfma_f32_16x16x32_bf16 v[60:63], v[156:159], v[164:167], v[60:63]
	v_mfma_f32_16x16x32_bf16 v[112:115], v[148:151], v[172:175], v[112:115]
	v_mfma_f32_16x16x32_bf16 v[48:51], v[156:159], v[172:175], v[48:51]
	v_mfma_f32_16x16x32_bf16 v[100:103], v[148:151], v[194:197], v[100:103]
	v_mfma_f32_16x16x32_bf16 v[40:43], v[156:159], v[194:197], v[40:43]
	v_mfma_f32_16x16x32_bf16 v[96:99], v[148:151], v[210:213], v[96:99]
	s_setprio 2
	s_barrier
	v_mfma_f32_16x16x32_bf16 v[36:39], v[156:159], v[210:213], v[36:39]
	s_setprio 0
	ds_read_b128 v[160:163], v209 offset:16384
	ds_read_b128 v[164:167], v209 offset:17408
	ds_read_b128 v[168:171], v209 offset:18432
	ds_read_b128 v[172:175], v209 offset:19456
	ds_read_b128 v[190:193], v209 offset:20480
	ds_read_b128 v[194:197], v209 offset:21504
	ds_read_b128 v[198:201], v209 offset:22528
	ds_read_b128 v[210:213], v209 offset:23552
	s_add_i32 s0, s95, s80
	s_mov_b32 m0, s0
	v_lshl_add_u64 v[202:203], s[8:9], 0, v[180:181]
	global_load_lds_dwordx4 v[202:203], off
	s_add_i32 m0, s0, 0x2000
	s_add_u32 s0, s8, 0x80000
	v_lshl_add_u64 v[214:215], s[8:9], 0, v[184:185]
	s_addc_u32 s1, s9, 0
	s_add_i32 s2, s96, s80
	global_load_lds_dwordx4 v[214:215], off
	v_lshl_add_u64 v[216:217], s[0:1], 0, v[180:181]
	s_mov_b32 m0, s2
	v_lshl_add_u64 v[218:219], s[10:11], 0, v[182:183]
	global_load_lds_dwordx4 v[216:217], off
	s_add_i32 m0, s2, 0x2000
	v_lshl_add_u64 v[216:217], s[0:1], 0, v[184:185]
	global_load_lds_dwordx4 v[216:217], off
	s_mov_b32 m0, s81
	v_lshl_add_u64 v[216:217], s[10:11], 0, v[178:179]
	global_load_lds_dwordx4 v[216:217], off
	s_mov_b32 m0, s82
	s_nop 0
	global_load_lds_dwordx4 v[218:219], off
	s_waitcnt vmcnt(8) lgkmcnt(0)
	s_setprio 1
	s_barrier
	v_mfma_f32_16x16x32_bf16 v[92:95], v[128:131], v[160:163], v[92:95]
	v_mfma_f32_16x16x32_bf16 v[24:27], v[136:139], v[160:163], v[24:27]
	v_mfma_f32_16x16x32_bf16 v[84:87], v[128:131], v[168:171], v[84:87]
	v_mfma_f32_16x16x32_bf16 v[20:23], v[136:139], v[168:171], v[20:23]
	v_mfma_f32_16x16x32_bf16 v[76:79], v[128:131], v[190:193], v[76:79]
	v_mfma_f32_16x16x32_bf16 v[12:15], v[136:139], v[190:193], v[12:15]
	v_mfma_f32_16x16x32_bf16 v[72:75], v[128:131], v[198:201], v[72:75]
	v_mfma_f32_16x16x32_bf16 v[0:3], v[136:139], v[198:201], v[0:3]
	v_mfma_f32_16x16x32_bf16 v[92:95], v[132:135], v[164:167], v[92:95]
	v_mfma_f32_16x16x32_bf16 v[24:27], v[140:143], v[164:167], v[24:27]
	v_mfma_f32_16x16x32_bf16 v[84:87], v[132:135], v[172:175], v[84:87]
	v_mfma_f32_16x16x32_bf16 v[20:23], v[140:143], v[172:175], v[20:23]
	v_mfma_f32_16x16x32_bf16 v[76:79], v[132:135], v[194:197], v[76:79]
	v_mfma_f32_16x16x32_bf16 v[12:15], v[140:143], v[194:197], v[12:15]
	v_mfma_f32_16x16x32_bf16 v[72:75], v[132:135], v[210:213], v[72:75]
	v_mfma_f32_16x16x32_bf16 v[0:3], v[140:143], v[210:213], v[0:3]
	v_mfma_f32_16x16x32_bf16 v[88:91], v[144:147], v[160:163], v[88:91]
	v_mfma_f32_16x16x32_bf16 v[28:31], v[152:155], v[160:163], v[28:31]
	v_mfma_f32_16x16x32_bf16 v[80:83], v[144:147], v[168:171], v[80:83]
	v_mfma_f32_16x16x32_bf16 v[16:19], v[152:155], v[168:171], v[16:19]
	v_mfma_f32_16x16x32_bf16 v[68:71], v[144:147], v[190:193], v[68:71]
	v_mfma_f32_16x16x32_bf16 v[8:11], v[152:155], v[190:193], v[8:11]
	v_mfma_f32_16x16x32_bf16 v[64:67], v[144:147], v[198:201], v[64:67]
	v_mfma_f32_16x16x32_bf16 v[4:7], v[152:155], v[198:201], v[4:7]
	v_mfma_f32_16x16x32_bf16 v[88:91], v[148:151], v[164:167], v[88:91]
	v_mfma_f32_16x16x32_bf16 v[28:31], v[156:159], v[164:167], v[28:31]
	v_mfma_f32_16x16x32_bf16 v[80:83], v[148:151], v[172:175], v[80:83]
	v_mfma_f32_16x16x32_bf16 v[16:19], v[156:159], v[172:175], v[16:19]
	v_mfma_f32_16x16x32_bf16 v[68:71], v[148:151], v[194:197], v[68:71]
	v_mfma_f32_16x16x32_bf16 v[8:11], v[156:159], v[194:197], v[8:11]
	v_mfma_f32_16x16x32_bf16 v[64:67], v[148:151], v[210:213], v[64:67]
	s_setprio 2
	s_barrier
	v_mfma_f32_16x16x32_bf16 v[4:7], v[156:159], v[210:213], v[4:7]
	s_setprio 0
	ds_read_b128 v[160:163], v209 offset:32768
	ds_read_b128 v[164:167], v209 offset:33792
	ds_read_b128 v[168:171], v209 offset:34816
	ds_read_b128 v[172:175], v209 offset:35840
	ds_read_b128 v[190:193], v209 offset:36864
	ds_read_b128 v[194:197], v209 offset:37888
	ds_read_b128 v[198:201], v209 offset:38912
	ds_read_b128 v[210:213], v209 offset:39936
	s_add_i32 s2, 0, 0x18000
	s_add_i32 s3, 0, 0x1c000
	v_add_u32_e32 v140, s2, v206
	v_add_u32_e32 v156, s3, v206
	ds_read_b128 v[128:131], v140
	ds_read_b128 v[132:135], v140 offset:1024
	ds_read_b128 v[136:139], v140 offset:2048
	ds_read_b128 v[140:143], v140 offset:3072
	ds_read_b128 v[144:147], v156
	ds_read_b128 v[148:151], v156 offset:1024
	ds_read_b128 v[152:155], v156 offset:2048
	ds_read_b128 v[156:159], v156 offset:3072
	s_add_u32 s0, s10, 0x80000
	s_addc_u32 s1, s11, 0
	s_mov_b32 m0, s83
	v_lshl_add_u64 v[220:221], s[0:1], 0, v[178:179]
	global_load_lds_dwordx4 v[220:221], off
	s_mov_b32 m0, s84
	v_lshl_add_u64 v[220:221], s[0:1], 0, v[182:183]
	global_load_lds_dwordx4 v[220:221], off
	s_waitcnt vmcnt(8) lgkmcnt(0)
	s_setprio 1
	s_barrier
	v_mfma_f32_16x16x32_bf16 v[124:127], v[128:131], v[160:163], v[124:127]
	v_mfma_f32_16x16x32_bf16 v[56:59], v[136:139], v[160:163], v[56:59]
	v_mfma_f32_16x16x32_bf16 v[116:119], v[128:131], v[168:171], v[116:119]
	v_mfma_f32_16x16x32_bf16 v[52:55], v[136:139], v[168:171], v[52:55]
	v_mfma_f32_16x16x32_bf16 v[108:111], v[128:131], v[190:193], v[108:111]
	v_mfma_f32_16x16x32_bf16 v[44:47], v[136:139], v[190:193], v[44:47]
	v_mfma_f32_16x16x32_bf16 v[104:107], v[128:131], v[198:201], v[104:107]
	v_mfma_f32_16x16x32_bf16 v[32:35], v[136:139], v[198:201], v[32:35]
	v_mfma_f32_16x16x32_bf16 v[124:127], v[132:135], v[164:167], v[124:127]
	v_mfma_f32_16x16x32_bf16 v[56:59], v[140:143], v[164:167], v[56:59]
	v_mfma_f32_16x16x32_bf16 v[116:119], v[132:135], v[172:175], v[116:119]
	v_mfma_f32_16x16x32_bf16 v[52:55], v[140:143], v[172:175], v[52:55]
	v_mfma_f32_16x16x32_bf16 v[108:111], v[132:135], v[194:197], v[108:111]
	v_mfma_f32_16x16x32_bf16 v[44:47], v[140:143], v[194:197], v[44:47]
	v_mfma_f32_16x16x32_bf16 v[104:107], v[132:135], v[210:213], v[104:107]
	v_mfma_f32_16x16x32_bf16 v[32:35], v[140:143], v[210:213], v[32:35]
	v_mfma_f32_16x16x32_bf16 v[120:123], v[144:147], v[160:163], v[120:123]
	v_mfma_f32_16x16x32_bf16 v[60:63], v[152:155], v[160:163], v[60:63]
	v_mfma_f32_16x16x32_bf16 v[112:115], v[144:147], v[168:171], v[112:115]
	v_mfma_f32_16x16x32_bf16 v[48:51], v[152:155], v[168:171], v[48:51]
	v_mfma_f32_16x16x32_bf16 v[100:103], v[144:147], v[190:193], v[100:103]
	v_mfma_f32_16x16x32_bf16 v[40:43], v[152:155], v[190:193], v[40:43]
	v_mfma_f32_16x16x32_bf16 v[96:99], v[144:147], v[198:201], v[96:99]
	v_mfma_f32_16x16x32_bf16 v[36:39], v[152:155], v[198:201], v[36:39]
	v_mfma_f32_16x16x32_bf16 v[120:123], v[148:151], v[164:167], v[120:123]
	v_mfma_f32_16x16x32_bf16 v[60:63], v[156:159], v[164:167], v[60:63]
	v_mfma_f32_16x16x32_bf16 v[112:115], v[148:151], v[172:175], v[112:115]
	v_mfma_f32_16x16x32_bf16 v[48:51], v[156:159], v[172:175], v[48:51]
	v_mfma_f32_16x16x32_bf16 v[100:103], v[148:151], v[194:197], v[100:103]
	v_mfma_f32_16x16x32_bf16 v[40:43], v[156:159], v[194:197], v[40:43]
	v_mfma_f32_16x16x32_bf16 v[96:99], v[148:151], v[210:213], v[96:99]
	s_setprio 2
	s_barrier
	v_mfma_f32_16x16x32_bf16 v[36:39], v[156:159], v[210:213], v[36:39]
	s_setprio 0
	ds_read_b128 v[160:163], v209 offset:49152
	ds_read_b128 v[164:167], v209 offset:50176
	ds_read_b128 v[168:171], v209 offset:51200
	ds_read_b128 v[172:175], v209 offset:52224
	ds_read_b128 v[190:193], v209 offset:53248
	ds_read_b128 v[194:197], v209 offset:54272
	ds_read_b128 v[198:201], v209 offset:55296
	ds_read_b128 v[210:213], v209 offset:56320
	s_add_i32 s0, s2, s80
	s_mov_b32 m0, s0
	v_lshl_add_u64 v[202:203], v[202:203], 0, s[24:25]
	global_load_lds_dwordx4 v[202:203], off
	s_add_i32 m0, s0, 0x2000
	s_add_u32 s0, s8, 0x80080
	v_lshl_add_u64 v[202:203], v[214:215], 0, s[24:25]
	s_addc_u32 s1, s9, 0
	s_add_i32 s2, s3, s80
	global_load_lds_dwordx4 v[202:203], off
	s_mov_b32 m0, s2
	v_lshl_add_u64 v[202:203], s[0:1], 0, v[180:181]
	global_load_lds_dwordx4 v[202:203], off
	s_add_i32 m0, s2, 0x2000
	v_lshl_add_u64 v[202:203], s[0:1], 0, v[184:185]
	global_load_lds_dwordx4 v[202:203], off
	s_mov_b32 m0, s90
	v_lshl_add_u64 v[202:203], v[216:217], 0, s[24:25]
	global_load_lds_dwordx4 v[202:203], off
	s_mov_b32 m0, s91
	v_lshl_add_u64 v[202:203], v[218:219], 0, s[24:25]
	global_load_lds_dwordx4 v[202:203], off
	s_waitcnt vmcnt(8) lgkmcnt(0)
	s_setprio 1
	s_barrier
	v_mfma_f32_16x16x32_bf16 v[92:95], v[128:131], v[160:163], v[92:95]
	v_mfma_f32_16x16x32_bf16 v[24:27], v[136:139], v[160:163], v[24:27]
	v_mfma_f32_16x16x32_bf16 v[84:87], v[128:131], v[168:171], v[84:87]
	v_mfma_f32_16x16x32_bf16 v[20:23], v[136:139], v[168:171], v[20:23]
	v_mfma_f32_16x16x32_bf16 v[76:79], v[128:131], v[190:193], v[76:79]
	v_mfma_f32_16x16x32_bf16 v[12:15], v[136:139], v[190:193], v[12:15]
	v_mfma_f32_16x16x32_bf16 v[72:75], v[128:131], v[198:201], v[72:75]
	v_mfma_f32_16x16x32_bf16 v[0:3], v[136:139], v[198:201], v[0:3]
	v_mfma_f32_16x16x32_bf16 v[92:95], v[132:135], v[164:167], v[92:95]
	v_mfma_f32_16x16x32_bf16 v[24:27], v[140:143], v[164:167], v[24:27]
	v_mfma_f32_16x16x32_bf16 v[84:87], v[132:135], v[172:175], v[84:87]
	v_mfma_f32_16x16x32_bf16 v[20:23], v[140:143], v[172:175], v[20:23]
	v_mfma_f32_16x16x32_bf16 v[76:79], v[132:135], v[194:197], v[76:79]
	v_mfma_f32_16x16x32_bf16 v[12:15], v[140:143], v[194:197], v[12:15]
	v_mfma_f32_16x16x32_bf16 v[72:75], v[132:135], v[210:213], v[72:75]
	v_mfma_f32_16x16x32_bf16 v[0:3], v[140:143], v[210:213], v[0:3]
	v_mfma_f32_16x16x32_bf16 v[88:91], v[144:147], v[160:163], v[88:91]
	v_mfma_f32_16x16x32_bf16 v[28:31], v[152:155], v[160:163], v[28:31]
	v_mfma_f32_16x16x32_bf16 v[80:83], v[144:147], v[168:171], v[80:83]
	v_mfma_f32_16x16x32_bf16 v[16:19], v[152:155], v[168:171], v[16:19]
	v_mfma_f32_16x16x32_bf16 v[68:71], v[144:147], v[190:193], v[68:71]
	v_mfma_f32_16x16x32_bf16 v[8:11], v[152:155], v[190:193], v[8:11]
	v_mfma_f32_16x16x32_bf16 v[64:67], v[144:147], v[198:201], v[64:67]
	v_mfma_f32_16x16x32_bf16 v[4:7], v[152:155], v[198:201], v[4:7]
	v_mfma_f32_16x16x32_bf16 v[88:91], v[148:151], v[164:167], v[88:91]
	s_add_i32 vcc_hi, vcc_hi, 2
	v_mfma_f32_16x16x32_bf16 v[28:31], v[156:159], v[164:167], v[28:31]
	s_add_u32 s4, s4, 0x100
	v_mfma_f32_16x16x32_bf16 v[80:83], v[148:151], v[172:175], v[80:83]
	s_addc_u32 s5, s5, 0
	v_mfma_f32_16x16x32_bf16 v[16:19], v[156:159], v[172:175], v[16:19]
	s_add_u32 s65, s65, 0x100
	v_mfma_f32_16x16x32_bf16 v[68:71], v[148:151], v[194:197], v[68:71]
	s_addc_u32 vcc_lo, vcc_lo, 0
	v_mfma_f32_16x16x32_bf16 v[8:11], v[156:159], v[194:197], v[8:11]
	s_cmp_gt_u32 vcc_hi, 29
	v_mfma_f32_16x16x32_bf16 v[64:67], v[148:151], v[210:213], v[64:67]
	s_setprio 2
	s_barrier
	v_mfma_f32_16x16x32_bf16 v[4:7], v[156:159], v[210:213], v[4:7]
	s_setprio 0
	s_cbranch_scc0 .LBB0_399
	s_and_b64 vcc, exec, s[26:27]
	s_cbranch_vccz .LBB0_402
	s_barrier

.LBB0_541:
	ds_read_b128 v[128:131], v157
	ds_read_b128 v[132:135], v157 offset:1024
	ds_read_b128 v[136:139], v157 offset:2048
	ds_read_b128 v[140:143], v157 offset:3072
	ds_read_b128 v[160:163], v158
	ds_read_b128 v[164:167], v158 offset:1024
	ds_read_b128 v[168:171], v158 offset:2048
	ds_read_b128 v[172:175], v158 offset:3072
	ds_read_b128 v[178:181], v159
	ds_read_b128 v[182:185], v159 offset:1024
	ds_read_b128 v[186:189], v159 offset:2048
	ds_read_b128 v[190:193], v159 offset:3072
	ds_read_b128 v[194:197], v159 offset:4096
	ds_read_b128 v[206:209], v159 offset:5120
	ds_read_b128 v[210:213], v159 offset:6144
	ds_read_b128 v[214:217], v159 offset:7168
	s_add_i32 m0, s66, 0xc000
	v_lshl_add_u64 v[152:153], s[56:57], 0, v[148:149]
	global_load_lds_dwordx4 v[152:153], off
	s_add_i32 m0, s66, 0xe000
	v_lshl_add_u64 v[152:153], s[56:57], 0, v[150:151]
	global_load_lds_dwordx4 v[152:153], off
	s_waitcnt vmcnt(8) lgkmcnt(0)
	s_setprio 1
	s_barrier
	v_mfma_f32_16x16x32_bf16 v[124:127], v[128:131], v[178:181], v[124:127]
	v_mfma_f32_16x16x32_bf16 v[120:123], v[136:139], v[178:181], v[120:123]
	v_mfma_f32_16x16x32_bf16 v[112:115], v[128:131], v[186:189], v[112:115]
	s_add_u32 s58, s56, 0x100
	v_mfma_f32_16x16x32_bf16 v[108:111], v[136:139], v[186:189], v[108:111]
	s_addc_u32 s59, s57, 0
	v_mfma_f32_16x16x32_bf16 v[96:99], v[128:131], v[194:197], v[96:99]
	s_cmpk_eq_i32 s89, 0x54
	v_mfma_f32_16x16x32_bf16 v[92:95], v[136:139], v[194:197], v[92:95]
	s_cselect_b32 s63, s12, s59
	v_mfma_f32_16x16x32_bf16 v[80:83], v[128:131], v[210:213], v[80:83]
	s_cselect_b32 s62, s55, s58
	v_mfma_f32_16x16x32_bf16 v[76:79], v[136:139], v[210:213], v[76:79]
	s_cselect_b32 s61, s85, s88
	v_mfma_f32_16x16x32_bf16 v[124:127], v[132:135], v[182:185], v[124:127]
	s_cselect_b32 s60, s86, s87
	v_mfma_f32_16x16x32_bf16 v[120:123], v[140:143], v[182:185], v[120:123]
	v_mfma_f32_16x16x32_bf16 v[112:115], v[132:135], v[190:193], v[112:115]
	v_mfma_f32_16x16x32_bf16 v[108:111], v[140:143], v[190:193], v[108:111]
	v_mfma_f32_16x16x32_bf16 v[96:99], v[132:135], v[206:209], v[96:99]
	v_mfma_f32_16x16x32_bf16 v[92:95], v[140:143], v[206:209], v[92:95]
	v_mfma_f32_16x16x32_bf16 v[80:83], v[132:135], v[214:217], v[80:83]
	v_mfma_f32_16x16x32_bf16 v[76:79], v[140:143], v[214:217], v[76:79]
	v_mfma_f32_16x16x32_bf16 v[116:119], v[160:163], v[178:181], v[116:119]
	v_mfma_f32_16x16x32_bf16 v[104:107], v[168:171], v[178:181], v[104:107]
	v_mfma_f32_16x16x32_bf16 v[100:103], v[160:163], v[186:189], v[100:103]
	v_mfma_f32_16x16x32_bf16 v[88:91], v[168:171], v[186:189], v[88:91]
	v_mfma_f32_16x16x32_bf16 v[84:87], v[160:163], v[194:197], v[84:87]
	v_mfma_f32_16x16x32_bf16 v[72:75], v[168:171], v[194:197], v[72:75]
	v_mfma_f32_16x16x32_bf16 v[68:71], v[160:163], v[210:213], v[68:71]
	v_mfma_f32_16x16x32_bf16 v[64:67], v[168:171], v[210:213], v[64:67]
	v_mfma_f32_16x16x32_bf16 v[116:119], v[164:167], v[182:185], v[116:119]
	v_mfma_f32_16x16x32_bf16 v[104:107], v[172:175], v[182:185], v[104:107]
	v_mfma_f32_16x16x32_bf16 v[100:103], v[164:167], v[190:193], v[100:103]
	v_mfma_f32_16x16x32_bf16 v[88:91], v[172:175], v[190:193], v[88:91]
	v_mfma_f32_16x16x32_bf16 v[84:87], v[164:167], v[206:209], v[84:87]
	v_mfma_f32_16x16x32_bf16 v[72:75], v[172:175], v[206:209], v[72:75]
	v_mfma_f32_16x16x32_bf16 v[68:71], v[164:167], v[214:217], v[68:71]
	s_setprio 2
	s_barrier
	v_mfma_f32_16x16x32_bf16 v[64:67], v[172:175], v[214:217], v[64:67]
	s_setprio 0
	ds_read_b128 v[178:181], v159 offset:16384
	ds_read_b128 v[182:185], v159 offset:17408
	ds_read_b128 v[186:189], v159 offset:18432
	ds_read_b128 v[190:193], v159 offset:19456
	ds_read_b128 v[194:197], v159 offset:20480
	ds_read_b128 v[206:209], v159 offset:21504
	ds_read_b128 v[210:213], v159 offset:22528
	ds_read_b128 v[214:217], v159 offset:23552
	s_add_i32 s0, s79, s65
	s_mov_b32 m0, s0
	v_lshl_add_u64 v[152:153], s[60:61], 0, v[146:147]
	global_load_lds_dwordx4 v[152:153], off
	s_add_i32 m0, s0, 0x2000
	s_add_u32 s0, s60, 0x160000
	v_lshl_add_u64 v[198:199], s[60:61], 0, v[144:145]
	s_addc_u32 s1, s61, 0
	s_add_i32 s2, s80, s65
	global_load_lds_dwordx4 v[198:199], off
	v_lshl_add_u64 v[202:203], s[0:1], 0, v[146:147]
	s_mov_b32 m0, s2
	v_lshl_add_u64 v[218:219], s[62:63], 0, v[144:145]
	global_load_lds_dwordx4 v[202:203], off
	s_add_i32 m0, s2, 0x2000
	v_lshl_add_u64 v[202:203], s[0:1], 0, v[144:145]
	global_load_lds_dwordx4 v[202:203], off
	s_mov_b32 m0, s66
	v_lshl_add_u64 v[202:203], s[62:63], 0, v[146:147]
	global_load_lds_dwordx4 v[202:203], off
	s_mov_b32 m0, s67
	s_nop 0
	global_load_lds_dwordx4 v[218:219], off
	s_waitcnt vmcnt(8) lgkmcnt(0)
	s_setprio 1
	s_barrier
	v_mfma_f32_16x16x32_bf16 v[60:63], v[128:131], v[178:181], v[60:63]
	v_mfma_f32_16x16x32_bf16 v[56:59], v[136:139], v[178:181], v[56:59]
	v_mfma_f32_16x16x32_bf16 v[48:51], v[128:131], v[186:189], v[48:51]
	v_mfma_f32_16x16x32_bf16 v[44:47], v[136:139], v[186:189], v[44:47]
	v_mfma_f32_16x16x32_bf16 v[32:35], v[128:131], v[194:197], v[32:35]
	v_mfma_f32_16x16x32_bf16 v[28:31], v[136:139], v[194:197], v[28:31]
	v_mfma_f32_16x16x32_bf16 v[16:19], v[128:131], v[210:213], v[16:19]
	v_mfma_f32_16x16x32_bf16 v[12:15], v[136:139], v[210:213], v[12:15]
	v_mfma_f32_16x16x32_bf16 v[60:63], v[132:135], v[182:185], v[60:63]
	v_mfma_f32_16x16x32_bf16 v[56:59], v[140:143], v[182:185], v[56:59]
	v_mfma_f32_16x16x32_bf16 v[48:51], v[132:135], v[190:193], v[48:51]
	v_mfma_f32_16x16x32_bf16 v[44:47], v[140:143], v[190:193], v[44:47]
	v_mfma_f32_16x16x32_bf16 v[32:35], v[132:135], v[206:209], v[32:35]
	v_mfma_f32_16x16x32_bf16 v[28:31], v[140:143], v[206:209], v[28:31]
	v_mfma_f32_16x16x32_bf16 v[16:19], v[132:135], v[214:217], v[16:19]
	v_mfma_f32_16x16x32_bf16 v[12:15], v[140:143], v[214:217], v[12:15]
	v_mfma_f32_16x16x32_bf16 v[52:55], v[160:163], v[178:181], v[52:55]
	v_mfma_f32_16x16x32_bf16 v[40:43], v[168:171], v[178:181], v[40:43]
	v_mfma_f32_16x16x32_bf16 v[36:39], v[160:163], v[186:189], v[36:39]
	v_mfma_f32_16x16x32_bf16 v[24:27], v[168:171], v[186:189], v[24:27]
	v_mfma_f32_16x16x32_bf16 v[20:23], v[160:163], v[194:197], v[20:23]
	v_mfma_f32_16x16x32_bf16 v[8:11], v[168:171], v[194:197], v[8:11]
	v_mfma_f32_16x16x32_bf16 v[4:7], v[160:163], v[210:213], v[4:7]
	v_mfma_f32_16x16x32_bf16 v[0:3], v[168:171], v[210:213], v[0:3]
	v_mfma_f32_16x16x32_bf16 v[52:55], v[164:167], v[182:185], v[52:55]
	v_mfma_f32_16x16x32_bf16 v[40:43], v[172:175], v[182:185], v[40:43]
	v_mfma_f32_16x16x32_bf16 v[36:39], v[164:167], v[190:193], v[36:39]
	v_mfma_f32_16x16x32_bf16 v[24:27], v[172:175], v[190:193], v[24:27]
	v_mfma_f32_16x16x32_bf16 v[20:23], v[164:167], v[206:209], v[20:23]
	v_mfma_f32_16x16x32_bf16 v[8:11], v[172:175], v[206:209], v[8:11]
	v_mfma_f32_16x16x32_bf16 v[4:7], v[164:167], v[214:217], v[4:7]
	s_setprio 2
	s_barrier
	v_mfma_f32_16x16x32_bf16 v[0:3], v[172:175], v[214:217], v[0:3]
	s_setprio 0
	ds_read_b128 v[178:181], v159 offset:32768
	ds_read_b128 v[182:185], v159 offset:33792
	ds_read_b128 v[186:189], v159 offset:34816
	ds_read_b128 v[190:193], v159 offset:35840
	ds_read_b128 v[194:197], v159 offset:36864
	ds_read_b128 v[206:209], v159 offset:37888
	ds_read_b128 v[210:213], v159 offset:38912
	ds_read_b128 v[214:217], v159 offset:39936
	s_add_i32 s2, 0, 0x18000
	s_add_i32 s3, 0, 0x1c000
	v_add_u32_e32 v140, s2, v156
	v_add_u32_e32 v172, s3, v156
	ds_read_b128 v[128:131], v140
	ds_read_b128 v[132:135], v140 offset:1024
	ds_read_b128 v[136:139], v140 offset:2048
	ds_read_b128 v[140:143], v140 offset:3072
	ds_read_b128 v[160:163], v172
	ds_read_b128 v[164:167], v172 offset:1024
	ds_read_b128 v[168:171], v172 offset:2048
	ds_read_b128 v[172:175], v172 offset:3072
	s_add_u32 s0, s62, 0x160000
	s_addc_u32 s1, s63, 0
	s_mov_b32 m0, s68
	v_lshl_add_u64 v[220:221], s[0:1], 0, v[146:147]
	global_load_lds_dwordx4 v[220:221], off
	s_mov_b32 m0, s69
	v_lshl_add_u64 v[220:221], s[0:1], 0, v[144:145]
	global_load_lds_dwordx4 v[220:221], off
	s_waitcnt vmcnt(8) lgkmcnt(0)
	s_setprio 1
	s_barrier
	v_mfma_f32_16x16x32_bf16 v[124:127], v[128:131], v[178:181], v[124:127]
	v_mfma_f32_16x16x32_bf16 v[120:123], v[136:139], v[178:181], v[120:123]
	v_mfma_f32_16x16x32_bf16 v[112:115], v[128:131], v[186:189], v[112:115]
	v_mfma_f32_16x16x32_bf16 v[108:111], v[136:139], v[186:189], v[108:111]
	v_mfma_f32_16x16x32_bf16 v[96:99], v[128:131], v[194:197], v[96:99]
	v_mfma_f32_16x16x32_bf16 v[92:95], v[136:139], v[194:197], v[92:95]
	v_mfma_f32_16x16x32_bf16 v[80:83], v[128:131], v[210:213], v[80:83]
	v_mfma_f32_16x16x32_bf16 v[76:79], v[136:139], v[210:213], v[76:79]
	v_mfma_f32_16x16x32_bf16 v[124:127], v[132:135], v[182:185], v[124:127]
	v_mfma_f32_16x16x32_bf16 v[120:123], v[140:143], v[182:185], v[120:123]
	v_mfma_f32_16x16x32_bf16 v[112:115], v[132:135], v[190:193], v[112:115]
	v_mfma_f32_16x16x32_bf16 v[108:111], v[140:143], v[190:193], v[108:111]
	v_mfma_f32_16x16x32_bf16 v[96:99], v[132:135], v[206:209], v[96:99]
	v_mfma_f32_16x16x32_bf16 v[92:95], v[140:143], v[206:209], v[92:95]
	v_mfma_f32_16x16x32_bf16 v[80:83], v[132:135], v[214:217], v[80:83]
	v_mfma_f32_16x16x32_bf16 v[76:79], v[140:143], v[214:217], v[76:79]
	v_mfma_f32_16x16x32_bf16 v[116:119], v[160:163], v[178:181], v[116:119]
	v_mfma_f32_16x16x32_bf16 v[104:107], v[168:171], v[178:181], v[104:107]
	v_mfma_f32_16x16x32_bf16 v[100:103], v[160:163], v[186:189], v[100:103]
	v_mfma_f32_16x16x32_bf16 v[88:91], v[168:171], v[186:189], v[88:91]
	v_mfma_f32_16x16x32_bf16 v[84:87], v[160:163], v[194:197], v[84:87]
	v_mfma_f32_16x16x32_bf16 v[72:75], v[168:171], v[194:197], v[72:75]
	v_mfma_f32_16x16x32_bf16 v[68:71], v[160:163], v[210:213], v[68:71]
	v_mfma_f32_16x16x32_bf16 v[64:67], v[168:171], v[210:213], v[64:67]
	v_mfma_f32_16x16x32_bf16 v[116:119], v[164:167], v[182:185], v[116:119]
	v_mfma_f32_16x16x32_bf16 v[104:107], v[172:175], v[182:185], v[104:107]
	v_mfma_f32_16x16x32_bf16 v[100:103], v[164:167], v[190:193], v[100:103]
	v_mfma_f32_16x16x32_bf16 v[88:91], v[172:175], v[190:193], v[88:91]
	v_mfma_f32_16x16x32_bf16 v[84:87], v[164:167], v[206:209], v[84:87]
	v_mfma_f32_16x16x32_bf16 v[72:75], v[172:175], v[206:209], v[72:75]
	v_mfma_f32_16x16x32_bf16 v[68:71], v[164:167], v[214:217], v[68:71]
	s_setprio 2
	s_barrier
	v_mfma_f32_16x16x32_bf16 v[64:67], v[172:175], v[214:217], v[64:67]
	s_setprio 0
	ds_read_b128 v[178:181], v159 offset:49152
	ds_read_b128 v[182:185], v159 offset:50176
	ds_read_b128 v[186:189], v159 offset:51200
	ds_read_b128 v[190:193], v159 offset:52224
	ds_read_b128 v[194:197], v159 offset:53248
	ds_read_b128 v[206:209], v159 offset:54272
	ds_read_b128 v[210:213], v159 offset:55296
	ds_read_b128 v[214:217], v159 offset:56320
	s_add_i32 s0, s2, s65
	s_mov_b32 m0, s0
	v_lshl_add_u64 v[152:153], v[152:153], 0, s[10:11]
	global_load_lds_dwordx4 v[152:153], off
	s_add_i32 m0, s0, 0x2000
	s_add_u32 s0, s60, 0x160080
	v_lshl_add_u64 v[152:153], v[198:199], 0, s[10:11]
	s_addc_u32 s1, s61, 0
	s_add_i32 s2, s3, s65
	global_load_lds_dwordx4 v[152:153], off
	s_mov_b32 m0, s2
	v_lshl_add_u64 v[152:153], s[0:1], 0, v[146:147]
	global_load_lds_dwordx4 v[152:153], off
	s_add_i32 m0, s2, 0x2000
	v_lshl_add_u64 v[152:153], s[0:1], 0, v[144:145]
	global_load_lds_dwordx4 v[152:153], off
	s_mov_b32 m0, s77
	v_lshl_add_u64 v[152:153], v[202:203], 0, s[10:11]
	global_load_lds_dwordx4 v[152:153], off
	s_mov_b32 m0, s78
	v_lshl_add_u64 v[152:153], v[218:219], 0, s[10:11]
	global_load_lds_dwordx4 v[152:153], off
	s_waitcnt vmcnt(8) lgkmcnt(0)
	s_setprio 1
	s_barrier
	v_mfma_f32_16x16x32_bf16 v[60:63], v[128:131], v[178:181], v[60:63]
	v_mfma_f32_16x16x32_bf16 v[56:59], v[136:139], v[178:181], v[56:59]
	v_mfma_f32_16x16x32_bf16 v[48:51], v[128:131], v[186:189], v[48:51]
	v_mfma_f32_16x16x32_bf16 v[44:47], v[136:139], v[186:189], v[44:47]
	v_mfma_f32_16x16x32_bf16 v[32:35], v[128:131], v[194:197], v[32:35]
	v_mfma_f32_16x16x32_bf16 v[28:31], v[136:139], v[194:197], v[28:31]
	v_mfma_f32_16x16x32_bf16 v[16:19], v[128:131], v[210:213], v[16:19]
	v_mfma_f32_16x16x32_bf16 v[12:15], v[136:139], v[210:213], v[12:15]
	v_mfma_f32_16x16x32_bf16 v[60:63], v[132:135], v[182:185], v[60:63]
	v_mfma_f32_16x16x32_bf16 v[56:59], v[140:143], v[182:185], v[56:59]
	v_mfma_f32_16x16x32_bf16 v[48:51], v[132:135], v[190:193], v[48:51]
	v_mfma_f32_16x16x32_bf16 v[44:47], v[140:143], v[190:193], v[44:47]
	v_mfma_f32_16x16x32_bf16 v[32:35], v[132:135], v[206:209], v[32:35]
	v_mfma_f32_16x16x32_bf16 v[28:31], v[140:143], v[206:209], v[28:31]
	v_mfma_f32_16x16x32_bf16 v[16:19], v[132:135], v[214:217], v[16:19]
	v_mfma_f32_16x16x32_bf16 v[12:15], v[140:143], v[214:217], v[12:15]
	v_mfma_f32_16x16x32_bf16 v[52:55], v[160:163], v[178:181], v[52:55]
	v_mfma_f32_16x16x32_bf16 v[40:43], v[168:171], v[178:181], v[40:43]
	v_mfma_f32_16x16x32_bf16 v[36:39], v[160:163], v[186:189], v[36:39]
	v_mfma_f32_16x16x32_bf16 v[24:27], v[168:171], v[186:189], v[24:27]
	v_mfma_f32_16x16x32_bf16 v[20:23], v[160:163], v[194:197], v[20:23]
	v_mfma_f32_16x16x32_bf16 v[8:11], v[168:171], v[194:197], v[8:11]
	v_mfma_f32_16x16x32_bf16 v[4:7], v[160:163], v[210:213], v[4:7]
	v_mfma_f32_16x16x32_bf16 v[0:3], v[168:171], v[210:213], v[0:3]
	v_mfma_f32_16x16x32_bf16 v[52:55], v[164:167], v[182:185], v[52:55]
	v_mfma_f32_16x16x32_bf16 v[40:43], v[172:175], v[182:185], v[40:43]
	s_add_i32 s89, s89, 2
	v_mfma_f32_16x16x32_bf16 v[36:39], v[164:167], v[190:193], v[36:39]
	s_add_u32 s87, s87, 0x100
	v_mfma_f32_16x16x32_bf16 v[24:27], v[172:175], v[190:193], v[24:27]
	s_addc_u32 s88, s88, 0
	v_mfma_f32_16x16x32_bf16 v[20:23], v[164:167], v[206:209], v[20:23]
	s_cmpk_gt_u32 s89, 0x55
	v_mfma_f32_16x16x32_bf16 v[8:11], v[172:175], v[206:209], v[8:11]
	s_mov_b64 s[56:57], s[58:59]
	v_mfma_f32_16x16x32_bf16 v[4:7], v[164:167], v[214:217], v[4:7]
	s_setprio 2
	s_barrier
	v_mfma_f32_16x16x32_bf16 v[0:3], v[172:175], v[214:217], v[0:3]
	s_setprio 0
	s_cbranch_scc0 .LBB0_541
	s_and_b64 vcc, exec, s[14:15]
	s_cbranch_vccz .LBB0_544
	s_barrier

.LBB0_666:
	ds_read_b128 v[140:143], v147
	ds_read_b128 v[150:153], v147 offset:1024
	ds_read_b128 v[154:157], v147 offset:2048
	ds_read_b128 v[158:161], v147 offset:3072
	ds_read_b128 v[162:165], v148
	ds_read_b128 v[166:169], v148 offset:1024
	ds_read_b128 v[170:173], v148 offset:2048
	ds_read_b128 v[178:181], v148 offset:3072
	ds_read_b128 v[182:185], v149
	ds_read_b128 v[186:189], v149 offset:1024
	ds_read_b128 v[190:193], v149 offset:2048
	ds_read_b128 v[194:197], v149 offset:3072
	ds_read_b128 v[206:209], v149 offset:4096
	ds_read_b128 v[210:213], v149 offset:5120
	ds_read_b128 v[214:217], v149 offset:6144
	ds_read_b128 v[218:221], v149 offset:7168
	s_add_i32 m0, s27, 0xc000
	v_lshl_add_u64 v[174:175], s[28:29], 0, v[136:137]
	global_load_lds_dwordx4 v[174:175], off
	s_add_i32 m0, s27, 0xe000
	v_lshl_add_u64 v[174:175], s[28:29], 0, v[138:139]
	global_load_lds_dwordx4 v[174:175], off
	s_waitcnt vmcnt(8) lgkmcnt(0)
	s_setprio 1
	s_barrier
	v_mfma_f32_16x16x32_bf16 v[124:127], v[140:143], v[182:185], v[124:127]
	v_mfma_f32_16x16x32_bf16 v[120:123], v[154:157], v[182:185], v[120:123]
	v_mfma_f32_16x16x32_bf16 v[116:119], v[140:143], v[190:193], v[116:119]
	s_add_u32 s0, s28, 0xfff80080
	v_mfma_f32_16x16x32_bf16 v[108:111], v[154:157], v[190:193], v[108:111]
	s_addc_u32 s1, s29, -1
	v_mfma_f32_16x16x32_bf16 v[100:103], v[140:143], v[206:209], v[100:103]
	s_cmp_eq_u32 s71, 28
	v_mfma_f32_16x16x32_bf16 v[92:95], v[154:157], v[206:209], v[92:95]
	s_cselect_b32 s35, s15, s1
	v_mfma_f32_16x16x32_bf16 v[84:87], v[140:143], v[214:217], v[84:87]
	s_cselect_b32 s34, s66, s0
	v_mfma_f32_16x16x32_bf16 v[76:79], v[154:157], v[214:217], v[76:79]
	s_cselect_b32 s31, s67, s70
	v_mfma_f32_16x16x32_bf16 v[124:127], v[150:153], v[186:189], v[124:127]
	s_cselect_b32 s30, s68, s69
	v_mfma_f32_16x16x32_bf16 v[120:123], v[158:161], v[186:189], v[120:123]
	v_mfma_f32_16x16x32_bf16 v[116:119], v[150:153], v[194:197], v[116:119]
	v_mfma_f32_16x16x32_bf16 v[108:111], v[158:161], v[194:197], v[108:111]
	v_mfma_f32_16x16x32_bf16 v[100:103], v[150:153], v[210:213], v[100:103]
	v_mfma_f32_16x16x32_bf16 v[92:95], v[158:161], v[210:213], v[92:95]
	v_mfma_f32_16x16x32_bf16 v[84:87], v[150:153], v[218:221], v[84:87]
	v_mfma_f32_16x16x32_bf16 v[76:79], v[158:161], v[218:221], v[76:79]
	v_mfma_f32_16x16x32_bf16 v[112:115], v[162:165], v[182:185], v[112:115]
	v_mfma_f32_16x16x32_bf16 v[104:107], v[170:173], v[182:185], v[104:107]
	v_mfma_f32_16x16x32_bf16 v[96:99], v[162:165], v[190:193], v[96:99]
	v_mfma_f32_16x16x32_bf16 v[88:91], v[170:173], v[190:193], v[88:91]
	v_mfma_f32_16x16x32_bf16 v[80:83], v[162:165], v[206:209], v[80:83]
	v_mfma_f32_16x16x32_bf16 v[72:75], v[170:173], v[206:209], v[72:75]
	v_mfma_f32_16x16x32_bf16 v[68:71], v[162:165], v[214:217], v[68:71]
	v_mfma_f32_16x16x32_bf16 v[64:67], v[170:173], v[214:217], v[64:67]
	v_mfma_f32_16x16x32_bf16 v[112:115], v[166:169], v[186:189], v[112:115]
	v_mfma_f32_16x16x32_bf16 v[104:107], v[178:181], v[186:189], v[104:107]
	v_mfma_f32_16x16x32_bf16 v[96:99], v[166:169], v[194:197], v[96:99]
	v_mfma_f32_16x16x32_bf16 v[88:91], v[178:181], v[194:197], v[88:91]
	v_mfma_f32_16x16x32_bf16 v[80:83], v[166:169], v[210:213], v[80:83]
	v_mfma_f32_16x16x32_bf16 v[72:75], v[178:181], v[210:213], v[72:75]
	v_mfma_f32_16x16x32_bf16 v[68:71], v[166:169], v[218:221], v[68:71]
	s_setprio 2
	s_barrier
	v_mfma_f32_16x16x32_bf16 v[64:67], v[178:181], v[218:221], v[64:67]
	s_setprio 0
	ds_read_b128 v[182:185], v149 offset:16384
	ds_read_b128 v[186:189], v149 offset:17408
	ds_read_b128 v[190:193], v149 offset:18432
	ds_read_b128 v[194:197], v149 offset:19456
	ds_read_b128 v[206:209], v149 offset:20480
	ds_read_b128 v[210:213], v149 offset:21504
	ds_read_b128 v[214:217], v149 offset:22528
	ds_read_b128 v[218:221], v149 offset:23552
	s_add_i32 s0, s62, s53
	s_mov_b32 m0, s0
	v_lshl_add_u64 v[174:175], s[30:31], 0, v[132:133]
	global_load_lds_dwordx4 v[174:175], off
	s_add_i32 m0, s0, 0x2000
	s_add_u32 s0, s30, 0x80000
	v_lshl_add_u64 v[198:199], s[30:31], 0, v[128:129]
	s_addc_u32 s1, s31, 0
	s_add_i32 s2, s63, s53
	global_load_lds_dwordx4 v[198:199], off
	v_lshl_add_u64 v[202:203], s[0:1], 0, v[132:133]
	s_mov_b32 m0, s2
	v_lshl_add_u64 v[222:223], s[34:35], 0, v[130:131]
	global_load_lds_dwordx4 v[202:203], off
	s_add_i32 m0, s2, 0x2000
	v_lshl_add_u64 v[202:203], s[0:1], 0, v[128:129]
	global_load_lds_dwordx4 v[202:203], off
	s_mov_b32 m0, s27
	v_lshl_add_u64 v[202:203], s[34:35], 0, v[134:135]
	global_load_lds_dwordx4 v[202:203], off
	s_mov_b32 m0, s55
	s_nop 0
	global_load_lds_dwordx4 v[222:223], off
	s_waitcnt vmcnt(8) lgkmcnt(0)
	s_setprio 1
	s_barrier
	v_mfma_f32_16x16x32_bf16 v[60:63], v[140:143], v[182:185], v[60:63]
	v_mfma_f32_16x16x32_bf16 v[56:59], v[154:157], v[182:185], v[56:59]
	v_mfma_f32_16x16x32_bf16 v[52:55], v[140:143], v[190:193], v[52:55]
	v_mfma_f32_16x16x32_bf16 v[44:47], v[154:157], v[190:193], v[44:47]
	v_mfma_f32_16x16x32_bf16 v[36:39], v[140:143], v[206:209], v[36:39]
	v_mfma_f32_16x16x32_bf16 v[28:31], v[154:157], v[206:209], v[28:31]
	v_mfma_f32_16x16x32_bf16 v[20:23], v[140:143], v[214:217], v[20:23]
	v_mfma_f32_16x16x32_bf16 v[12:15], v[154:157], v[214:217], v[12:15]
	v_mfma_f32_16x16x32_bf16 v[60:63], v[150:153], v[186:189], v[60:63]
	v_mfma_f32_16x16x32_bf16 v[56:59], v[158:161], v[186:189], v[56:59]
	v_mfma_f32_16x16x32_bf16 v[52:55], v[150:153], v[194:197], v[52:55]
	v_mfma_f32_16x16x32_bf16 v[44:47], v[158:161], v[194:197], v[44:47]
	v_mfma_f32_16x16x32_bf16 v[36:39], v[150:153], v[210:213], v[36:39]
	v_mfma_f32_16x16x32_bf16 v[28:31], v[158:161], v[210:213], v[28:31]
	v_mfma_f32_16x16x32_bf16 v[20:23], v[150:153], v[218:221], v[20:23]
	v_mfma_f32_16x16x32_bf16 v[12:15], v[158:161], v[218:221], v[12:15]
	v_mfma_f32_16x16x32_bf16 v[48:51], v[162:165], v[182:185], v[48:51]
	v_mfma_f32_16x16x32_bf16 v[40:43], v[170:173], v[182:185], v[40:43]
	v_mfma_f32_16x16x32_bf16 v[32:35], v[162:165], v[190:193], v[32:35]
	v_mfma_f32_16x16x32_bf16 v[24:27], v[170:173], v[190:193], v[24:27]
	v_mfma_f32_16x16x32_bf16 v[16:19], v[162:165], v[206:209], v[16:19]
	v_mfma_f32_16x16x32_bf16 v[8:11], v[170:173], v[206:209], v[8:11]
	v_mfma_f32_16x16x32_bf16 v[4:7], v[162:165], v[214:217], v[4:7]
	v_mfma_f32_16x16x32_bf16 v[0:3], v[170:173], v[214:217], v[0:3]
	v_mfma_f32_16x16x32_bf16 v[48:51], v[166:169], v[186:189], v[48:51]
	v_mfma_f32_16x16x32_bf16 v[40:43], v[178:181], v[186:189], v[40:43]
	v_mfma_f32_16x16x32_bf16 v[32:35], v[166:169], v[194:197], v[32:35]
	v_mfma_f32_16x16x32_bf16 v[24:27], v[178:181], v[194:197], v[24:27]
	v_mfma_f32_16x16x32_bf16 v[16:19], v[166:169], v[210:213], v[16:19]
	v_mfma_f32_16x16x32_bf16 v[8:11], v[178:181], v[210:213], v[8:11]
	v_mfma_f32_16x16x32_bf16 v[4:7], v[166:169], v[218:221], v[4:7]
	s_setprio 2
	s_barrier
	v_mfma_f32_16x16x32_bf16 v[0:3], v[178:181], v[218:221], v[0:3]
	s_setprio 0
	ds_read_b128 v[182:185], v149 offset:32768
	ds_read_b128 v[186:189], v149 offset:33792
	ds_read_b128 v[190:193], v149 offset:34816
	ds_read_b128 v[194:197], v149 offset:35840
	ds_read_b128 v[206:209], v149 offset:36864
	ds_read_b128 v[210:213], v149 offset:37888
	ds_read_b128 v[214:217], v149 offset:38912
	ds_read_b128 v[218:221], v149 offset:39936
	s_add_i32 s2, 0, 0x18000
	s_add_i32 s3, 0, 0x1c000
	v_add_u32_e32 v158, s2, v146
	v_add_u32_e32 v177, s3, v146
	ds_read_b128 v[140:143], v158
	ds_read_b128 v[150:153], v158 offset:1024
	ds_read_b128 v[154:157], v158 offset:2048
	ds_read_b128 v[158:161], v158 offset:3072
	ds_read_b128 v[162:165], v177
	ds_read_b128 v[166:169], v177 offset:1024
	ds_read_b128 v[170:173], v177 offset:2048
	ds_read_b128 v[178:181], v177 offset:3072
	s_add_u32 s0, s34, 0x80000
	s_addc_u32 s1, s35, 0
	s_mov_b32 m0, s56
	v_lshl_add_u64 v[224:225], s[0:1], 0, v[134:135]
	global_load_lds_dwordx4 v[224:225], off
	s_mov_b32 m0, s57
	v_lshl_add_u64 v[224:225], s[0:1], 0, v[130:131]
	global_load_lds_dwordx4 v[224:225], off
	s_waitcnt vmcnt(8) lgkmcnt(0)
	s_setprio 1
	s_barrier
	v_mfma_f32_16x16x32_bf16 v[124:127], v[140:143], v[182:185], v[124:127]
	v_mfma_f32_16x16x32_bf16 v[120:123], v[154:157], v[182:185], v[120:123]
	v_mfma_f32_16x16x32_bf16 v[116:119], v[140:143], v[190:193], v[116:119]
	v_mfma_f32_16x16x32_bf16 v[108:111], v[154:157], v[190:193], v[108:111]
	v_mfma_f32_16x16x32_bf16 v[100:103], v[140:143], v[206:209], v[100:103]
	v_mfma_f32_16x16x32_bf16 v[92:95], v[154:157], v[206:209], v[92:95]
	v_mfma_f32_16x16x32_bf16 v[84:87], v[140:143], v[214:217], v[84:87]
	v_mfma_f32_16x16x32_bf16 v[76:79], v[154:157], v[214:217], v[76:79]
	v_mfma_f32_16x16x32_bf16 v[124:127], v[150:153], v[186:189], v[124:127]
	v_mfma_f32_16x16x32_bf16 v[120:123], v[158:161], v[186:189], v[120:123]
	v_mfma_f32_16x16x32_bf16 v[116:119], v[150:153], v[194:197], v[116:119]
	v_mfma_f32_16x16x32_bf16 v[108:111], v[158:161], v[194:197], v[108:111]
	v_mfma_f32_16x16x32_bf16 v[100:103], v[150:153], v[210:213], v[100:103]
	v_mfma_f32_16x16x32_bf16 v[92:95], v[158:161], v[210:213], v[92:95]
	v_mfma_f32_16x16x32_bf16 v[84:87], v[150:153], v[218:221], v[84:87]
	v_mfma_f32_16x16x32_bf16 v[76:79], v[158:161], v[218:221], v[76:79]
	v_mfma_f32_16x16x32_bf16 v[112:115], v[162:165], v[182:185], v[112:115]
	v_mfma_f32_16x16x32_bf16 v[104:107], v[170:173], v[182:185], v[104:107]
	v_mfma_f32_16x16x32_bf16 v[96:99], v[162:165], v[190:193], v[96:99]
	v_mfma_f32_16x16x32_bf16 v[88:91], v[170:173], v[190:193], v[88:91]
	v_mfma_f32_16x16x32_bf16 v[80:83], v[162:165], v[206:209], v[80:83]
	v_mfma_f32_16x16x32_bf16 v[72:75], v[170:173], v[206:209], v[72:75]
	v_mfma_f32_16x16x32_bf16 v[68:71], v[162:165], v[214:217], v[68:71]
	v_mfma_f32_16x16x32_bf16 v[64:67], v[170:173], v[214:217], v[64:67]
	v_mfma_f32_16x16x32_bf16 v[112:115], v[166:169], v[186:189], v[112:115]
	v_mfma_f32_16x16x32_bf16 v[104:107], v[178:181], v[186:189], v[104:107]
	v_mfma_f32_16x16x32_bf16 v[96:99], v[166:169], v[194:197], v[96:99]
	v_mfma_f32_16x16x32_bf16 v[88:91], v[178:181], v[194:197], v[88:91]
	v_mfma_f32_16x16x32_bf16 v[80:83], v[166:169], v[210:213], v[80:83]
	v_mfma_f32_16x16x32_bf16 v[72:75], v[178:181], v[210:213], v[72:75]
	v_mfma_f32_16x16x32_bf16 v[68:71], v[166:169], v[218:221], v[68:71]
	s_setprio 2
	s_barrier
	v_mfma_f32_16x16x32_bf16 v[64:67], v[178:181], v[218:221], v[64:67]
	s_setprio 0
	ds_read_b128 v[182:185], v149 offset:49152
	ds_read_b128 v[186:189], v149 offset:50176
	ds_read_b128 v[190:193], v149 offset:51200
	ds_read_b128 v[194:197], v149 offset:52224
	ds_read_b128 v[206:209], v149 offset:53248
	ds_read_b128 v[210:213], v149 offset:54272
	ds_read_b128 v[214:217], v149 offset:55296
	ds_read_b128 v[218:221], v149 offset:56320
	s_add_i32 s0, s2, s53
	s_mov_b32 m0, s0
	v_lshl_add_u64 v[174:175], v[174:175], 0, s[8:9]
	global_load_lds_dwordx4 v[174:175], off
	s_add_i32 m0, s0, 0x2000
	s_add_u32 s0, s30, 0x80080
	v_lshl_add_u64 v[174:175], v[198:199], 0, s[8:9]
	s_addc_u32 s1, s31, 0
	s_add_i32 s2, s3, s53
	global_load_lds_dwordx4 v[174:175], off
	s_mov_b32 m0, s2
	v_lshl_add_u64 v[174:175], s[0:1], 0, v[132:133]
	global_load_lds_dwordx4 v[174:175], off
	s_add_i32 m0, s2, 0x2000
	v_lshl_add_u64 v[174:175], s[0:1], 0, v[128:129]
	global_load_lds_dwordx4 v[174:175], off
	s_mov_b32 m0, s60
	v_lshl_add_u64 v[174:175], v[202:203], 0, s[8:9]
	global_load_lds_dwordx4 v[174:175], off
	s_mov_b32 m0, s61
	v_lshl_add_u64 v[174:175], v[222:223], 0, s[8:9]
	global_load_lds_dwordx4 v[174:175], off
	s_waitcnt vmcnt(8) lgkmcnt(0)
	s_setprio 1
	s_barrier
	v_mfma_f32_16x16x32_bf16 v[60:63], v[140:143], v[182:185], v[60:63]
	v_mfma_f32_16x16x32_bf16 v[56:59], v[154:157], v[182:185], v[56:59]
	v_mfma_f32_16x16x32_bf16 v[52:55], v[140:143], v[190:193], v[52:55]
	v_mfma_f32_16x16x32_bf16 v[44:47], v[154:157], v[190:193], v[44:47]
	v_mfma_f32_16x16x32_bf16 v[36:39], v[140:143], v[206:209], v[36:39]
	v_mfma_f32_16x16x32_bf16 v[28:31], v[154:157], v[206:209], v[28:31]
	v_mfma_f32_16x16x32_bf16 v[20:23], v[140:143], v[214:217], v[20:23]
	v_mfma_f32_16x16x32_bf16 v[12:15], v[154:157], v[214:217], v[12:15]
	v_mfma_f32_16x16x32_bf16 v[60:63], v[150:153], v[186:189], v[60:63]
	v_mfma_f32_16x16x32_bf16 v[56:59], v[158:161], v[186:189], v[56:59]
	v_mfma_f32_16x16x32_bf16 v[52:55], v[150:153], v[194:197], v[52:55]
	v_mfma_f32_16x16x32_bf16 v[44:47], v[158:161], v[194:197], v[44:47]
	v_mfma_f32_16x16x32_bf16 v[36:39], v[150:153], v[210:213], v[36:39]
	v_mfma_f32_16x16x32_bf16 v[28:31], v[158:161], v[210:213], v[28:31]
	v_mfma_f32_16x16x32_bf16 v[20:23], v[150:153], v[218:221], v[20:23]
	v_mfma_f32_16x16x32_bf16 v[12:15], v[158:161], v[218:221], v[12:15]
	v_mfma_f32_16x16x32_bf16 v[48:51], v[162:165], v[182:185], v[48:51]
	v_mfma_f32_16x16x32_bf16 v[40:43], v[170:173], v[182:185], v[40:43]
	v_mfma_f32_16x16x32_bf16 v[32:35], v[162:165], v[190:193], v[32:35]
	v_mfma_f32_16x16x32_bf16 v[24:27], v[170:173], v[190:193], v[24:27]
	v_mfma_f32_16x16x32_bf16 v[16:19], v[162:165], v[206:209], v[16:19]
	v_mfma_f32_16x16x32_bf16 v[8:11], v[170:173], v[206:209], v[8:11]
	v_mfma_f32_16x16x32_bf16 v[4:7], v[162:165], v[214:217], v[4:7]
	v_mfma_f32_16x16x32_bf16 v[0:3], v[170:173], v[214:217], v[0:3]
	v_mfma_f32_16x16x32_bf16 v[48:51], v[166:169], v[186:189], v[48:51]
	s_add_i32 s71, s71, 2
	v_mfma_f32_16x16x32_bf16 v[40:43], v[178:181], v[186:189], v[40:43]
	s_add_u32 s28, s28, 0x100
	v_mfma_f32_16x16x32_bf16 v[32:35], v[166:169], v[194:197], v[32:35]
	s_addc_u32 s29, s29, 0
	v_mfma_f32_16x16x32_bf16 v[24:27], v[178:181], v[194:197], v[24:27]
	s_add_u32 s69, s69, 0x100
	v_mfma_f32_16x16x32_bf16 v[16:19], v[166:169], v[210:213], v[16:19]
	s_addc_u32 s70, s70, 0
	v_mfma_f32_16x16x32_bf16 v[8:11], v[178:181], v[210:213], v[8:11]
	s_cmp_gt_u32 s71, 29
	v_mfma_f32_16x16x32_bf16 v[4:7], v[166:169], v[218:221], v[4:7]
	s_setprio 2
	s_barrier
	v_mfma_f32_16x16x32_bf16 v[0:3], v[178:181], v[218:221], v[0:3]
	s_setprio 0
	s_cbranch_scc0 .LBB0_666
	s_and_b64 vcc, exec, s[12:13]
	s_cbranch_vccz .LBB0_669
	s_barrier

.LBB0_828:
	ds_read_b128 v[138:141], v145
	ds_read_b128 v[150:153], v145 offset:1024
	ds_read_b128 v[154:157], v145 offset:2048
	ds_read_b128 v[158:161], v145 offset:3072
	ds_read_b128 v[162:165], v146
	ds_read_b128 v[166:169], v146 offset:1024
	ds_read_b128 v[170:173], v146 offset:2048
	ds_read_b128 v[178:181], v146 offset:3072
	ds_read_b128 v[182:185], v147
	ds_read_b128 v[186:189], v147 offset:1024
	ds_read_b128 v[190:193], v147 offset:2048
	ds_read_b128 v[194:197], v147 offset:3072
	ds_read_b128 v[206:209], v147 offset:4096
	ds_read_b128 v[210:213], v147 offset:5120
	ds_read_b128 v[214:217], v147 offset:6144
	ds_read_b128 v[218:221], v147 offset:7168
	s_add_u32 s2, s58, s62
	s_addc_u32 s3, s59, s63
	s_add_u32 s9, s2, 0x100
	s_addc_u32 s38, s3, 0
	s_and_b64 s[0:1], s[60:61], exec
	v_cndmask_b32_e64 v137, 0, 1, s[64:65]
	s_cselect_b32 s65, s23, s38
	s_cselect_b32 s64, s12, s9
	s_add_u32 s0, s56, s62
	s_addc_u32 s1, s57, s63
	s_add_u32 s9, s0, 0x100
	s_addc_u32 s38, s1, 0
	s_and_b64 s[0:1], s[60:61], exec
	s_cselect_b32 s67, s13, s38
	s_cselect_b32 s66, s8, s9
	s_add_u32 s70, s2, 0x80080
	s_addc_u32 s71, s3, 0
	s_add_i32 s39, s87, s79
	s_add_i32 m0, s74, 0xc000
	s_add_i32 s53, s74, 0xe000
	s_add_i32 s50, s39, 0x2000
	s_add_u32 s68, s66, 0x80000
	s_addc_u32 s69, s67, 0
	s_add_i32 s51, s88, s79
	s_add_i32 s38, s51, 0x2000
	s_add_i32 s1, 0, 0x18000
	s_add_i32 s9, 0, 0x1c000
	s_add_u32 s62, s64, 0x80000
	s_addc_u32 s63, s65, 0
	s_add_i32 s3, s1, s79
	s_add_i32 s76, s3, 0x2000
	s_add_u32 s60, s66, 0x80080
	s_addc_u32 s61, s67, 0
	s_add_i32 s2, s9, s79
	s_add_i32 s0, s2, 0x2000
	v_cmp_ne_u32_e32 vcc, 1, v137
	v_lshl_add_u64 v[174:175], s[70:71], 0, v[128:129]
	global_load_lds_dwordx4 v[174:175], off
	s_mov_b32 m0, s53
	v_lshl_add_u64 v[174:175], s[70:71], 0, v[132:133]
	global_load_lds_dwordx4 v[174:175], off
	s_waitcnt vmcnt(8) lgkmcnt(0)
	s_setprio 1
	s_barrier
	v_mfma_f32_16x16x32_bf16 v[124:127], v[138:141], v[182:185], v[124:127]
	v_mfma_f32_16x16x32_bf16 v[120:123], v[154:157], v[182:185], v[120:123]
	v_mfma_f32_16x16x32_bf16 v[108:111], v[138:141], v[190:193], v[108:111]
	v_mfma_f32_16x16x32_bf16 v[104:107], v[154:157], v[190:193], v[104:107]
	v_mfma_f32_16x16x32_bf16 v[92:95], v[138:141], v[206:209], v[92:95]
	v_mfma_f32_16x16x32_bf16 v[88:91], v[154:157], v[206:209], v[88:91]
	v_mfma_f32_16x16x32_bf16 v[76:79], v[138:141], v[214:217], v[76:79]
	v_mfma_f32_16x16x32_bf16 v[72:75], v[154:157], v[214:217], v[72:75]
	v_mfma_f32_16x16x32_bf16 v[124:127], v[150:153], v[186:189], v[124:127]
	v_mfma_f32_16x16x32_bf16 v[120:123], v[158:161], v[186:189], v[120:123]
	v_mfma_f32_16x16x32_bf16 v[108:111], v[150:153], v[194:197], v[108:111]
	v_mfma_f32_16x16x32_bf16 v[104:107], v[158:161], v[194:197], v[104:107]
	v_mfma_f32_16x16x32_bf16 v[92:95], v[150:153], v[210:213], v[92:95]
	v_mfma_f32_16x16x32_bf16 v[88:91], v[158:161], v[210:213], v[88:91]
	v_mfma_f32_16x16x32_bf16 v[76:79], v[150:153], v[218:221], v[76:79]
	v_mfma_f32_16x16x32_bf16 v[72:75], v[158:161], v[218:221], v[72:75]
	v_mfma_f32_16x16x32_bf16 v[116:119], v[162:165], v[182:185], v[116:119]
	v_mfma_f32_16x16x32_bf16 v[112:115], v[170:173], v[182:185], v[112:115]
	v_mfma_f32_16x16x32_bf16 v[100:103], v[162:165], v[190:193], v[100:103]
	v_mfma_f32_16x16x32_bf16 v[96:99], v[170:173], v[190:193], v[96:99]
	v_mfma_f32_16x16x32_bf16 v[84:87], v[162:165], v[206:209], v[84:87]
	v_mfma_f32_16x16x32_bf16 v[80:83], v[170:173], v[206:209], v[80:83]
	v_mfma_f32_16x16x32_bf16 v[68:71], v[162:165], v[214:217], v[68:71]
	v_mfma_f32_16x16x32_bf16 v[64:67], v[170:173], v[214:217], v[64:67]
	v_mfma_f32_16x16x32_bf16 v[116:119], v[166:169], v[186:189], v[116:119]
	v_mfma_f32_16x16x32_bf16 v[112:115], v[178:181], v[186:189], v[112:115]
	v_mfma_f32_16x16x32_bf16 v[100:103], v[166:169], v[194:197], v[100:103]
	v_mfma_f32_16x16x32_bf16 v[96:99], v[178:181], v[194:197], v[96:99]
	v_mfma_f32_16x16x32_bf16 v[84:87], v[166:169], v[210:213], v[84:87]
	v_mfma_f32_16x16x32_bf16 v[80:83], v[178:181], v[210:213], v[80:83]
	v_mfma_f32_16x16x32_bf16 v[68:71], v[166:169], v[218:221], v[68:71]
	s_setprio 2
	s_barrier
	v_mfma_f32_16x16x32_bf16 v[64:67], v[178:181], v[218:221], v[64:67]
	s_setprio 0
	ds_read_b128 v[182:185], v147 offset:16384
	ds_read_b128 v[186:189], v147 offset:17408
	ds_read_b128 v[190:193], v147 offset:18432
	ds_read_b128 v[194:197], v147 offset:19456
	ds_read_b128 v[206:209], v147 offset:20480
	ds_read_b128 v[210:213], v147 offset:21504
	ds_read_b128 v[214:217], v147 offset:22528
	ds_read_b128 v[218:221], v147 offset:23552
	s_mov_b32 m0, s39
	v_lshl_add_u64 v[174:175], s[66:67], 0, v[130:131]
	global_load_lds_dwordx4 v[174:175], off
	v_lshl_add_u64 v[198:199], s[66:67], 0, v[134:135]
	s_mov_b32 m0, s50
	v_lshl_add_u64 v[202:203], s[68:69], 0, v[130:131]
	global_load_lds_dwordx4 v[198:199], off
	s_mov_b32 m0, s51
	v_lshl_add_u64 v[222:223], s[64:65], 0, v[132:133]
	global_load_lds_dwordx4 v[202:203], off
	s_mov_b32 m0, s38
	v_lshl_add_u64 v[202:203], s[68:69], 0, v[134:135]
	global_load_lds_dwordx4 v[202:203], off
	s_mov_b32 m0, s74
	v_lshl_add_u64 v[202:203], s[64:65], 0, v[128:129]
	global_load_lds_dwordx4 v[202:203], off
	s_mov_b32 m0, s55
	s_nop 0
	global_load_lds_dwordx4 v[222:223], off
	s_waitcnt vmcnt(8) lgkmcnt(0)
	s_setprio 1
	s_barrier
	v_mfma_f32_16x16x32_bf16 v[60:63], v[138:141], v[182:185], v[60:63]
	v_mfma_f32_16x16x32_bf16 v[56:59], v[154:157], v[182:185], v[56:59]
	v_mfma_f32_16x16x32_bf16 v[44:47], v[138:141], v[190:193], v[44:47]
	v_mfma_f32_16x16x32_bf16 v[40:43], v[154:157], v[190:193], v[40:43]
	v_mfma_f32_16x16x32_bf16 v[28:31], v[138:141], v[206:209], v[28:31]
	v_mfma_f32_16x16x32_bf16 v[24:27], v[154:157], v[206:209], v[24:27]
	v_mfma_f32_16x16x32_bf16 v[12:15], v[138:141], v[214:217], v[12:15]
	v_mfma_f32_16x16x32_bf16 v[8:11], v[154:157], v[214:217], v[8:11]
	v_mfma_f32_16x16x32_bf16 v[60:63], v[150:153], v[186:189], v[60:63]
	v_mfma_f32_16x16x32_bf16 v[56:59], v[158:161], v[186:189], v[56:59]
	v_mfma_f32_16x16x32_bf16 v[44:47], v[150:153], v[194:197], v[44:47]
	v_mfma_f32_16x16x32_bf16 v[40:43], v[158:161], v[194:197], v[40:43]
	v_mfma_f32_16x16x32_bf16 v[28:31], v[150:153], v[210:213], v[28:31]
	v_mfma_f32_16x16x32_bf16 v[24:27], v[158:161], v[210:213], v[24:27]
	v_mfma_f32_16x16x32_bf16 v[12:15], v[150:153], v[218:221], v[12:15]
	v_mfma_f32_16x16x32_bf16 v[8:11], v[158:161], v[218:221], v[8:11]
	v_mfma_f32_16x16x32_bf16 v[52:55], v[162:165], v[182:185], v[52:55]
	v_mfma_f32_16x16x32_bf16 v[48:51], v[170:173], v[182:185], v[48:51]
	v_mfma_f32_16x16x32_bf16 v[36:39], v[162:165], v[190:193], v[36:39]
	v_mfma_f32_16x16x32_bf16 v[32:35], v[170:173], v[190:193], v[32:35]
	v_mfma_f32_16x16x32_bf16 v[20:23], v[162:165], v[206:209], v[20:23]
	v_mfma_f32_16x16x32_bf16 v[16:19], v[170:173], v[206:209], v[16:19]
	v_mfma_f32_16x16x32_bf16 v[4:7], v[162:165], v[214:217], v[4:7]
	v_mfma_f32_16x16x32_bf16 v[0:3], v[170:173], v[214:217], v[0:3]
	v_mfma_f32_16x16x32_bf16 v[52:55], v[166:169], v[186:189], v[52:55]
	v_mfma_f32_16x16x32_bf16 v[48:51], v[178:181], v[186:189], v[48:51]
	v_mfma_f32_16x16x32_bf16 v[36:39], v[166:169], v[194:197], v[36:39]
	v_mfma_f32_16x16x32_bf16 v[32:35], v[178:181], v[194:197], v[32:35]
	v_mfma_f32_16x16x32_bf16 v[20:23], v[166:169], v[210:213], v[20:23]
	v_mfma_f32_16x16x32_bf16 v[16:19], v[178:181], v[210:213], v[16:19]
	v_mfma_f32_16x16x32_bf16 v[4:7], v[166:169], v[218:221], v[4:7]
	s_setprio 2
	s_barrier
	v_mfma_f32_16x16x32_bf16 v[0:3], v[178:181], v[218:221], v[0:3]
	s_setprio 0
	ds_read_b128 v[182:185], v147 offset:32768
	ds_read_b128 v[186:189], v147 offset:33792
	ds_read_b128 v[190:193], v147 offset:34816
	ds_read_b128 v[194:197], v147 offset:35840
	ds_read_b128 v[206:209], v147 offset:36864
	ds_read_b128 v[210:213], v147 offset:37888
	ds_read_b128 v[214:217], v147 offset:38912
	ds_read_b128 v[218:221], v147 offset:39936
	v_add_u32_e32 v137, s1, v144
	ds_read_b128 v[138:141], v137
	ds_read_b128 v[150:153], v137 offset:1024
	ds_read_b128 v[154:157], v137 offset:2048
	ds_read_b128 v[158:161], v137 offset:3072
	v_add_u32_e32 v137, s9, v144
	ds_read_b128 v[162:165], v137
	ds_read_b128 v[166:169], v137 offset:1024
	ds_read_b128 v[170:173], v137 offset:2048
	ds_read_b128 v[178:181], v137 offset:3072
	s_mov_b32 m0, s80
	v_lshl_add_u64 v[224:225], s[62:63], 0, v[128:129]
	global_load_lds_dwordx4 v[224:225], off
	s_mov_b32 m0, s81
	v_lshl_add_u64 v[224:225], s[62:63], 0, v[132:133]
	global_load_lds_dwordx4 v[224:225], off
	s_waitcnt vmcnt(8) lgkmcnt(0)
	s_setprio 1
	s_barrier
	v_mfma_f32_16x16x32_bf16 v[124:127], v[138:141], v[182:185], v[124:127]
	v_mfma_f32_16x16x32_bf16 v[120:123], v[154:157], v[182:185], v[120:123]
	v_mfma_f32_16x16x32_bf16 v[108:111], v[138:141], v[190:193], v[108:111]
	v_mfma_f32_16x16x32_bf16 v[104:107], v[154:157], v[190:193], v[104:107]
	v_mfma_f32_16x16x32_bf16 v[92:95], v[138:141], v[206:209], v[92:95]
	v_mfma_f32_16x16x32_bf16 v[88:91], v[154:157], v[206:209], v[88:91]
	v_mfma_f32_16x16x32_bf16 v[76:79], v[138:141], v[214:217], v[76:79]
	v_mfma_f32_16x16x32_bf16 v[72:75], v[154:157], v[214:217], v[72:75]
	v_mfma_f32_16x16x32_bf16 v[124:127], v[150:153], v[186:189], v[124:127]
	v_mfma_f32_16x16x32_bf16 v[120:123], v[158:161], v[186:189], v[120:123]
	v_mfma_f32_16x16x32_bf16 v[108:111], v[150:153], v[194:197], v[108:111]
	v_mfma_f32_16x16x32_bf16 v[104:107], v[158:161], v[194:197], v[104:107]
	v_mfma_f32_16x16x32_bf16 v[92:95], v[150:153], v[210:213], v[92:95]
	v_mfma_f32_16x16x32_bf16 v[88:91], v[158:161], v[210:213], v[88:91]
	v_mfma_f32_16x16x32_bf16 v[76:79], v[150:153], v[218:221], v[76:79]
	v_mfma_f32_16x16x32_bf16 v[72:75], v[158:161], v[218:221], v[72:75]
	v_mfma_f32_16x16x32_bf16 v[116:119], v[162:165], v[182:185], v[116:119]
	v_mfma_f32_16x16x32_bf16 v[112:115], v[170:173], v[182:185], v[112:115]
	v_mfma_f32_16x16x32_bf16 v[100:103], v[162:165], v[190:193], v[100:103]
	v_mfma_f32_16x16x32_bf16 v[96:99], v[170:173], v[190:193], v[96:99]
	v_mfma_f32_16x16x32_bf16 v[84:87], v[162:165], v[206:209], v[84:87]
	v_mfma_f32_16x16x32_bf16 v[80:83], v[170:173], v[206:209], v[80:83]
	v_mfma_f32_16x16x32_bf16 v[68:71], v[162:165], v[214:217], v[68:71]
	v_mfma_f32_16x16x32_bf16 v[64:67], v[170:173], v[214:217], v[64:67]
	v_mfma_f32_16x16x32_bf16 v[116:119], v[166:169], v[186:189], v[116:119]
	v_mfma_f32_16x16x32_bf16 v[112:115], v[178:181], v[186:189], v[112:115]
	v_mfma_f32_16x16x32_bf16 v[100:103], v[166:169], v[194:197], v[100:103]
	v_mfma_f32_16x16x32_bf16 v[96:99], v[178:181], v[194:197], v[96:99]
	v_mfma_f32_16x16x32_bf16 v[84:87], v[166:169], v[210:213], v[84:87]
	v_mfma_f32_16x16x32_bf16 v[80:83], v[178:181], v[210:213], v[80:83]
	v_mfma_f32_16x16x32_bf16 v[68:71], v[166:169], v[218:221], v[68:71]
	s_setprio 2
	s_barrier
	v_mfma_f32_16x16x32_bf16 v[64:67], v[178:181], v[218:221], v[64:67]
	s_setprio 0
	ds_read_b128 v[182:185], v147 offset:49152
	ds_read_b128 v[186:189], v147 offset:50176
	ds_read_b128 v[190:193], v147 offset:51200
	ds_read_b128 v[194:197], v147 offset:52224
	ds_read_b128 v[206:209], v147 offset:53248
	ds_read_b128 v[210:213], v147 offset:54272
	ds_read_b128 v[214:217], v147 offset:55296
	ds_read_b128 v[218:221], v147 offset:56320
	s_mov_b32 m0, s3
	v_lshl_add_u64 v[174:175], v[174:175], 0, s[16:17]
	global_load_lds_dwordx4 v[174:175], off
	s_mov_b32 m0, s76
	v_lshl_add_u64 v[174:175], v[198:199], 0, s[16:17]
	global_load_lds_dwordx4 v[174:175], off
	s_mov_b32 m0, s2
	v_lshl_add_u64 v[174:175], s[60:61], 0, v[130:131]
	global_load_lds_dwordx4 v[174:175], off
	s_mov_b32 m0, s0
	v_lshl_add_u64 v[174:175], s[60:61], 0, v[134:135]
	global_load_lds_dwordx4 v[174:175], off
	s_mov_b32 m0, s85
	v_lshl_add_u64 v[174:175], v[202:203], 0, s[16:17]
	global_load_lds_dwordx4 v[174:175], off
	s_mov_b32 m0, s86
	v_lshl_add_u64 v[174:175], v[222:223], 0, s[16:17]
	global_load_lds_dwordx4 v[174:175], off
	s_waitcnt vmcnt(8) lgkmcnt(0)
	s_setprio 1
	s_barrier
	v_mfma_f32_16x16x32_bf16 v[60:63], v[138:141], v[182:185], v[60:63]
	v_mfma_f32_16x16x32_bf16 v[56:59], v[154:157], v[182:185], v[56:59]
	v_mfma_f32_16x16x32_bf16 v[44:47], v[138:141], v[190:193], v[44:47]
	v_mfma_f32_16x16x32_bf16 v[40:43], v[154:157], v[190:193], v[40:43]
	v_mfma_f32_16x16x32_bf16 v[28:31], v[138:141], v[206:209], v[28:31]
	v_mfma_f32_16x16x32_bf16 v[24:27], v[154:157], v[206:209], v[24:27]
	v_mfma_f32_16x16x32_bf16 v[12:15], v[138:141], v[214:217], v[12:15]
	v_mfma_f32_16x16x32_bf16 v[8:11], v[154:157], v[214:217], v[8:11]
	v_mfma_f32_16x16x32_bf16 v[60:63], v[150:153], v[186:189], v[60:63]
	v_mfma_f32_16x16x32_bf16 v[56:59], v[158:161], v[186:189], v[56:59]
	v_mfma_f32_16x16x32_bf16 v[44:47], v[150:153], v[194:197], v[44:47]
	v_mfma_f32_16x16x32_bf16 v[40:43], v[158:161], v[194:197], v[40:43]
	v_mfma_f32_16x16x32_bf16 v[28:31], v[150:153], v[210:213], v[28:31]
	v_mfma_f32_16x16x32_bf16 v[24:27], v[158:161], v[210:213], v[24:27]
	v_mfma_f32_16x16x32_bf16 v[12:15], v[150:153], v[218:221], v[12:15]
	v_mfma_f32_16x16x32_bf16 v[8:11], v[158:161], v[218:221], v[8:11]
	v_mfma_f32_16x16x32_bf16 v[52:55], v[162:165], v[182:185], v[52:55]
	v_mfma_f32_16x16x32_bf16 v[48:51], v[170:173], v[182:185], v[48:51]
	v_mfma_f32_16x16x32_bf16 v[36:39], v[162:165], v[190:193], v[36:39]
	v_mfma_f32_16x16x32_bf16 v[32:35], v[170:173], v[190:193], v[32:35]
	v_mfma_f32_16x16x32_bf16 v[20:23], v[162:165], v[206:209], v[20:23]
	v_mfma_f32_16x16x32_bf16 v[16:19], v[170:173], v[206:209], v[16:19]
	v_mfma_f32_16x16x32_bf16 v[4:7], v[162:165], v[214:217], v[4:7]
	v_mfma_f32_16x16x32_bf16 v[0:3], v[170:173], v[214:217], v[0:3]
	v_mfma_f32_16x16x32_bf16 v[52:55], v[166:169], v[186:189], v[52:55]
	v_mfma_f32_16x16x32_bf16 v[48:51], v[178:181], v[186:189], v[48:51]
	v_mfma_f32_16x16x32_bf16 v[36:39], v[166:169], v[194:197], v[36:39]
	v_mfma_f32_16x16x32_bf16 v[32:35], v[178:181], v[194:197], v[32:35]
	v_mfma_f32_16x16x32_bf16 v[20:23], v[166:169], v[210:213], v[20:23]
	v_mfma_f32_16x16x32_bf16 v[16:19], v[178:181], v[210:213], v[16:19]
	v_mfma_f32_16x16x32_bf16 v[4:7], v[166:169], v[218:221], v[4:7]
	s_setprio 2
	s_barrier
	v_mfma_f32_16x16x32_bf16 v[0:3], v[178:181], v[218:221], v[0:3]
	s_setprio 0
	s_mov_b64 s[64:65], 0
	s_mov_b64 s[60:61], -1
	s_mov_b64 s[62:63], 0x100
	s_cbranch_vccz .LBB0_828
	s_and_b64 vcc, exec, s[18:19]
	s_cbranch_vccz .LBB0_831
	s_barrier

.LBB0_849:
	ds_read_b128 v[138:141], v147
	ds_read_b128 v[152:155], v147 offset:1024
	ds_read_b128 v[156:159], v147 offset:2048
	ds_read_b128 v[160:163], v147 offset:3072
	ds_read_b128 v[164:167], v148
	ds_read_b128 v[168:171], v148 offset:1024
	ds_read_b128 v[172:175], v148 offset:2048
	ds_read_b128 v[178:181], v148 offset:3072
	ds_read_b128 v[182:185], v149
	ds_read_b128 v[186:189], v149 offset:1024
	ds_read_b128 v[190:193], v149 offset:2048
	ds_read_b128 v[194:197], v149 offset:3072
	ds_read_b128 v[206:209], v149 offset:4096
	ds_read_b128 v[210:213], v149 offset:5120
	ds_read_b128 v[214:217], v149 offset:6144
	ds_read_b128 v[218:221], v149 offset:7168
	s_add_u32 s2, s30, s52
	s_addc_u32 s3, s31, s53
	s_add_u32 s9, s2, 0x100
	s_addc_u32 s38, s3, 0
	s_and_b64 s[0:1], s[34:35], exec
	v_cndmask_b32_e64 v137, 0, 1, s[54:55]
	s_cselect_b32 s55, s27, s38
	s_cselect_b32 s54, s89, s9
	s_add_u32 s0, s28, s52
	s_addc_u32 s1, s29, s53
	s_add_u32 s9, s0, 0x100
	s_addc_u32 s38, s1, 0
	s_and_b64 s[0:1], s[34:35], exec
	s_cselect_b32 s57, s90, s38
	s_cselect_b32 s56, s8, s9
	s_add_u32 s60, s2, 0x80080
	s_addc_u32 s61, s3, 0
	s_add_i32 s39, s79, s36
	s_add_i32 m0, s63, 0xc000
	s_add_i32 s74, s63, 0xe000
	s_add_i32 s50, s39, 0x2000
	s_add_u32 s58, s56, 0x80000
	s_addc_u32 s59, s57, 0
	s_add_i32 s38, s80, s36
	s_add_i32 s51, s38, 0x2000
	s_add_i32 s76, 0, 0x18000
	s_add_i32 s0, 0, 0x1c000
	s_add_u32 s52, s54, 0x80000
	s_addc_u32 s53, s55, 0
	s_add_i32 s3, s76, s36
	s_add_i32 s1, s3, 0x2000
	s_add_u32 s34, s56, 0x80080
	s_addc_u32 s35, s57, 0
	s_add_i32 s2, s0, s36
	s_add_i32 s9, s2, 0x2000
	v_cmp_ne_u32_e32 vcc, 1, v137
	v_lshl_add_u64 v[142:143], s[60:61], 0, v[134:135]
	global_load_lds_dwordx4 v[142:143], off
	s_mov_b32 m0, s74
	v_lshl_add_u64 v[142:143], s[60:61], 0, v[130:131]
	global_load_lds_dwordx4 v[142:143], off
	s_waitcnt vmcnt(8) lgkmcnt(0)
	s_setprio 1
	s_barrier
	v_mfma_f32_16x16x32_bf16 v[124:127], v[138:141], v[182:185], v[124:127]
	v_mfma_f32_16x16x32_bf16 v[120:123], v[156:159], v[182:185], v[120:123]
	v_mfma_f32_16x16x32_bf16 v[108:111], v[138:141], v[190:193], v[108:111]
	v_mfma_f32_16x16x32_bf16 v[104:107], v[156:159], v[190:193], v[104:107]
	v_mfma_f32_16x16x32_bf16 v[92:95], v[138:141], v[206:209], v[92:95]
	v_mfma_f32_16x16x32_bf16 v[88:91], v[156:159], v[206:209], v[88:91]
	v_mfma_f32_16x16x32_bf16 v[76:79], v[138:141], v[214:217], v[76:79]
	v_mfma_f32_16x16x32_bf16 v[72:75], v[156:159], v[214:217], v[72:75]
	v_mfma_f32_16x16x32_bf16 v[124:127], v[152:155], v[186:189], v[124:127]
	v_mfma_f32_16x16x32_bf16 v[120:123], v[160:163], v[186:189], v[120:123]
	v_mfma_f32_16x16x32_bf16 v[108:111], v[152:155], v[194:197], v[108:111]
	v_mfma_f32_16x16x32_bf16 v[104:107], v[160:163], v[194:197], v[104:107]
	v_mfma_f32_16x16x32_bf16 v[92:95], v[152:155], v[210:213], v[92:95]
	v_mfma_f32_16x16x32_bf16 v[88:91], v[160:163], v[210:213], v[88:91]
	v_mfma_f32_16x16x32_bf16 v[76:79], v[152:155], v[218:221], v[76:79]
	v_mfma_f32_16x16x32_bf16 v[72:75], v[160:163], v[218:221], v[72:75]
	v_mfma_f32_16x16x32_bf16 v[116:119], v[164:167], v[182:185], v[116:119]
	v_mfma_f32_16x16x32_bf16 v[112:115], v[172:175], v[182:185], v[112:115]
	v_mfma_f32_16x16x32_bf16 v[100:103], v[164:167], v[190:193], v[100:103]
	v_mfma_f32_16x16x32_bf16 v[96:99], v[172:175], v[190:193], v[96:99]
	v_mfma_f32_16x16x32_bf16 v[84:87], v[164:167], v[206:209], v[84:87]
	v_mfma_f32_16x16x32_bf16 v[80:83], v[172:175], v[206:209], v[80:83]
	v_mfma_f32_16x16x32_bf16 v[68:71], v[164:167], v[214:217], v[68:71]
	v_mfma_f32_16x16x32_bf16 v[64:67], v[172:175], v[214:217], v[64:67]
	v_mfma_f32_16x16x32_bf16 v[116:119], v[168:171], v[186:189], v[116:119]
	v_mfma_f32_16x16x32_bf16 v[112:115], v[178:181], v[186:189], v[112:115]
	v_mfma_f32_16x16x32_bf16 v[100:103], v[168:171], v[194:197], v[100:103]
	v_mfma_f32_16x16x32_bf16 v[96:99], v[178:181], v[194:197], v[96:99]
	v_mfma_f32_16x16x32_bf16 v[84:87], v[168:171], v[210:213], v[84:87]
	v_mfma_f32_16x16x32_bf16 v[80:83], v[178:181], v[210:213], v[80:83]
	v_mfma_f32_16x16x32_bf16 v[68:71], v[168:171], v[218:221], v[68:71]
	s_setprio 2
	s_barrier
	v_mfma_f32_16x16x32_bf16 v[64:67], v[178:181], v[218:221], v[64:67]
	s_setprio 0
	ds_read_b128 v[182:185], v149 offset:16384
	ds_read_b128 v[186:189], v149 offset:17408
	ds_read_b128 v[190:193], v149 offset:18432
	ds_read_b128 v[194:197], v149 offset:19456
	ds_read_b128 v[206:209], v149 offset:20480
	ds_read_b128 v[210:213], v149 offset:21504
	ds_read_b128 v[214:217], v149 offset:22528
	ds_read_b128 v[218:221], v149 offset:23552
	s_mov_b32 m0, s39
	v_lshl_add_u64 v[142:143], s[56:57], 0, v[132:133]
	global_load_lds_dwordx4 v[142:143], off
	v_lshl_add_u64 v[198:199], s[56:57], 0, v[128:129]
	s_mov_b32 m0, s50
	v_lshl_add_u64 v[202:203], s[58:59], 0, v[132:133]
	global_load_lds_dwordx4 v[198:199], off
	s_mov_b32 m0, s38
	v_lshl_add_u64 v[222:223], s[54:55], 0, v[130:131]
	global_load_lds_dwordx4 v[202:203], off
	s_mov_b32 m0, s51
	v_lshl_add_u64 v[202:203], s[58:59], 0, v[128:129]
	global_load_lds_dwordx4 v[202:203], off
	s_mov_b32 m0, s63
	v_lshl_add_u64 v[202:203], s[54:55], 0, v[134:135]
	global_load_lds_dwordx4 v[202:203], off
	s_mov_b32 m0, s64
	s_nop 0
	global_load_lds_dwordx4 v[222:223], off
	s_waitcnt vmcnt(8) lgkmcnt(0)
	s_setprio 1
	s_barrier
	v_mfma_f32_16x16x32_bf16 v[60:63], v[138:141], v[182:185], v[60:63]
	v_mfma_f32_16x16x32_bf16 v[56:59], v[156:159], v[182:185], v[56:59]
	v_mfma_f32_16x16x32_bf16 v[44:47], v[138:141], v[190:193], v[44:47]
	v_mfma_f32_16x16x32_bf16 v[40:43], v[156:159], v[190:193], v[40:43]
	v_mfma_f32_16x16x32_bf16 v[28:31], v[138:141], v[206:209], v[28:31]
	v_mfma_f32_16x16x32_bf16 v[24:27], v[156:159], v[206:209], v[24:27]
	v_mfma_f32_16x16x32_bf16 v[12:15], v[138:141], v[214:217], v[12:15]
	v_mfma_f32_16x16x32_bf16 v[8:11], v[156:159], v[214:217], v[8:11]
	v_mfma_f32_16x16x32_bf16 v[60:63], v[152:155], v[186:189], v[60:63]
	v_mfma_f32_16x16x32_bf16 v[56:59], v[160:163], v[186:189], v[56:59]
	v_mfma_f32_16x16x32_bf16 v[44:47], v[152:155], v[194:197], v[44:47]
	v_mfma_f32_16x16x32_bf16 v[40:43], v[160:163], v[194:197], v[40:43]
	v_mfma_f32_16x16x32_bf16 v[28:31], v[152:155], v[210:213], v[28:31]
	v_mfma_f32_16x16x32_bf16 v[24:27], v[160:163], v[210:213], v[24:27]
	v_mfma_f32_16x16x32_bf16 v[12:15], v[152:155], v[218:221], v[12:15]
	v_mfma_f32_16x16x32_bf16 v[8:11], v[160:163], v[218:221], v[8:11]
	v_mfma_f32_16x16x32_bf16 v[52:55], v[164:167], v[182:185], v[52:55]
	v_mfma_f32_16x16x32_bf16 v[48:51], v[172:175], v[182:185], v[48:51]
	v_mfma_f32_16x16x32_bf16 v[36:39], v[164:167], v[190:193], v[36:39]
	v_mfma_f32_16x16x32_bf16 v[32:35], v[172:175], v[190:193], v[32:35]
	v_mfma_f32_16x16x32_bf16 v[20:23], v[164:167], v[206:209], v[20:23]
	v_mfma_f32_16x16x32_bf16 v[16:19], v[172:175], v[206:209], v[16:19]
	v_mfma_f32_16x16x32_bf16 v[4:7], v[164:167], v[214:217], v[4:7]
	v_mfma_f32_16x16x32_bf16 v[0:3], v[172:175], v[214:217], v[0:3]
	v_mfma_f32_16x16x32_bf16 v[52:55], v[168:171], v[186:189], v[52:55]
	v_mfma_f32_16x16x32_bf16 v[48:51], v[178:181], v[186:189], v[48:51]
	v_mfma_f32_16x16x32_bf16 v[36:39], v[168:171], v[194:197], v[36:39]
	v_mfma_f32_16x16x32_bf16 v[32:35], v[178:181], v[194:197], v[32:35]
	v_mfma_f32_16x16x32_bf16 v[20:23], v[168:171], v[210:213], v[20:23]
	v_mfma_f32_16x16x32_bf16 v[16:19], v[178:181], v[210:213], v[16:19]
	v_mfma_f32_16x16x32_bf16 v[4:7], v[168:171], v[218:221], v[4:7]
	s_setprio 2
	s_barrier
	v_mfma_f32_16x16x32_bf16 v[0:3], v[178:181], v[218:221], v[0:3]
	s_setprio 0
	ds_read_b128 v[182:185], v149 offset:32768
	ds_read_b128 v[186:189], v149 offset:33792
	ds_read_b128 v[190:193], v149 offset:34816
	ds_read_b128 v[194:197], v149 offset:35840
	ds_read_b128 v[206:209], v149 offset:36864
	ds_read_b128 v[210:213], v149 offset:37888
	ds_read_b128 v[214:217], v149 offset:38912
	ds_read_b128 v[218:221], v149 offset:39936
	v_add_u32_e32 v137, s76, v146
	ds_read_b128 v[138:141], v137
	ds_read_b128 v[152:155], v137 offset:1024
	ds_read_b128 v[156:159], v137 offset:2048
	ds_read_b128 v[160:163], v137 offset:3072
	v_add_u32_e32 v137, s0, v146
	ds_read_b128 v[164:167], v137
	ds_read_b128 v[168:171], v137 offset:1024
	ds_read_b128 v[172:175], v137 offset:2048
	ds_read_b128 v[178:181], v137 offset:3072
	s_mov_b32 m0, s65
	v_lshl_add_u64 v[224:225], s[52:53], 0, v[134:135]
	global_load_lds_dwordx4 v[224:225], off
	s_mov_b32 m0, s66
	v_lshl_add_u64 v[224:225], s[52:53], 0, v[130:131]
	global_load_lds_dwordx4 v[224:225], off
	s_waitcnt vmcnt(8) lgkmcnt(0)
	s_setprio 1
	s_barrier
	v_mfma_f32_16x16x32_bf16 v[124:127], v[138:141], v[182:185], v[124:127]
	v_mfma_f32_16x16x32_bf16 v[120:123], v[156:159], v[182:185], v[120:123]
	v_mfma_f32_16x16x32_bf16 v[108:111], v[138:141], v[190:193], v[108:111]
	v_mfma_f32_16x16x32_bf16 v[104:107], v[156:159], v[190:193], v[104:107]
	v_mfma_f32_16x16x32_bf16 v[92:95], v[138:141], v[206:209], v[92:95]
	v_mfma_f32_16x16x32_bf16 v[88:91], v[156:159], v[206:209], v[88:91]
	v_mfma_f32_16x16x32_bf16 v[76:79], v[138:141], v[214:217], v[76:79]
	v_mfma_f32_16x16x32_bf16 v[72:75], v[156:159], v[214:217], v[72:75]
	v_mfma_f32_16x16x32_bf16 v[124:127], v[152:155], v[186:189], v[124:127]
	v_mfma_f32_16x16x32_bf16 v[120:123], v[160:163], v[186:189], v[120:123]
	v_mfma_f32_16x16x32_bf16 v[108:111], v[152:155], v[194:197], v[108:111]
	v_mfma_f32_16x16x32_bf16 v[104:107], v[160:163], v[194:197], v[104:107]
	v_mfma_f32_16x16x32_bf16 v[92:95], v[152:155], v[210:213], v[92:95]
	v_mfma_f32_16x16x32_bf16 v[88:91], v[160:163], v[210:213], v[88:91]
	v_mfma_f32_16x16x32_bf16 v[76:79], v[152:155], v[218:221], v[76:79]
	v_mfma_f32_16x16x32_bf16 v[72:75], v[160:163], v[218:221], v[72:75]
	v_mfma_f32_16x16x32_bf16 v[116:119], v[164:167], v[182:185], v[116:119]
	v_mfma_f32_16x16x32_bf16 v[112:115], v[172:175], v[182:185], v[112:115]
	v_mfma_f32_16x16x32_bf16 v[100:103], v[164:167], v[190:193], v[100:103]
	v_mfma_f32_16x16x32_bf16 v[96:99], v[172:175], v[190:193], v[96:99]
	v_mfma_f32_16x16x32_bf16 v[84:87], v[164:167], v[206:209], v[84:87]
	v_mfma_f32_16x16x32_bf16 v[80:83], v[172:175], v[206:209], v[80:83]
	v_mfma_f32_16x16x32_bf16 v[68:71], v[164:167], v[214:217], v[68:71]
	v_mfma_f32_16x16x32_bf16 v[64:67], v[172:175], v[214:217], v[64:67]
	v_mfma_f32_16x16x32_bf16 v[116:119], v[168:171], v[186:189], v[116:119]
	v_mfma_f32_16x16x32_bf16 v[112:115], v[178:181], v[186:189], v[112:115]
	v_mfma_f32_16x16x32_bf16 v[100:103], v[168:171], v[194:197], v[100:103]
	v_mfma_f32_16x16x32_bf16 v[96:99], v[178:181], v[194:197], v[96:99]
	v_mfma_f32_16x16x32_bf16 v[84:87], v[168:171], v[210:213], v[84:87]
	v_mfma_f32_16x16x32_bf16 v[80:83], v[178:181], v[210:213], v[80:83]
	v_mfma_f32_16x16x32_bf16 v[68:71], v[168:171], v[218:221], v[68:71]
	s_setprio 2
	s_barrier
	v_mfma_f32_16x16x32_bf16 v[64:67], v[178:181], v[218:221], v[64:67]
	s_setprio 0
	ds_read_b128 v[182:185], v149 offset:49152
	ds_read_b128 v[186:189], v149 offset:50176
	ds_read_b128 v[190:193], v149 offset:51200
	ds_read_b128 v[194:197], v149 offset:52224
	ds_read_b128 v[206:209], v149 offset:53248
	ds_read_b128 v[210:213], v149 offset:54272
	ds_read_b128 v[214:217], v149 offset:55296
	ds_read_b128 v[218:221], v149 offset:56320
	s_mov_b32 m0, s3
	v_lshl_add_u64 v[142:143], v[142:143], 0, s[14:15]
	global_load_lds_dwordx4 v[142:143], off
	s_mov_b32 m0, s1
	v_lshl_add_u64 v[142:143], v[198:199], 0, s[14:15]
	global_load_lds_dwordx4 v[142:143], off
	s_mov_b32 m0, s2
	v_lshl_add_u64 v[142:143], s[34:35], 0, v[132:133]
	global_load_lds_dwordx4 v[142:143], off
	s_mov_b32 m0, s9
	v_lshl_add_u64 v[142:143], s[34:35], 0, v[128:129]
	global_load_lds_dwordx4 v[142:143], off
	s_mov_b32 m0, s77
	v_lshl_add_u64 v[142:143], v[202:203], 0, s[14:15]
	global_load_lds_dwordx4 v[142:143], off
	s_mov_b32 m0, s78
	v_lshl_add_u64 v[142:143], v[222:223], 0, s[14:15]
	global_load_lds_dwordx4 v[142:143], off
	s_waitcnt vmcnt(8) lgkmcnt(0)
	s_setprio 1
	s_barrier
	v_mfma_f32_16x16x32_bf16 v[60:63], v[138:141], v[182:185], v[60:63]
	v_mfma_f32_16x16x32_bf16 v[56:59], v[156:159], v[182:185], v[56:59]
	v_mfma_f32_16x16x32_bf16 v[44:47], v[138:141], v[190:193], v[44:47]
	v_mfma_f32_16x16x32_bf16 v[40:43], v[156:159], v[190:193], v[40:43]
	v_mfma_f32_16x16x32_bf16 v[28:31], v[138:141], v[206:209], v[28:31]
	v_mfma_f32_16x16x32_bf16 v[24:27], v[156:159], v[206:209], v[24:27]
	v_mfma_f32_16x16x32_bf16 v[12:15], v[138:141], v[214:217], v[12:15]
	v_mfma_f32_16x16x32_bf16 v[8:11], v[156:159], v[214:217], v[8:11]
	v_mfma_f32_16x16x32_bf16 v[60:63], v[152:155], v[186:189], v[60:63]
	v_mfma_f32_16x16x32_bf16 v[56:59], v[160:163], v[186:189], v[56:59]
	v_mfma_f32_16x16x32_bf16 v[44:47], v[152:155], v[194:197], v[44:47]
	v_mfma_f32_16x16x32_bf16 v[40:43], v[160:163], v[194:197], v[40:43]
	v_mfma_f32_16x16x32_bf16 v[28:31], v[152:155], v[210:213], v[28:31]
	v_mfma_f32_16x16x32_bf16 v[24:27], v[160:163], v[210:213], v[24:27]
	v_mfma_f32_16x16x32_bf16 v[12:15], v[152:155], v[218:221], v[12:15]
	v_mfma_f32_16x16x32_bf16 v[8:11], v[160:163], v[218:221], v[8:11]
	v_mfma_f32_16x16x32_bf16 v[52:55], v[164:167], v[182:185], v[52:55]
	v_mfma_f32_16x16x32_bf16 v[48:51], v[172:175], v[182:185], v[48:51]
	v_mfma_f32_16x16x32_bf16 v[36:39], v[164:167], v[190:193], v[36:39]
	v_mfma_f32_16x16x32_bf16 v[32:35], v[172:175], v[190:193], v[32:35]
	v_mfma_f32_16x16x32_bf16 v[20:23], v[164:167], v[206:209], v[20:23]
	v_mfma_f32_16x16x32_bf16 v[16:19], v[172:175], v[206:209], v[16:19]
	v_mfma_f32_16x16x32_bf16 v[4:7], v[164:167], v[214:217], v[4:7]
	v_mfma_f32_16x16x32_bf16 v[0:3], v[172:175], v[214:217], v[0:3]
	v_mfma_f32_16x16x32_bf16 v[52:55], v[168:171], v[186:189], v[52:55]
	v_mfma_f32_16x16x32_bf16 v[48:51], v[178:181], v[186:189], v[48:51]
	v_mfma_f32_16x16x32_bf16 v[36:39], v[168:171], v[194:197], v[36:39]
	v_mfma_f32_16x16x32_bf16 v[32:35], v[178:181], v[194:197], v[32:35]
	v_mfma_f32_16x16x32_bf16 v[20:23], v[168:171], v[210:213], v[20:23]
	v_mfma_f32_16x16x32_bf16 v[16:19], v[178:181], v[210:213], v[16:19]
	v_mfma_f32_16x16x32_bf16 v[4:7], v[168:171], v[218:221], v[4:7]
	s_setprio 2
	s_barrier
	v_mfma_f32_16x16x32_bf16 v[0:3], v[178:181], v[218:221], v[0:3]
	s_setprio 0
	s_mov_b64 s[54:55], 0
	s_mov_b64 s[34:35], -1
	s_mov_b64 s[52:53], 0x100
	s_cbranch_vccz .LBB0_849
	s_and_b64 vcc, exec, s[16:17]
	s_cbranch_vccz .LBB0_852
	s_barrier

.LBB0_877:
	ds_read_b128 v[142:145], v135 offset:1024
	ds_read_b128 v[146:149], v135 offset:2048
	ds_read_b128 v[150:153], v135 offset:3072
	ds_read_b128 v[154:157], v136
	ds_read_b128 v[158:161], v136 offset:1024
	ds_read_b128 v[162:165], v136 offset:2048
	ds_read_b128 v[166:169], v136 offset:3072
	ds_read_b128 v[170:173], v137
	ds_read_b128 v[178:181], v137 offset:1024
	ds_read_b128 v[182:185], v137 offset:2048
	ds_read_b128 v[186:189], v137 offset:3072
	ds_read_b128 v[190:193], v137 offset:4096
	ds_read_b128 v[194:197], v137 offset:5120
	ds_read_b128 v[206:209], v137 offset:6144
	ds_read_b128 v[210:213], v137 offset:7168
	s_add_u32 s2, s54, s64
	s_addc_u32 s3, s55, s65
	s_add_u32 s8, s2, 0x100
	s_addc_u32 s9, s3, 0
	s_and_b64 s[0:1], s[62:63], exec
	v_cndmask_b32_e64 v138, 0, 1, s[66:67]
	s_cselect_b32 s67, s21, s9
	s_cselect_b32 s66, s23, s8
	s_add_u32 s0, s30, s64
	s_addc_u32 s1, s31, s65
	s_add_u32 s8, s0, 0x100
	s_addc_u32 s9, s1, 0
	s_and_b64 s[0:1], s[62:63], exec
	s_cselect_b32 s69, s95, s9
	s_cselect_b32 s68, s96, s8
	s_add_u32 s72, s2, 0x10080
	v_cmp_ne_u32_e32 vcc, 1, v138
	ds_read_b128 v[138:141], v135
	s_addc_u32 s73, s3, 0
	s_add_i32 s19, s91, s77
	s_add_i32 m0, s80, 0xc000
	s_add_i32 s38, s80, 0xe000
	s_add_i32 s0, s19, 0x2000
	s_add_u32 s70, s68, 0x10000
	s_addc_u32 s71, s69, 0
	s_add_i32 s76, s92, s77
	s_add_i32 s18, s76, 0x2000
	s_add_i32 s3, 0, 0x18000
	s_add_i32 s2, 0, 0x1c000
	s_add_u32 s64, s66, 0x10000
	s_addc_u32 s65, s67, 0
	s_add_i32 s1, s3, s77
	s_add_i32 s9, s1, 0x2000
	s_add_u32 s62, s68, 0x10080
	s_addc_u32 s63, s69, 0
	s_add_i32 s97, s2, s77
	s_add_i32 s8, s97, 0x2000
	v_lshl_add_u64 v[174:175], s[72:73], 0, v[128:129]
	global_load_lds_dwordx4 v[174:175], off
	s_mov_b32 m0, s38
	v_lshl_add_u64 v[174:175], s[72:73], 0, v[130:131]
	global_load_lds_dwordx4 v[174:175], off
	s_waitcnt vmcnt(8) lgkmcnt(0)
	s_setprio 1
	s_barrier
	v_mfma_f32_16x16x32_bf16 v[124:127], v[138:141], v[170:173], v[124:127]
	v_mfma_f32_16x16x32_bf16 v[120:123], v[146:149], v[170:173], v[120:123]
	v_mfma_f32_16x16x32_bf16 v[116:119], v[138:141], v[182:185], v[116:119]
	v_mfma_f32_16x16x32_bf16 v[112:115], v[146:149], v[182:185], v[112:115]
	v_mfma_f32_16x16x32_bf16 v[104:107], v[138:141], v[190:193], v[104:107]
	v_mfma_f32_16x16x32_bf16 v[96:99], v[146:149], v[190:193], v[96:99]
	v_mfma_f32_16x16x32_bf16 v[88:91], v[138:141], v[206:209], v[88:91]
	v_mfma_f32_16x16x32_bf16 v[80:83], v[146:149], v[206:209], v[80:83]
	v_mfma_f32_16x16x32_bf16 v[124:127], v[142:145], v[178:181], v[124:127]
	v_mfma_f32_16x16x32_bf16 v[120:123], v[150:153], v[178:181], v[120:123]
	v_mfma_f32_16x16x32_bf16 v[116:119], v[142:145], v[186:189], v[116:119]
	v_mfma_f32_16x16x32_bf16 v[112:115], v[150:153], v[186:189], v[112:115]
	v_mfma_f32_16x16x32_bf16 v[104:107], v[142:145], v[194:197], v[104:107]
	v_mfma_f32_16x16x32_bf16 v[96:99], v[150:153], v[194:197], v[96:99]
	v_mfma_f32_16x16x32_bf16 v[88:91], v[142:145], v[210:213], v[88:91]
	v_mfma_f32_16x16x32_bf16 v[80:83], v[150:153], v[210:213], v[80:83]
	v_mfma_f32_16x16x32_bf16 v[108:111], v[154:157], v[170:173], v[108:111]
	v_mfma_f32_16x16x32_bf16 v[100:103], v[162:165], v[170:173], v[100:103]
	v_mfma_f32_16x16x32_bf16 v[92:95], v[154:157], v[182:185], v[92:95]
	v_mfma_f32_16x16x32_bf16 v[84:87], v[162:165], v[182:185], v[84:87]
	v_mfma_f32_16x16x32_bf16 v[76:79], v[154:157], v[190:193], v[76:79]
	v_mfma_f32_16x16x32_bf16 v[72:75], v[162:165], v[190:193], v[72:75]
	v_mfma_f32_16x16x32_bf16 v[68:71], v[154:157], v[206:209], v[68:71]
	v_mfma_f32_16x16x32_bf16 v[64:67], v[162:165], v[206:209], v[64:67]
	v_mfma_f32_16x16x32_bf16 v[108:111], v[158:161], v[178:181], v[108:111]
	v_mfma_f32_16x16x32_bf16 v[100:103], v[166:169], v[178:181], v[100:103]
	v_mfma_f32_16x16x32_bf16 v[92:95], v[158:161], v[186:189], v[92:95]
	v_mfma_f32_16x16x32_bf16 v[84:87], v[166:169], v[186:189], v[84:87]
	v_mfma_f32_16x16x32_bf16 v[76:79], v[158:161], v[194:197], v[76:79]
	v_mfma_f32_16x16x32_bf16 v[72:75], v[166:169], v[194:197], v[72:75]
	v_mfma_f32_16x16x32_bf16 v[68:71], v[158:161], v[210:213], v[68:71]
	s_setprio 2
	s_barrier
	v_mfma_f32_16x16x32_bf16 v[64:67], v[166:169], v[210:213], v[64:67]
	s_setprio 0
	ds_read_b128 v[170:173], v137 offset:16384
	ds_read_b128 v[178:181], v137 offset:17408
	ds_read_b128 v[182:185], v137 offset:18432
	ds_read_b128 v[186:189], v137 offset:19456
	ds_read_b128 v[190:193], v137 offset:20480
	ds_read_b128 v[194:197], v137 offset:21504
	ds_read_b128 v[206:209], v137 offset:22528
	ds_read_b128 v[210:213], v137 offset:23552
	s_mov_b32 m0, s19
	v_lshl_add_u64 v[174:175], s[68:69], 0, v[128:129]
	global_load_lds_dwordx4 v[174:175], off
	v_lshl_add_u64 v[198:199], s[68:69], 0, v[130:131]
	s_mov_b32 m0, s0
	v_lshl_add_u64 v[202:203], s[70:71], 0, v[128:129]
	global_load_lds_dwordx4 v[198:199], off
	s_mov_b32 m0, s76
	v_lshl_add_u64 v[214:215], s[66:67], 0, v[130:131]
	global_load_lds_dwordx4 v[202:203], off
	s_mov_b32 m0, s18
	v_lshl_add_u64 v[202:203], s[70:71], 0, v[130:131]
	global_load_lds_dwordx4 v[202:203], off
	s_mov_b32 m0, s80
	v_lshl_add_u64 v[202:203], s[66:67], 0, v[128:129]
	global_load_lds_dwordx4 v[202:203], off
	s_mov_b32 m0, s81
	s_nop 0
	global_load_lds_dwordx4 v[214:215], off
	s_waitcnt vmcnt(8) lgkmcnt(0)
	s_setprio 1
	s_barrier
	v_mfma_f32_16x16x32_bf16 v[60:63], v[138:141], v[170:173], v[60:63]
	v_mfma_f32_16x16x32_bf16 v[56:59], v[146:149], v[170:173], v[56:59]
	v_mfma_f32_16x16x32_bf16 v[52:55], v[138:141], v[182:185], v[52:55]
	v_mfma_f32_16x16x32_bf16 v[48:51], v[146:149], v[182:185], v[48:51]
	v_mfma_f32_16x16x32_bf16 v[40:43], v[138:141], v[190:193], v[40:43]
	v_mfma_f32_16x16x32_bf16 v[32:35], v[146:149], v[190:193], v[32:35]
	v_mfma_f32_16x16x32_bf16 v[24:27], v[138:141], v[206:209], v[24:27]
	v_mfma_f32_16x16x32_bf16 v[16:19], v[146:149], v[206:209], v[16:19]
	v_mfma_f32_16x16x32_bf16 v[60:63], v[142:145], v[178:181], v[60:63]
	v_mfma_f32_16x16x32_bf16 v[56:59], v[150:153], v[178:181], v[56:59]
	v_mfma_f32_16x16x32_bf16 v[52:55], v[142:145], v[186:189], v[52:55]
	v_mfma_f32_16x16x32_bf16 v[48:51], v[150:153], v[186:189], v[48:51]
	v_mfma_f32_16x16x32_bf16 v[40:43], v[142:145], v[194:197], v[40:43]
	v_mfma_f32_16x16x32_bf16 v[32:35], v[150:153], v[194:197], v[32:35]
	v_mfma_f32_16x16x32_bf16 v[24:27], v[142:145], v[210:213], v[24:27]
	v_mfma_f32_16x16x32_bf16 v[16:19], v[150:153], v[210:213], v[16:19]
	v_mfma_f32_16x16x32_bf16 v[44:47], v[154:157], v[170:173], v[44:47]
	v_mfma_f32_16x16x32_bf16 v[36:39], v[162:165], v[170:173], v[36:39]
	v_mfma_f32_16x16x32_bf16 v[28:31], v[154:157], v[182:185], v[28:31]
	v_mfma_f32_16x16x32_bf16 v[20:23], v[162:165], v[182:185], v[20:23]
	v_mfma_f32_16x16x32_bf16 v[12:15], v[154:157], v[190:193], v[12:15]
	v_mfma_f32_16x16x32_bf16 v[8:11], v[162:165], v[190:193], v[8:11]
	v_mfma_f32_16x16x32_bf16 v[4:7], v[154:157], v[206:209], v[4:7]
	v_mfma_f32_16x16x32_bf16 v[0:3], v[162:165], v[206:209], v[0:3]
	v_mfma_f32_16x16x32_bf16 v[44:47], v[158:161], v[178:181], v[44:47]
	v_mfma_f32_16x16x32_bf16 v[36:39], v[166:169], v[178:181], v[36:39]
	v_mfma_f32_16x16x32_bf16 v[28:31], v[158:161], v[186:189], v[28:31]
	v_mfma_f32_16x16x32_bf16 v[20:23], v[166:169], v[186:189], v[20:23]
	v_mfma_f32_16x16x32_bf16 v[12:15], v[158:161], v[194:197], v[12:15]
	v_mfma_f32_16x16x32_bf16 v[8:11], v[166:169], v[194:197], v[8:11]
	v_mfma_f32_16x16x32_bf16 v[4:7], v[158:161], v[210:213], v[4:7]
	s_setprio 2
	s_barrier
	v_mfma_f32_16x16x32_bf16 v[0:3], v[166:169], v[210:213], v[0:3]
	s_setprio 0
	ds_read_b128 v[170:173], v137 offset:32768
	ds_read_b128 v[178:181], v137 offset:33792
	ds_read_b128 v[182:185], v137 offset:34816
	ds_read_b128 v[186:189], v137 offset:35840
	ds_read_b128 v[190:193], v137 offset:36864
	ds_read_b128 v[194:197], v137 offset:37888
	ds_read_b128 v[206:209], v137 offset:38912
	ds_read_b128 v[210:213], v137 offset:39936
	v_add_u32_e32 v150, s3, v134
	v_add_u32_e32 v166, s2, v134
	ds_read_b128 v[138:141], v150
	ds_read_b128 v[142:145], v150 offset:1024
	ds_read_b128 v[146:149], v150 offset:2048
	ds_read_b128 v[150:153], v150 offset:3072
	ds_read_b128 v[154:157], v166
	ds_read_b128 v[158:161], v166 offset:1024
	ds_read_b128 v[162:165], v166 offset:2048
	ds_read_b128 v[166:169], v166 offset:3072
	s_mov_b32 m0, s82
	v_lshl_add_u64 v[216:217], s[64:65], 0, v[128:129]
	global_load_lds_dwordx4 v[216:217], off
	s_mov_b32 m0, s83
	v_lshl_add_u64 v[216:217], s[64:65], 0, v[130:131]
	global_load_lds_dwordx4 v[216:217], off
	s_waitcnt vmcnt(8) lgkmcnt(0)
	s_setprio 1
	s_barrier
	v_mfma_f32_16x16x32_bf16 v[124:127], v[138:141], v[170:173], v[124:127]
	v_mfma_f32_16x16x32_bf16 v[120:123], v[146:149], v[170:173], v[120:123]
	v_mfma_f32_16x16x32_bf16 v[116:119], v[138:141], v[182:185], v[116:119]
	v_mfma_f32_16x16x32_bf16 v[112:115], v[146:149], v[182:185], v[112:115]
	v_mfma_f32_16x16x32_bf16 v[104:107], v[138:141], v[190:193], v[104:107]
	v_mfma_f32_16x16x32_bf16 v[96:99], v[146:149], v[190:193], v[96:99]
	v_mfma_f32_16x16x32_bf16 v[88:91], v[138:141], v[206:209], v[88:91]
	v_mfma_f32_16x16x32_bf16 v[80:83], v[146:149], v[206:209], v[80:83]
	v_mfma_f32_16x16x32_bf16 v[124:127], v[142:145], v[178:181], v[124:127]
	v_mfma_f32_16x16x32_bf16 v[120:123], v[150:153], v[178:181], v[120:123]
	v_mfma_f32_16x16x32_bf16 v[116:119], v[142:145], v[186:189], v[116:119]
	v_mfma_f32_16x16x32_bf16 v[112:115], v[150:153], v[186:189], v[112:115]
	v_mfma_f32_16x16x32_bf16 v[104:107], v[142:145], v[194:197], v[104:107]
	v_mfma_f32_16x16x32_bf16 v[96:99], v[150:153], v[194:197], v[96:99]
	v_mfma_f32_16x16x32_bf16 v[88:91], v[142:145], v[210:213], v[88:91]
	v_mfma_f32_16x16x32_bf16 v[80:83], v[150:153], v[210:213], v[80:83]
	v_mfma_f32_16x16x32_bf16 v[108:111], v[154:157], v[170:173], v[108:111]
	v_mfma_f32_16x16x32_bf16 v[100:103], v[162:165], v[170:173], v[100:103]
	v_mfma_f32_16x16x32_bf16 v[92:95], v[154:157], v[182:185], v[92:95]
	v_mfma_f32_16x16x32_bf16 v[84:87], v[162:165], v[182:185], v[84:87]
	v_mfma_f32_16x16x32_bf16 v[76:79], v[154:157], v[190:193], v[76:79]
	v_mfma_f32_16x16x32_bf16 v[72:75], v[162:165], v[190:193], v[72:75]
	v_mfma_f32_16x16x32_bf16 v[68:71], v[154:157], v[206:209], v[68:71]
	v_mfma_f32_16x16x32_bf16 v[64:67], v[162:165], v[206:209], v[64:67]
	v_mfma_f32_16x16x32_bf16 v[108:111], v[158:161], v[178:181], v[108:111]
	v_mfma_f32_16x16x32_bf16 v[100:103], v[166:169], v[178:181], v[100:103]
	v_mfma_f32_16x16x32_bf16 v[92:95], v[158:161], v[186:189], v[92:95]
	v_mfma_f32_16x16x32_bf16 v[84:87], v[166:169], v[186:189], v[84:87]
	v_mfma_f32_16x16x32_bf16 v[76:79], v[158:161], v[194:197], v[76:79]
	v_mfma_f32_16x16x32_bf16 v[72:75], v[166:169], v[194:197], v[72:75]
	v_mfma_f32_16x16x32_bf16 v[68:71], v[158:161], v[210:213], v[68:71]
	s_setprio 2
	s_barrier
	v_mfma_f32_16x16x32_bf16 v[64:67], v[166:169], v[210:213], v[64:67]
	s_setprio 0
	ds_read_b128 v[170:173], v137 offset:49152
	ds_read_b128 v[178:181], v137 offset:50176
	ds_read_b128 v[182:185], v137 offset:51200
	ds_read_b128 v[186:189], v137 offset:52224
	ds_read_b128 v[190:193], v137 offset:53248
	ds_read_b128 v[194:197], v137 offset:54272
	ds_read_b128 v[206:209], v137 offset:55296
	ds_read_b128 v[210:213], v137 offset:56320
	s_mov_b32 m0, s1
	v_lshl_add_u64 v[174:175], v[174:175], 0, s[26:27]
	global_load_lds_dwordx4 v[174:175], off
	s_mov_b32 m0, s9
	v_lshl_add_u64 v[174:175], v[198:199], 0, s[26:27]
	global_load_lds_dwordx4 v[174:175], off
	s_mov_b32 m0, s97
	v_lshl_add_u64 v[174:175], s[62:63], 0, v[128:129]
	global_load_lds_dwordx4 v[174:175], off
	s_mov_b32 m0, s8
	v_lshl_add_u64 v[174:175], s[62:63], 0, v[130:131]
	global_load_lds_dwordx4 v[174:175], off
	s_mov_b32 m0, s89
	v_lshl_add_u64 v[174:175], v[202:203], 0, s[26:27]
	global_load_lds_dwordx4 v[174:175], off
	s_mov_b32 m0, s90
	v_lshl_add_u64 v[174:175], v[214:215], 0, s[26:27]
	global_load_lds_dwordx4 v[174:175], off
	s_waitcnt vmcnt(8) lgkmcnt(0)
	s_setprio 1
	s_barrier
	v_mfma_f32_16x16x32_bf16 v[60:63], v[138:141], v[170:173], v[60:63]
	v_mfma_f32_16x16x32_bf16 v[56:59], v[146:149], v[170:173], v[56:59]
	v_mfma_f32_16x16x32_bf16 v[52:55], v[138:141], v[182:185], v[52:55]
	v_mfma_f32_16x16x32_bf16 v[48:51], v[146:149], v[182:185], v[48:51]
	v_mfma_f32_16x16x32_bf16 v[40:43], v[138:141], v[190:193], v[40:43]
	v_mfma_f32_16x16x32_bf16 v[32:35], v[146:149], v[190:193], v[32:35]
	v_mfma_f32_16x16x32_bf16 v[24:27], v[138:141], v[206:209], v[24:27]
	v_mfma_f32_16x16x32_bf16 v[16:19], v[146:149], v[206:209], v[16:19]
	v_mfma_f32_16x16x32_bf16 v[60:63], v[142:145], v[178:181], v[60:63]
	v_mfma_f32_16x16x32_bf16 v[56:59], v[150:153], v[178:181], v[56:59]
	v_mfma_f32_16x16x32_bf16 v[52:55], v[142:145], v[186:189], v[52:55]
	v_mfma_f32_16x16x32_bf16 v[48:51], v[150:153], v[186:189], v[48:51]
	v_mfma_f32_16x16x32_bf16 v[40:43], v[142:145], v[194:197], v[40:43]
	v_mfma_f32_16x16x32_bf16 v[32:35], v[150:153], v[194:197], v[32:35]
	v_mfma_f32_16x16x32_bf16 v[24:27], v[142:145], v[210:213], v[24:27]
	v_mfma_f32_16x16x32_bf16 v[16:19], v[150:153], v[210:213], v[16:19]
	v_mfma_f32_16x16x32_bf16 v[44:47], v[154:157], v[170:173], v[44:47]
	v_mfma_f32_16x16x32_bf16 v[36:39], v[162:165], v[170:173], v[36:39]
	v_mfma_f32_16x16x32_bf16 v[28:31], v[154:157], v[182:185], v[28:31]
	v_mfma_f32_16x16x32_bf16 v[20:23], v[162:165], v[182:185], v[20:23]
	v_mfma_f32_16x16x32_bf16 v[12:15], v[154:157], v[190:193], v[12:15]
	v_mfma_f32_16x16x32_bf16 v[8:11], v[162:165], v[190:193], v[8:11]
	v_mfma_f32_16x16x32_bf16 v[4:7], v[154:157], v[206:209], v[4:7]
	v_mfma_f32_16x16x32_bf16 v[0:3], v[162:165], v[206:209], v[0:3]
	v_mfma_f32_16x16x32_bf16 v[44:47], v[158:161], v[178:181], v[44:47]
	v_mfma_f32_16x16x32_bf16 v[36:39], v[166:169], v[178:181], v[36:39]
	v_mfma_f32_16x16x32_bf16 v[28:31], v[158:161], v[186:189], v[28:31]
	v_mfma_f32_16x16x32_bf16 v[20:23], v[166:169], v[186:189], v[20:23]
	v_mfma_f32_16x16x32_bf16 v[12:15], v[158:161], v[194:197], v[12:15]
	v_mfma_f32_16x16x32_bf16 v[8:11], v[166:169], v[194:197], v[8:11]
	v_mfma_f32_16x16x32_bf16 v[4:7], v[158:161], v[210:213], v[4:7]
	s_setprio 2
	s_barrier
	v_mfma_f32_16x16x32_bf16 v[0:3], v[166:169], v[210:213], v[0:3]
	s_setprio 0
	s_mov_b64 s[66:67], 0
	s_mov_b64 s[62:63], -1
	s_mov_b64 s[64:65], 0x100
	s_cbranch_vccz .LBB0_877
	s_and_b64 vcc, exec, s[28:29]
	s_cbranch_vccz .LBB0_880
	s_barrier

.LBB0_904:
	ds_read_b128 v[142:145], v135 offset:1024
	ds_read_b128 v[146:149], v135 offset:2048
	ds_read_b128 v[150:153], v135 offset:3072
	ds_read_b128 v[154:157], v136
	ds_read_b128 v[158:161], v136 offset:1024
	ds_read_b128 v[162:165], v136 offset:2048
	ds_read_b128 v[166:169], v136 offset:3072
	ds_read_b128 v[170:173], v137
	ds_read_b128 v[178:181], v137 offset:1024
	ds_read_b128 v[182:185], v137 offset:2048
	ds_read_b128 v[186:189], v137 offset:3072
	ds_read_b128 v[190:193], v137 offset:4096
	ds_read_b128 v[194:197], v137 offset:5120
	ds_read_b128 v[206:209], v137 offset:6144
	ds_read_b128 v[210:213], v137 offset:7168
	s_add_u32 s2, s28, s56
	s_addc_u32 s3, s29, s57
	s_add_u32 s8, s2, 0x100
	s_addc_u32 s9, s3, 0
	s_and_b64 s[0:1], s[54:55], exec
	v_cndmask_b32_e64 v138, 0, 1, s[58:59]
	s_cselect_b32 s59, s13, s9
	s_cselect_b32 s58, s15, s8
	s_add_u32 s0, s22, s56
	s_addc_u32 s1, s23, s57
	s_add_u32 s8, s0, 0x100
	s_addc_u32 s9, s1, 0
	s_and_b64 s[0:1], s[54:55], exec
	s_cselect_b32 s61, s87, s9
	s_cselect_b32 s60, s88, s8
	s_add_u32 s64, s2, 0x10080
	v_cmp_ne_u32_e32 vcc, 1, v138
	ds_read_b128 v[138:141], v135
	s_addc_u32 s65, s3, 0
	s_add_i32 s38, s83, s66
	s_add_i32 m0, s69, 0xc000
	s_add_i32 s39, s69, 0xe000
	s_add_i32 s0, s38, 0x2000
	s_add_u32 s62, s60, 0x10000
	s_addc_u32 s63, s61, 0
	s_add_i32 s90, s84, s66
	s_add_i32 s76, s90, 0x2000
	s_add_i32 s3, 0, 0x18000
	s_add_i32 s2, 0, 0x1c000
	s_add_u32 s56, s58, 0x10000
	s_addc_u32 s57, s59, 0
	s_add_i32 s1, s3, s66
	s_add_i32 s9, s1, 0x2000
	s_add_u32 s54, s60, 0x10080
	s_addc_u32 s55, s61, 0
	s_add_i32 s89, s2, s66
	s_add_i32 s8, s89, 0x2000
	v_lshl_add_u64 v[174:175], s[64:65], 0, v[128:129]
	global_load_lds_dwordx4 v[174:175], off
	s_mov_b32 m0, s39
	v_lshl_add_u64 v[174:175], s[64:65], 0, v[130:131]
	global_load_lds_dwordx4 v[174:175], off
	s_waitcnt vmcnt(8) lgkmcnt(0)
	s_setprio 1
	s_barrier
	v_mfma_f32_16x16x32_bf16 v[124:127], v[138:141], v[170:173], v[124:127]
	v_mfma_f32_16x16x32_bf16 v[120:123], v[146:149], v[170:173], v[120:123]
	v_mfma_f32_16x16x32_bf16 v[116:119], v[138:141], v[182:185], v[116:119]
	v_mfma_f32_16x16x32_bf16 v[112:115], v[146:149], v[182:185], v[112:115]
	v_mfma_f32_16x16x32_bf16 v[104:107], v[138:141], v[190:193], v[104:107]
	v_mfma_f32_16x16x32_bf16 v[96:99], v[146:149], v[190:193], v[96:99]
	v_mfma_f32_16x16x32_bf16 v[88:91], v[138:141], v[206:209], v[88:91]
	v_mfma_f32_16x16x32_bf16 v[80:83], v[146:149], v[206:209], v[80:83]
	v_mfma_f32_16x16x32_bf16 v[124:127], v[142:145], v[178:181], v[124:127]
	v_mfma_f32_16x16x32_bf16 v[120:123], v[150:153], v[178:181], v[120:123]
	v_mfma_f32_16x16x32_bf16 v[116:119], v[142:145], v[186:189], v[116:119]
	v_mfma_f32_16x16x32_bf16 v[112:115], v[150:153], v[186:189], v[112:115]
	v_mfma_f32_16x16x32_bf16 v[104:107], v[142:145], v[194:197], v[104:107]
	v_mfma_f32_16x16x32_bf16 v[96:99], v[150:153], v[194:197], v[96:99]
	v_mfma_f32_16x16x32_bf16 v[88:91], v[142:145], v[210:213], v[88:91]
	v_mfma_f32_16x16x32_bf16 v[80:83], v[150:153], v[210:213], v[80:83]
	v_mfma_f32_16x16x32_bf16 v[108:111], v[154:157], v[170:173], v[108:111]
	v_mfma_f32_16x16x32_bf16 v[100:103], v[162:165], v[170:173], v[100:103]
	v_mfma_f32_16x16x32_bf16 v[92:95], v[154:157], v[182:185], v[92:95]
	v_mfma_f32_16x16x32_bf16 v[84:87], v[162:165], v[182:185], v[84:87]
	v_mfma_f32_16x16x32_bf16 v[76:79], v[154:157], v[190:193], v[76:79]
	v_mfma_f32_16x16x32_bf16 v[72:75], v[162:165], v[190:193], v[72:75]
	v_mfma_f32_16x16x32_bf16 v[68:71], v[154:157], v[206:209], v[68:71]
	v_mfma_f32_16x16x32_bf16 v[64:67], v[162:165], v[206:209], v[64:67]
	v_mfma_f32_16x16x32_bf16 v[108:111], v[158:161], v[178:181], v[108:111]
	v_mfma_f32_16x16x32_bf16 v[100:103], v[166:169], v[178:181], v[100:103]
	v_mfma_f32_16x16x32_bf16 v[92:95], v[158:161], v[186:189], v[92:95]
	v_mfma_f32_16x16x32_bf16 v[84:87], v[166:169], v[186:189], v[84:87]
	v_mfma_f32_16x16x32_bf16 v[76:79], v[158:161], v[194:197], v[76:79]
	v_mfma_f32_16x16x32_bf16 v[72:75], v[166:169], v[194:197], v[72:75]
	v_mfma_f32_16x16x32_bf16 v[68:71], v[158:161], v[210:213], v[68:71]
	s_setprio 2
	s_barrier
	v_mfma_f32_16x16x32_bf16 v[64:67], v[166:169], v[210:213], v[64:67]
	s_setprio 0
	ds_read_b128 v[170:173], v137 offset:16384
	ds_read_b128 v[178:181], v137 offset:17408
	ds_read_b128 v[182:185], v137 offset:18432
	ds_read_b128 v[186:189], v137 offset:19456
	ds_read_b128 v[190:193], v137 offset:20480
	ds_read_b128 v[194:197], v137 offset:21504
	ds_read_b128 v[206:209], v137 offset:22528
	ds_read_b128 v[210:213], v137 offset:23552
	s_mov_b32 m0, s38
	v_lshl_add_u64 v[174:175], s[60:61], 0, v[128:129]
	global_load_lds_dwordx4 v[174:175], off
	v_lshl_add_u64 v[198:199], s[60:61], 0, v[130:131]
	s_mov_b32 m0, s0
	v_lshl_add_u64 v[202:203], s[62:63], 0, v[128:129]
	global_load_lds_dwordx4 v[198:199], off
	s_mov_b32 m0, s90
	v_lshl_add_u64 v[214:215], s[58:59], 0, v[130:131]
	global_load_lds_dwordx4 v[202:203], off
	s_mov_b32 m0, s76
	v_lshl_add_u64 v[202:203], s[62:63], 0, v[130:131]
	global_load_lds_dwordx4 v[202:203], off
	s_mov_b32 m0, s69
	v_lshl_add_u64 v[202:203], s[58:59], 0, v[128:129]
	global_load_lds_dwordx4 v[202:203], off
	s_mov_b32 m0, s70
	s_nop 0
	global_load_lds_dwordx4 v[214:215], off
	s_waitcnt vmcnt(8) lgkmcnt(0)
	s_setprio 1
	s_barrier
	v_mfma_f32_16x16x32_bf16 v[60:63], v[138:141], v[170:173], v[60:63]
	v_mfma_f32_16x16x32_bf16 v[56:59], v[146:149], v[170:173], v[56:59]
	v_mfma_f32_16x16x32_bf16 v[52:55], v[138:141], v[182:185], v[52:55]
	v_mfma_f32_16x16x32_bf16 v[48:51], v[146:149], v[182:185], v[48:51]
	v_mfma_f32_16x16x32_bf16 v[40:43], v[138:141], v[190:193], v[40:43]
	v_mfma_f32_16x16x32_bf16 v[32:35], v[146:149], v[190:193], v[32:35]
	v_mfma_f32_16x16x32_bf16 v[24:27], v[138:141], v[206:209], v[24:27]
	v_mfma_f32_16x16x32_bf16 v[16:19], v[146:149], v[206:209], v[16:19]
	v_mfma_f32_16x16x32_bf16 v[60:63], v[142:145], v[178:181], v[60:63]
	v_mfma_f32_16x16x32_bf16 v[56:59], v[150:153], v[178:181], v[56:59]
	v_mfma_f32_16x16x32_bf16 v[52:55], v[142:145], v[186:189], v[52:55]
	v_mfma_f32_16x16x32_bf16 v[48:51], v[150:153], v[186:189], v[48:51]
	v_mfma_f32_16x16x32_bf16 v[40:43], v[142:145], v[194:197], v[40:43]
	v_mfma_f32_16x16x32_bf16 v[32:35], v[150:153], v[194:197], v[32:35]
	v_mfma_f32_16x16x32_bf16 v[24:27], v[142:145], v[210:213], v[24:27]
	v_mfma_f32_16x16x32_bf16 v[16:19], v[150:153], v[210:213], v[16:19]
	v_mfma_f32_16x16x32_bf16 v[44:47], v[154:157], v[170:173], v[44:47]
	v_mfma_f32_16x16x32_bf16 v[36:39], v[162:165], v[170:173], v[36:39]
	v_mfma_f32_16x16x32_bf16 v[28:31], v[154:157], v[182:185], v[28:31]
	v_mfma_f32_16x16x32_bf16 v[20:23], v[162:165], v[182:185], v[20:23]
	v_mfma_f32_16x16x32_bf16 v[12:15], v[154:157], v[190:193], v[12:15]
	v_mfma_f32_16x16x32_bf16 v[8:11], v[162:165], v[190:193], v[8:11]
	v_mfma_f32_16x16x32_bf16 v[4:7], v[154:157], v[206:209], v[4:7]
	v_mfma_f32_16x16x32_bf16 v[0:3], v[162:165], v[206:209], v[0:3]
	v_mfma_f32_16x16x32_bf16 v[44:47], v[158:161], v[178:181], v[44:47]
	v_mfma_f32_16x16x32_bf16 v[36:39], v[166:169], v[178:181], v[36:39]
	v_mfma_f32_16x16x32_bf16 v[28:31], v[158:161], v[186:189], v[28:31]
	v_mfma_f32_16x16x32_bf16 v[20:23], v[166:169], v[186:189], v[20:23]
	v_mfma_f32_16x16x32_bf16 v[12:15], v[158:161], v[194:197], v[12:15]
	v_mfma_f32_16x16x32_bf16 v[8:11], v[166:169], v[194:197], v[8:11]
	v_mfma_f32_16x16x32_bf16 v[4:7], v[158:161], v[210:213], v[4:7]
	s_setprio 2
	s_barrier
	v_mfma_f32_16x16x32_bf16 v[0:3], v[166:169], v[210:213], v[0:3]
	s_setprio 0
	ds_read_b128 v[170:173], v137 offset:32768
	ds_read_b128 v[178:181], v137 offset:33792
	ds_read_b128 v[182:185], v137 offset:34816
	ds_read_b128 v[186:189], v137 offset:35840
	ds_read_b128 v[190:193], v137 offset:36864
	ds_read_b128 v[194:197], v137 offset:37888
	ds_read_b128 v[206:209], v137 offset:38912
	ds_read_b128 v[210:213], v137 offset:39936
	v_add_u32_e32 v150, s3, v134
	v_add_u32_e32 v166, s2, v134
	ds_read_b128 v[138:141], v150
	ds_read_b128 v[142:145], v150 offset:1024
	ds_read_b128 v[146:149], v150 offset:2048
	ds_read_b128 v[150:153], v150 offset:3072
	ds_read_b128 v[154:157], v166
	ds_read_b128 v[158:161], v166 offset:1024
	ds_read_b128 v[162:165], v166 offset:2048
	ds_read_b128 v[166:169], v166 offset:3072
	s_mov_b32 m0, s71
	v_lshl_add_u64 v[216:217], s[56:57], 0, v[128:129]
	global_load_lds_dwordx4 v[216:217], off
	s_mov_b32 m0, s72
	v_lshl_add_u64 v[216:217], s[56:57], 0, v[130:131]
	global_load_lds_dwordx4 v[216:217], off
	s_waitcnt vmcnt(8) lgkmcnt(0)
	s_setprio 1
	s_barrier
	v_mfma_f32_16x16x32_bf16 v[124:127], v[138:141], v[170:173], v[124:127]
	v_mfma_f32_16x16x32_bf16 v[120:123], v[146:149], v[170:173], v[120:123]
	v_mfma_f32_16x16x32_bf16 v[116:119], v[138:141], v[182:185], v[116:119]
	v_mfma_f32_16x16x32_bf16 v[112:115], v[146:149], v[182:185], v[112:115]
	v_mfma_f32_16x16x32_bf16 v[104:107], v[138:141], v[190:193], v[104:107]
	v_mfma_f32_16x16x32_bf16 v[96:99], v[146:149], v[190:193], v[96:99]
	v_mfma_f32_16x16x32_bf16 v[88:91], v[138:141], v[206:209], v[88:91]
	v_mfma_f32_16x16x32_bf16 v[80:83], v[146:149], v[206:209], v[80:83]
	v_mfma_f32_16x16x32_bf16 v[124:127], v[142:145], v[178:181], v[124:127]
	v_mfma_f32_16x16x32_bf16 v[120:123], v[150:153], v[178:181], v[120:123]
	v_mfma_f32_16x16x32_bf16 v[116:119], v[142:145], v[186:189], v[116:119]
	v_mfma_f32_16x16x32_bf16 v[112:115], v[150:153], v[186:189], v[112:115]
	v_mfma_f32_16x16x32_bf16 v[104:107], v[142:145], v[194:197], v[104:107]
	v_mfma_f32_16x16x32_bf16 v[96:99], v[150:153], v[194:197], v[96:99]
	v_mfma_f32_16x16x32_bf16 v[88:91], v[142:145], v[210:213], v[88:91]
	v_mfma_f32_16x16x32_bf16 v[80:83], v[150:153], v[210:213], v[80:83]
	v_mfma_f32_16x16x32_bf16 v[108:111], v[154:157], v[170:173], v[108:111]
	v_mfma_f32_16x16x32_bf16 v[100:103], v[162:165], v[170:173], v[100:103]
	v_mfma_f32_16x16x32_bf16 v[92:95], v[154:157], v[182:185], v[92:95]
	v_mfma_f32_16x16x32_bf16 v[84:87], v[162:165], v[182:185], v[84:87]
	v_mfma_f32_16x16x32_bf16 v[76:79], v[154:157], v[190:193], v[76:79]
	v_mfma_f32_16x16x32_bf16 v[72:75], v[162:165], v[190:193], v[72:75]
	v_mfma_f32_16x16x32_bf16 v[68:71], v[154:157], v[206:209], v[68:71]
	v_mfma_f32_16x16x32_bf16 v[64:67], v[162:165], v[206:209], v[64:67]
	v_mfma_f32_16x16x32_bf16 v[108:111], v[158:161], v[178:181], v[108:111]
	v_mfma_f32_16x16x32_bf16 v[100:103], v[166:169], v[178:181], v[100:103]
	v_mfma_f32_16x16x32_bf16 v[92:95], v[158:161], v[186:189], v[92:95]
	v_mfma_f32_16x16x32_bf16 v[84:87], v[166:169], v[186:189], v[84:87]
	v_mfma_f32_16x16x32_bf16 v[76:79], v[158:161], v[194:197], v[76:79]
	v_mfma_f32_16x16x32_bf16 v[72:75], v[166:169], v[194:197], v[72:75]
	v_mfma_f32_16x16x32_bf16 v[68:71], v[158:161], v[210:213], v[68:71]
	s_setprio 2
	s_barrier
	v_mfma_f32_16x16x32_bf16 v[64:67], v[166:169], v[210:213], v[64:67]
	s_setprio 0
	ds_read_b128 v[170:173], v137 offset:49152
	ds_read_b128 v[178:181], v137 offset:50176
	ds_read_b128 v[182:185], v137 offset:51200
	ds_read_b128 v[186:189], v137 offset:52224
	ds_read_b128 v[190:193], v137 offset:53248
	ds_read_b128 v[194:197], v137 offset:54272
	ds_read_b128 v[206:209], v137 offset:55296
	ds_read_b128 v[210:213], v137 offset:56320
	s_mov_b32 m0, s1
	v_lshl_add_u64 v[174:175], v[174:175], 0, s[18:19]
	global_load_lds_dwordx4 v[174:175], off
	s_mov_b32 m0, s9
	v_lshl_add_u64 v[174:175], v[198:199], 0, s[18:19]
	global_load_lds_dwordx4 v[174:175], off
	s_mov_b32 m0, s89
	v_lshl_add_u64 v[174:175], s[54:55], 0, v[128:129]
	global_load_lds_dwordx4 v[174:175], off
	s_mov_b32 m0, s8
	v_lshl_add_u64 v[174:175], s[54:55], 0, v[130:131]
	global_load_lds_dwordx4 v[174:175], off
	s_mov_b32 m0, s81
	v_lshl_add_u64 v[174:175], v[202:203], 0, s[18:19]
	global_load_lds_dwordx4 v[174:175], off
	s_mov_b32 m0, s82
	v_lshl_add_u64 v[174:175], v[214:215], 0, s[18:19]
	global_load_lds_dwordx4 v[174:175], off
	s_waitcnt vmcnt(8) lgkmcnt(0)
	s_setprio 1
	s_barrier
	v_mfma_f32_16x16x32_bf16 v[60:63], v[138:141], v[170:173], v[60:63]
	v_mfma_f32_16x16x32_bf16 v[56:59], v[146:149], v[170:173], v[56:59]
	v_mfma_f32_16x16x32_bf16 v[52:55], v[138:141], v[182:185], v[52:55]
	v_mfma_f32_16x16x32_bf16 v[48:51], v[146:149], v[182:185], v[48:51]
	v_mfma_f32_16x16x32_bf16 v[40:43], v[138:141], v[190:193], v[40:43]
	v_mfma_f32_16x16x32_bf16 v[32:35], v[146:149], v[190:193], v[32:35]
	v_mfma_f32_16x16x32_bf16 v[24:27], v[138:141], v[206:209], v[24:27]
	v_mfma_f32_16x16x32_bf16 v[16:19], v[146:149], v[206:209], v[16:19]
	v_mfma_f32_16x16x32_bf16 v[60:63], v[142:145], v[178:181], v[60:63]
	v_mfma_f32_16x16x32_bf16 v[56:59], v[150:153], v[178:181], v[56:59]
	v_mfma_f32_16x16x32_bf16 v[52:55], v[142:145], v[186:189], v[52:55]
	v_mfma_f32_16x16x32_bf16 v[48:51], v[150:153], v[186:189], v[48:51]
	v_mfma_f32_16x16x32_bf16 v[40:43], v[142:145], v[194:197], v[40:43]
	v_mfma_f32_16x16x32_bf16 v[32:35], v[150:153], v[194:197], v[32:35]
	v_mfma_f32_16x16x32_bf16 v[24:27], v[142:145], v[210:213], v[24:27]
	v_mfma_f32_16x16x32_bf16 v[16:19], v[150:153], v[210:213], v[16:19]
	v_mfma_f32_16x16x32_bf16 v[44:47], v[154:157], v[170:173], v[44:47]
	v_mfma_f32_16x16x32_bf16 v[36:39], v[162:165], v[170:173], v[36:39]
	v_mfma_f32_16x16x32_bf16 v[28:31], v[154:157], v[182:185], v[28:31]
	v_mfma_f32_16x16x32_bf16 v[20:23], v[162:165], v[182:185], v[20:23]
	v_mfma_f32_16x16x32_bf16 v[12:15], v[154:157], v[190:193], v[12:15]
	v_mfma_f32_16x16x32_bf16 v[8:11], v[162:165], v[190:193], v[8:11]
	v_mfma_f32_16x16x32_bf16 v[4:7], v[154:157], v[206:209], v[4:7]
	v_mfma_f32_16x16x32_bf16 v[0:3], v[162:165], v[206:209], v[0:3]
	v_mfma_f32_16x16x32_bf16 v[44:47], v[158:161], v[178:181], v[44:47]
	v_mfma_f32_16x16x32_bf16 v[36:39], v[166:169], v[178:181], v[36:39]
	v_mfma_f32_16x16x32_bf16 v[28:31], v[158:161], v[186:189], v[28:31]
	v_mfma_f32_16x16x32_bf16 v[20:23], v[166:169], v[186:189], v[20:23]
	v_mfma_f32_16x16x32_bf16 v[12:15], v[158:161], v[194:197], v[12:15]
	v_mfma_f32_16x16x32_bf16 v[8:11], v[166:169], v[194:197], v[8:11]
	v_mfma_f32_16x16x32_bf16 v[4:7], v[158:161], v[210:213], v[4:7]
	s_setprio 2
	s_barrier
	v_mfma_f32_16x16x32_bf16 v[0:3], v[166:169], v[210:213], v[0:3]
	s_setprio 0
	s_mov_b64 s[58:59], 0
	s_mov_b64 s[54:55], -1
	s_mov_b64 s[56:57], 0x100
	s_cbranch_vccz .LBB0_904
	s_and_b64 vcc, exec, s[20:21]
	s_cbranch_vccz .LBB0_907
	s_barrier

.LBB0_953:
	ds_read_b128 v[148:151], v145
	ds_read_b128 v[152:155], v145 offset:1024
	ds_read_b128 v[156:159], v145 offset:2048
	ds_read_b128 v[160:163], v145 offset:3072
	ds_read_b128 v[164:167], v146
	ds_read_b128 v[168:171], v146 offset:1024
	ds_read_b128 v[172:175], v146 offset:2048
	ds_read_b128 v[178:181], v146 offset:3072
	ds_read_b128 v[182:185], v147
	ds_read_b128 v[186:189], v147 offset:1024
	ds_read_b128 v[190:193], v147 offset:2048
	ds_read_b128 v[194:197], v147 offset:3072
	ds_read_b128 v[206:209], v147 offset:4096
	ds_read_b128 v[210:213], v147 offset:5120
	ds_read_b128 v[214:217], v147 offset:6144
	ds_read_b128 v[218:221], v147 offset:7168
	s_add_i32 m0, s67, 0xc000
	v_lshl_add_u64 v[140:141], s[54:55], 0, v[136:137]
	global_load_lds_dwordx4 v[140:141], off
	s_add_i32 m0, s67, 0xe000
	v_lshl_add_u64 v[140:141], s[54:55], 0, v[138:139]
	global_load_lds_dwordx4 v[140:141], off
	s_waitcnt vmcnt(8) lgkmcnt(0)
	s_setprio 1
	s_barrier
	v_mfma_f32_16x16x32_bf16 v[124:127], v[148:151], v[182:185], v[124:127]
	v_mfma_f32_16x16x32_bf16 v[120:123], v[156:159], v[182:185], v[120:123]
	v_mfma_f32_16x16x32_bf16 v[116:119], v[148:151], v[190:193], v[116:119]
	s_add_u32 s56, s54, 0x100
	v_mfma_f32_16x16x32_bf16 v[108:111], v[156:159], v[190:193], v[108:111]
	s_addc_u32 s57, s55, 0
	v_mfma_f32_16x16x32_bf16 v[100:103], v[148:151], v[206:209], v[100:103]
	s_cmp_eq_u32 vcc_hi, 20
	v_mfma_f32_16x16x32_bf16 v[92:95], v[156:159], v[206:209], v[92:95]
	s_cselect_b32 s61, s93, s57
	v_mfma_f32_16x16x32_bf16 v[84:87], v[148:151], v[214:217], v[84:87]
	s_cselect_b32 s60, s94, s56
	v_mfma_f32_16x16x32_bf16 v[76:79], v[156:159], v[214:217], v[76:79]
	s_cselect_b32 s59, s95, vcc_lo
	v_mfma_f32_16x16x32_bf16 v[124:127], v[152:155], v[186:189], v[124:127]
	s_cselect_b32 s58, s96, s97
	v_mfma_f32_16x16x32_bf16 v[120:123], v[160:163], v[186:189], v[120:123]
	v_mfma_f32_16x16x32_bf16 v[116:119], v[152:155], v[194:197], v[116:119]
	v_mfma_f32_16x16x32_bf16 v[108:111], v[160:163], v[194:197], v[108:111]
	v_mfma_f32_16x16x32_bf16 v[100:103], v[152:155], v[210:213], v[100:103]
	v_mfma_f32_16x16x32_bf16 v[92:95], v[160:163], v[210:213], v[92:95]
	v_mfma_f32_16x16x32_bf16 v[84:87], v[152:155], v[218:221], v[84:87]
	v_mfma_f32_16x16x32_bf16 v[76:79], v[160:163], v[218:221], v[76:79]
	v_mfma_f32_16x16x32_bf16 v[112:115], v[164:167], v[182:185], v[112:115]
	v_mfma_f32_16x16x32_bf16 v[104:107], v[172:175], v[182:185], v[104:107]
	v_mfma_f32_16x16x32_bf16 v[96:99], v[164:167], v[190:193], v[96:99]
	v_mfma_f32_16x16x32_bf16 v[88:91], v[172:175], v[190:193], v[88:91]
	v_mfma_f32_16x16x32_bf16 v[80:83], v[164:167], v[206:209], v[80:83]
	v_mfma_f32_16x16x32_bf16 v[72:75], v[172:175], v[206:209], v[72:75]
	v_mfma_f32_16x16x32_bf16 v[68:71], v[164:167], v[214:217], v[68:71]
	v_mfma_f32_16x16x32_bf16 v[64:67], v[172:175], v[214:217], v[64:67]
	v_mfma_f32_16x16x32_bf16 v[112:115], v[168:171], v[186:189], v[112:115]
	v_mfma_f32_16x16x32_bf16 v[104:107], v[178:181], v[186:189], v[104:107]
	v_mfma_f32_16x16x32_bf16 v[96:99], v[168:171], v[194:197], v[96:99]
	v_mfma_f32_16x16x32_bf16 v[88:91], v[178:181], v[194:197], v[88:91]
	v_mfma_f32_16x16x32_bf16 v[80:83], v[168:171], v[210:213], v[80:83]
	v_mfma_f32_16x16x32_bf16 v[72:75], v[178:181], v[210:213], v[72:75]
	v_mfma_f32_16x16x32_bf16 v[68:71], v[168:171], v[218:221], v[68:71]
	s_setprio 2
	s_barrier
	v_mfma_f32_16x16x32_bf16 v[64:67], v[178:181], v[218:221], v[64:67]
	s_setprio 0
	ds_read_b128 v[182:185], v147 offset:16384
	ds_read_b128 v[186:189], v147 offset:17408
	ds_read_b128 v[190:193], v147 offset:18432
	ds_read_b128 v[194:197], v147 offset:19456
	ds_read_b128 v[206:209], v147 offset:20480
	ds_read_b128 v[210:213], v147 offset:21504
	ds_read_b128 v[214:217], v147 offset:22528
	ds_read_b128 v[218:221], v147 offset:23552
	s_add_i32 s0, s79, s66
	s_mov_b32 m0, s0
	v_lshl_add_u64 v[140:141], s[58:59], 0, v[130:131]
	global_load_lds_dwordx4 v[140:141], off
	s_add_i32 m0, s0, 0x2000
	s_add_u32 s0, s58, 0x60000
	v_lshl_add_u64 v[198:199], s[58:59], 0, v[134:135]
	s_addc_u32 s1, s59, 0
	s_add_i32 s2, s80, s66
	global_load_lds_dwordx4 v[198:199], off
	v_lshl_add_u64 v[202:203], s[0:1], 0, v[130:131]
	s_mov_b32 m0, s2
	v_lshl_add_u64 v[222:223], s[60:61], 0, v[132:133]
	global_load_lds_dwordx4 v[202:203], off
	s_add_i32 m0, s2, 0x2000
	v_lshl_add_u64 v[202:203], s[0:1], 0, v[134:135]
	global_load_lds_dwordx4 v[202:203], off
	s_mov_b32 m0, s67
	v_lshl_add_u64 v[202:203], s[60:61], 0, v[128:129]
	global_load_lds_dwordx4 v[202:203], off
	s_mov_b32 m0, s68
	s_nop 0
	global_load_lds_dwordx4 v[222:223], off
	s_waitcnt vmcnt(8) lgkmcnt(0)
	s_setprio 1
	s_barrier
	v_mfma_f32_16x16x32_bf16 v[60:63], v[148:151], v[182:185], v[60:63]
	v_mfma_f32_16x16x32_bf16 v[56:59], v[156:159], v[182:185], v[56:59]
	v_mfma_f32_16x16x32_bf16 v[52:55], v[148:151], v[190:193], v[52:55]
	v_mfma_f32_16x16x32_bf16 v[44:47], v[156:159], v[190:193], v[44:47]
	v_mfma_f32_16x16x32_bf16 v[36:39], v[148:151], v[206:209], v[36:39]
	v_mfma_f32_16x16x32_bf16 v[28:31], v[156:159], v[206:209], v[28:31]
	v_mfma_f32_16x16x32_bf16 v[20:23], v[148:151], v[214:217], v[20:23]
	v_mfma_f32_16x16x32_bf16 v[12:15], v[156:159], v[214:217], v[12:15]
	v_mfma_f32_16x16x32_bf16 v[60:63], v[152:155], v[186:189], v[60:63]
	v_mfma_f32_16x16x32_bf16 v[56:59], v[160:163], v[186:189], v[56:59]
	v_mfma_f32_16x16x32_bf16 v[52:55], v[152:155], v[194:197], v[52:55]
	v_mfma_f32_16x16x32_bf16 v[44:47], v[160:163], v[194:197], v[44:47]
	v_mfma_f32_16x16x32_bf16 v[36:39], v[152:155], v[210:213], v[36:39]
	v_mfma_f32_16x16x32_bf16 v[28:31], v[160:163], v[210:213], v[28:31]
	v_mfma_f32_16x16x32_bf16 v[20:23], v[152:155], v[218:221], v[20:23]
	v_mfma_f32_16x16x32_bf16 v[12:15], v[160:163], v[218:221], v[12:15]
	v_mfma_f32_16x16x32_bf16 v[48:51], v[164:167], v[182:185], v[48:51]
	v_mfma_f32_16x16x32_bf16 v[40:43], v[172:175], v[182:185], v[40:43]
	v_mfma_f32_16x16x32_bf16 v[32:35], v[164:167], v[190:193], v[32:35]
	v_mfma_f32_16x16x32_bf16 v[24:27], v[172:175], v[190:193], v[24:27]
	v_mfma_f32_16x16x32_bf16 v[16:19], v[164:167], v[206:209], v[16:19]
	v_mfma_f32_16x16x32_bf16 v[8:11], v[172:175], v[206:209], v[8:11]
	v_mfma_f32_16x16x32_bf16 v[4:7], v[164:167], v[214:217], v[4:7]
	v_mfma_f32_16x16x32_bf16 v[0:3], v[172:175], v[214:217], v[0:3]
	v_mfma_f32_16x16x32_bf16 v[48:51], v[168:171], v[186:189], v[48:51]
	v_mfma_f32_16x16x32_bf16 v[40:43], v[178:181], v[186:189], v[40:43]
	v_mfma_f32_16x16x32_bf16 v[32:35], v[168:171], v[194:197], v[32:35]
	v_mfma_f32_16x16x32_bf16 v[24:27], v[178:181], v[194:197], v[24:27]
	v_mfma_f32_16x16x32_bf16 v[16:19], v[168:171], v[210:213], v[16:19]
	v_mfma_f32_16x16x32_bf16 v[8:11], v[178:181], v[210:213], v[8:11]
	v_mfma_f32_16x16x32_bf16 v[4:7], v[168:171], v[218:221], v[4:7]
	s_setprio 2
	s_barrier
	v_mfma_f32_16x16x32_bf16 v[0:3], v[178:181], v[218:221], v[0:3]
	s_setprio 0
	ds_read_b128 v[182:185], v147 offset:32768
	ds_read_b128 v[186:189], v147 offset:33792
	ds_read_b128 v[190:193], v147 offset:34816
	ds_read_b128 v[194:197], v147 offset:35840
	ds_read_b128 v[206:209], v147 offset:36864
	ds_read_b128 v[210:213], v147 offset:37888
	ds_read_b128 v[214:217], v147 offset:38912
	ds_read_b128 v[218:221], v147 offset:39936
	s_add_i32 s2, 0, 0x18000
	s_add_i32 s3, 0, 0x1c000
	v_add_u32_e32 v160, s2, v144
	v_add_u32_e32 v177, s3, v144
	ds_read_b128 v[148:151], v160
	ds_read_b128 v[152:155], v160 offset:1024
	ds_read_b128 v[156:159], v160 offset:2048
	ds_read_b128 v[160:163], v160 offset:3072
	ds_read_b128 v[164:167], v177
	ds_read_b128 v[168:171], v177 offset:1024
	ds_read_b128 v[172:175], v177 offset:2048
	ds_read_b128 v[178:181], v177 offset:3072
	s_add_u32 s0, s60, 0x60000
	s_addc_u32 s1, s61, 0
	s_mov_b32 m0, s69
	v_lshl_add_u64 v[224:225], s[0:1], 0, v[128:129]
	global_load_lds_dwordx4 v[224:225], off
	s_mov_b32 m0, s70
	v_lshl_add_u64 v[224:225], s[0:1], 0, v[132:133]
	global_load_lds_dwordx4 v[224:225], off
	s_waitcnt vmcnt(8) lgkmcnt(0)
	s_setprio 1
	s_barrier
	v_mfma_f32_16x16x32_bf16 v[124:127], v[148:151], v[182:185], v[124:127]
	v_mfma_f32_16x16x32_bf16 v[120:123], v[156:159], v[182:185], v[120:123]
	v_mfma_f32_16x16x32_bf16 v[116:119], v[148:151], v[190:193], v[116:119]
	v_mfma_f32_16x16x32_bf16 v[108:111], v[156:159], v[190:193], v[108:111]
	v_mfma_f32_16x16x32_bf16 v[100:103], v[148:151], v[206:209], v[100:103]
	v_mfma_f32_16x16x32_bf16 v[92:95], v[156:159], v[206:209], v[92:95]
	v_mfma_f32_16x16x32_bf16 v[84:87], v[148:151], v[214:217], v[84:87]
	v_mfma_f32_16x16x32_bf16 v[76:79], v[156:159], v[214:217], v[76:79]
	v_mfma_f32_16x16x32_bf16 v[124:127], v[152:155], v[186:189], v[124:127]
	v_mfma_f32_16x16x32_bf16 v[120:123], v[160:163], v[186:189], v[120:123]
	v_mfma_f32_16x16x32_bf16 v[116:119], v[152:155], v[194:197], v[116:119]
	v_mfma_f32_16x16x32_bf16 v[108:111], v[160:163], v[194:197], v[108:111]
	v_mfma_f32_16x16x32_bf16 v[100:103], v[152:155], v[210:213], v[100:103]
	v_mfma_f32_16x16x32_bf16 v[92:95], v[160:163], v[210:213], v[92:95]
	v_mfma_f32_16x16x32_bf16 v[84:87], v[152:155], v[218:221], v[84:87]
	v_mfma_f32_16x16x32_bf16 v[76:79], v[160:163], v[218:221], v[76:79]
	v_mfma_f32_16x16x32_bf16 v[112:115], v[164:167], v[182:185], v[112:115]
	v_mfma_f32_16x16x32_bf16 v[104:107], v[172:175], v[182:185], v[104:107]
	v_mfma_f32_16x16x32_bf16 v[96:99], v[164:167], v[190:193], v[96:99]
	v_mfma_f32_16x16x32_bf16 v[88:91], v[172:175], v[190:193], v[88:91]
	v_mfma_f32_16x16x32_bf16 v[80:83], v[164:167], v[206:209], v[80:83]
	v_mfma_f32_16x16x32_bf16 v[72:75], v[172:175], v[206:209], v[72:75]
	v_mfma_f32_16x16x32_bf16 v[68:71], v[164:167], v[214:217], v[68:71]
	v_mfma_f32_16x16x32_bf16 v[64:67], v[172:175], v[214:217], v[64:67]
	v_mfma_f32_16x16x32_bf16 v[112:115], v[168:171], v[186:189], v[112:115]
	v_mfma_f32_16x16x32_bf16 v[104:107], v[178:181], v[186:189], v[104:107]
	v_mfma_f32_16x16x32_bf16 v[96:99], v[168:171], v[194:197], v[96:99]
	v_mfma_f32_16x16x32_bf16 v[88:91], v[178:181], v[194:197], v[88:91]
	v_mfma_f32_16x16x32_bf16 v[80:83], v[168:171], v[210:213], v[80:83]
	v_mfma_f32_16x16x32_bf16 v[72:75], v[178:181], v[210:213], v[72:75]
	v_mfma_f32_16x16x32_bf16 v[68:71], v[168:171], v[218:221], v[68:71]
	s_setprio 2
	s_barrier
	v_mfma_f32_16x16x32_bf16 v[64:67], v[178:181], v[218:221], v[64:67]
	s_setprio 0
	ds_read_b128 v[182:185], v147 offset:49152
	ds_read_b128 v[186:189], v147 offset:50176
	ds_read_b128 v[190:193], v147 offset:51200
	ds_read_b128 v[194:197], v147 offset:52224
	ds_read_b128 v[206:209], v147 offset:53248
	ds_read_b128 v[210:213], v147 offset:54272
	ds_read_b128 v[214:217], v147 offset:55296
	ds_read_b128 v[218:221], v147 offset:56320
	s_add_i32 s0, s2, s66
	s_mov_b32 m0, s0
	v_lshl_add_u64 v[140:141], v[140:141], 0, s[12:13]
	global_load_lds_dwordx4 v[140:141], off
	s_add_i32 m0, s0, 0x2000
	s_add_u32 s0, s58, 0x60080
	v_lshl_add_u64 v[140:141], v[198:199], 0, s[12:13]
	s_addc_u32 s1, s59, 0
	s_add_i32 s2, s3, s66
	global_load_lds_dwordx4 v[140:141], off
	s_mov_b32 m0, s2
	v_lshl_add_u64 v[140:141], s[0:1], 0, v[130:131]
	global_load_lds_dwordx4 v[140:141], off
	s_add_i32 m0, s2, 0x2000
	v_lshl_add_u64 v[140:141], s[0:1], 0, v[134:135]
	global_load_lds_dwordx4 v[140:141], off
	s_mov_b32 m0, s77
	v_lshl_add_u64 v[140:141], v[202:203], 0, s[12:13]
	global_load_lds_dwordx4 v[140:141], off
	s_mov_b32 m0, s78
	v_lshl_add_u64 v[140:141], v[222:223], 0, s[12:13]
	global_load_lds_dwordx4 v[140:141], off
	s_waitcnt vmcnt(8) lgkmcnt(0)
	s_setprio 1
	s_barrier
	v_mfma_f32_16x16x32_bf16 v[60:63], v[148:151], v[182:185], v[60:63]
	v_mfma_f32_16x16x32_bf16 v[56:59], v[156:159], v[182:185], v[56:59]
	v_mfma_f32_16x16x32_bf16 v[52:55], v[148:151], v[190:193], v[52:55]
	v_mfma_f32_16x16x32_bf16 v[44:47], v[156:159], v[190:193], v[44:47]
	v_mfma_f32_16x16x32_bf16 v[36:39], v[148:151], v[206:209], v[36:39]
	v_mfma_f32_16x16x32_bf16 v[28:31], v[156:159], v[206:209], v[28:31]
	v_mfma_f32_16x16x32_bf16 v[20:23], v[148:151], v[214:217], v[20:23]
	v_mfma_f32_16x16x32_bf16 v[12:15], v[156:159], v[214:217], v[12:15]
	v_mfma_f32_16x16x32_bf16 v[60:63], v[152:155], v[186:189], v[60:63]
	v_mfma_f32_16x16x32_bf16 v[56:59], v[160:163], v[186:189], v[56:59]
	v_mfma_f32_16x16x32_bf16 v[52:55], v[152:155], v[194:197], v[52:55]
	v_mfma_f32_16x16x32_bf16 v[44:47], v[160:163], v[194:197], v[44:47]
	v_mfma_f32_16x16x32_bf16 v[36:39], v[152:155], v[210:213], v[36:39]
	v_mfma_f32_16x16x32_bf16 v[28:31], v[160:163], v[210:213], v[28:31]
	v_mfma_f32_16x16x32_bf16 v[20:23], v[152:155], v[218:221], v[20:23]
	v_mfma_f32_16x16x32_bf16 v[12:15], v[160:163], v[218:221], v[12:15]
	v_mfma_f32_16x16x32_bf16 v[48:51], v[164:167], v[182:185], v[48:51]
	v_mfma_f32_16x16x32_bf16 v[40:43], v[172:175], v[182:185], v[40:43]
	v_mfma_f32_16x16x32_bf16 v[32:35], v[164:167], v[190:193], v[32:35]
	v_mfma_f32_16x16x32_bf16 v[24:27], v[172:175], v[190:193], v[24:27]
	v_mfma_f32_16x16x32_bf16 v[16:19], v[164:167], v[206:209], v[16:19]
	v_mfma_f32_16x16x32_bf16 v[8:11], v[172:175], v[206:209], v[8:11]
	v_mfma_f32_16x16x32_bf16 v[4:7], v[164:167], v[214:217], v[4:7]
	v_mfma_f32_16x16x32_bf16 v[0:3], v[172:175], v[214:217], v[0:3]
	v_mfma_f32_16x16x32_bf16 v[48:51], v[168:171], v[186:189], v[48:51]
	v_mfma_f32_16x16x32_bf16 v[40:43], v[178:181], v[186:189], v[40:43]
	s_add_i32 vcc_hi, vcc_hi, 2
	v_mfma_f32_16x16x32_bf16 v[32:35], v[168:171], v[194:197], v[32:35]
	s_add_u32 s97, s97, 0x100
	v_mfma_f32_16x16x32_bf16 v[24:27], v[178:181], v[194:197], v[24:27]
	s_addc_u32 vcc_lo, vcc_lo, 0
	v_mfma_f32_16x16x32_bf16 v[16:19], v[168:171], v[210:213], v[16:19]
	s_cmp_gt_u32 vcc_hi, 21
	v_mfma_f32_16x16x32_bf16 v[8:11], v[178:181], v[210:213], v[8:11]
	s_mov_b64 s[54:55], s[56:57]
	v_mfma_f32_16x16x32_bf16 v[4:7], v[168:171], v[218:221], v[4:7]
	s_setprio 2
	s_barrier
	v_mfma_f32_16x16x32_bf16 v[0:3], v[178:181], v[218:221], v[0:3]
	s_setprio 0
	s_cbranch_scc0 .LBB0_953
	s_and_b64 vcc, exec, s[14:15]
	s_cbranch_vccz .LBB0_956
	s_barrier

.LBB0_979:
	ds_read_b128 v[144:147], v141
	ds_read_b128 v[148:151], v141 offset:1024
	ds_read_b128 v[152:155], v141 offset:2048
	ds_read_b128 v[156:159], v141 offset:3072
	ds_read_b128 v[160:163], v142
	ds_read_b128 v[164:167], v142 offset:1024
	ds_read_b128 v[168:171], v142 offset:2048
	ds_read_b128 v[172:175], v142 offset:3072
	ds_read_b128 v[178:181], v143
	ds_read_b128 v[182:185], v143 offset:1024
	ds_read_b128 v[186:189], v143 offset:2048
	ds_read_b128 v[190:193], v143 offset:3072
	ds_read_b128 v[194:197], v143 offset:4096
	ds_read_b128 v[206:209], v143 offset:5120
	ds_read_b128 v[210:213], v143 offset:6144
	ds_read_b128 v[214:217], v143 offset:7168
	s_add_u32 s2, s46, s58
	s_addc_u32 s3, s47, 0
	s_add_u32 s38, s2, 0x100
	s_addc_u32 s39, s3, 0
	s_and_b64 s[0:1], s[52:53], exec
	s_cselect_b32 s57, s23, s39
	s_cselect_b32 s56, s85, s38
	s_add_u32 s0, s34, s58
	s_addc_u32 s1, s35, 0
	s_add_u32 s38, s0, 0x100
	s_addc_u32 s39, s1, 0
	s_and_b64 s[0:1], s[52:53], exec
	s_cselect_b32 s59, s86, s39
	s_cselect_b32 s58, s87, s38
	s_add_u32 s62, s2, 0x10080
	s_addc_u32 s63, s3, 0
	s_add_i32 s38, s78, s66
	s_add_i32 m0, s25, 0xc000
	s_add_i32 s39, s25, 0xe000
	s_add_i32 s0, s38, 0x2000
	s_add_u32 s60, s58, 0x10000
	s_addc_u32 s61, s59, 0
	s_add_i32 s91, s79, s66
	s_add_i32 s76, s91, 0x2000
	s_add_i32 s3, 0, 0x18000
	s_add_i32 s2, 0, 0x1c000
	v_cndmask_b32_e64 v136, 0, 1, s[54:55]
	s_add_u32 s54, s56, 0x10000
	s_addc_u32 s55, s57, 0
	s_add_i32 s1, s3, s66
	s_add_i32 s89, s1, 0x2000
	s_add_u32 s52, s58, 0x10080
	s_addc_u32 s53, s59, 0
	s_add_i32 s90, s2, s66
	s_add_i32 s88, s90, 0x2000
	v_cmp_ne_u32_e32 vcc, 1, v136
	v_lshl_add_u64 v[136:137], s[62:63], 0, v[128:129]
	global_load_lds_dwordx4 v[136:137], off
	s_mov_b32 m0, s39
	v_lshl_add_u64 v[136:137], s[62:63], 0, v[132:133]
	global_load_lds_dwordx4 v[136:137], off
	s_waitcnt vmcnt(8) lgkmcnt(0)
	s_setprio 1
	s_barrier
	v_mfma_f32_16x16x32_bf16 v[124:127], v[144:147], v[178:181], v[124:127]
	v_mfma_f32_16x16x32_bf16 v[120:123], v[152:155], v[178:181], v[120:123]
	v_mfma_f32_16x16x32_bf16 v[116:119], v[144:147], v[186:189], v[116:119]
	v_mfma_f32_16x16x32_bf16 v[108:111], v[152:155], v[186:189], v[108:111]
	v_mfma_f32_16x16x32_bf16 v[100:103], v[144:147], v[194:197], v[100:103]
	v_mfma_f32_16x16x32_bf16 v[92:95], v[152:155], v[194:197], v[92:95]
	v_mfma_f32_16x16x32_bf16 v[84:87], v[144:147], v[210:213], v[84:87]
	v_mfma_f32_16x16x32_bf16 v[76:79], v[152:155], v[210:213], v[76:79]
	v_mfma_f32_16x16x32_bf16 v[124:127], v[148:151], v[182:185], v[124:127]
	v_mfma_f32_16x16x32_bf16 v[120:123], v[156:159], v[182:185], v[120:123]
	v_mfma_f32_16x16x32_bf16 v[116:119], v[148:151], v[190:193], v[116:119]
	v_mfma_f32_16x16x32_bf16 v[108:111], v[156:159], v[190:193], v[108:111]
	v_mfma_f32_16x16x32_bf16 v[100:103], v[148:151], v[206:209], v[100:103]
	v_mfma_f32_16x16x32_bf16 v[92:95], v[156:159], v[206:209], v[92:95]
	v_mfma_f32_16x16x32_bf16 v[84:87], v[148:151], v[214:217], v[84:87]
	v_mfma_f32_16x16x32_bf16 v[76:79], v[156:159], v[214:217], v[76:79]
	v_mfma_f32_16x16x32_bf16 v[112:115], v[160:163], v[178:181], v[112:115]
	v_mfma_f32_16x16x32_bf16 v[104:107], v[168:171], v[178:181], v[104:107]
	v_mfma_f32_16x16x32_bf16 v[96:99], v[160:163], v[186:189], v[96:99]
	v_mfma_f32_16x16x32_bf16 v[88:91], v[168:171], v[186:189], v[88:91]
	v_mfma_f32_16x16x32_bf16 v[80:83], v[160:163], v[194:197], v[80:83]
	v_mfma_f32_16x16x32_bf16 v[72:75], v[168:171], v[194:197], v[72:75]
	v_mfma_f32_16x16x32_bf16 v[68:71], v[160:163], v[210:213], v[68:71]
	v_mfma_f32_16x16x32_bf16 v[64:67], v[168:171], v[210:213], v[64:67]
	v_mfma_f32_16x16x32_bf16 v[112:115], v[164:167], v[182:185], v[112:115]
	v_mfma_f32_16x16x32_bf16 v[104:107], v[172:175], v[182:185], v[104:107]
	v_mfma_f32_16x16x32_bf16 v[96:99], v[164:167], v[190:193], v[96:99]
	v_mfma_f32_16x16x32_bf16 v[88:91], v[172:175], v[190:193], v[88:91]
	v_mfma_f32_16x16x32_bf16 v[80:83], v[164:167], v[206:209], v[80:83]
	v_mfma_f32_16x16x32_bf16 v[72:75], v[172:175], v[206:209], v[72:75]
	v_mfma_f32_16x16x32_bf16 v[68:71], v[164:167], v[214:217], v[68:71]
	s_setprio 2
	s_barrier
	v_mfma_f32_16x16x32_bf16 v[64:67], v[172:175], v[214:217], v[64:67]
	s_setprio 0
	ds_read_b128 v[178:181], v143 offset:16384
	ds_read_b128 v[182:185], v143 offset:17408
	ds_read_b128 v[186:189], v143 offset:18432
	ds_read_b128 v[190:193], v143 offset:19456
	ds_read_b128 v[194:197], v143 offset:20480
	ds_read_b128 v[206:209], v143 offset:21504
	ds_read_b128 v[210:213], v143 offset:22528
	ds_read_b128 v[214:217], v143 offset:23552
	s_mov_b32 m0, s38
	v_lshl_add_u64 v[136:137], s[58:59], 0, v[130:131]
	global_load_lds_dwordx4 v[136:137], off
	v_lshl_add_u64 v[198:199], s[58:59], 0, v[134:135]
	s_mov_b32 m0, s0
	v_lshl_add_u64 v[202:203], s[60:61], 0, v[130:131]
	global_load_lds_dwordx4 v[198:199], off
	s_mov_b32 m0, s91
	v_lshl_add_u64 v[218:219], s[56:57], 0, v[132:133]
	global_load_lds_dwordx4 v[202:203], off
	s_mov_b32 m0, s76
	v_lshl_add_u64 v[202:203], s[60:61], 0, v[134:135]
	global_load_lds_dwordx4 v[202:203], off
	s_mov_b32 m0, s25
	v_lshl_add_u64 v[202:203], s[56:57], 0, v[128:129]
	global_load_lds_dwordx4 v[202:203], off
	s_mov_b32 m0, s69
	s_nop 0
	global_load_lds_dwordx4 v[218:219], off
	s_waitcnt vmcnt(8) lgkmcnt(0)
	s_setprio 1
	s_barrier
	v_mfma_f32_16x16x32_bf16 v[60:63], v[144:147], v[178:181], v[60:63]
	v_mfma_f32_16x16x32_bf16 v[56:59], v[152:155], v[178:181], v[56:59]
	v_mfma_f32_16x16x32_bf16 v[52:55], v[144:147], v[186:189], v[52:55]
	v_mfma_f32_16x16x32_bf16 v[44:47], v[152:155], v[186:189], v[44:47]
	v_mfma_f32_16x16x32_bf16 v[36:39], v[144:147], v[194:197], v[36:39]
	v_mfma_f32_16x16x32_bf16 v[28:31], v[152:155], v[194:197], v[28:31]
	v_mfma_f32_16x16x32_bf16 v[20:23], v[144:147], v[210:213], v[20:23]
	v_mfma_f32_16x16x32_bf16 v[12:15], v[152:155], v[210:213], v[12:15]
	v_mfma_f32_16x16x32_bf16 v[60:63], v[148:151], v[182:185], v[60:63]
	v_mfma_f32_16x16x32_bf16 v[56:59], v[156:159], v[182:185], v[56:59]
	v_mfma_f32_16x16x32_bf16 v[52:55], v[148:151], v[190:193], v[52:55]
	v_mfma_f32_16x16x32_bf16 v[44:47], v[156:159], v[190:193], v[44:47]
	v_mfma_f32_16x16x32_bf16 v[36:39], v[148:151], v[206:209], v[36:39]
	v_mfma_f32_16x16x32_bf16 v[28:31], v[156:159], v[206:209], v[28:31]
	v_mfma_f32_16x16x32_bf16 v[20:23], v[148:151], v[214:217], v[20:23]
	v_mfma_f32_16x16x32_bf16 v[12:15], v[156:159], v[214:217], v[12:15]
	v_mfma_f32_16x16x32_bf16 v[48:51], v[160:163], v[178:181], v[48:51]
	v_mfma_f32_16x16x32_bf16 v[40:43], v[168:171], v[178:181], v[40:43]
	v_mfma_f32_16x16x32_bf16 v[32:35], v[160:163], v[186:189], v[32:35]
	v_mfma_f32_16x16x32_bf16 v[24:27], v[168:171], v[186:189], v[24:27]
	v_mfma_f32_16x16x32_bf16 v[16:19], v[160:163], v[194:197], v[16:19]
	v_mfma_f32_16x16x32_bf16 v[8:11], v[168:171], v[194:197], v[8:11]
	v_mfma_f32_16x16x32_bf16 v[4:7], v[160:163], v[210:213], v[4:7]
	v_mfma_f32_16x16x32_bf16 v[0:3], v[168:171], v[210:213], v[0:3]
	v_mfma_f32_16x16x32_bf16 v[48:51], v[164:167], v[182:185], v[48:51]
	v_mfma_f32_16x16x32_bf16 v[40:43], v[172:175], v[182:185], v[40:43]
	v_mfma_f32_16x16x32_bf16 v[32:35], v[164:167], v[190:193], v[32:35]
	v_mfma_f32_16x16x32_bf16 v[24:27], v[172:175], v[190:193], v[24:27]
	v_mfma_f32_16x16x32_bf16 v[16:19], v[164:167], v[206:209], v[16:19]
	v_mfma_f32_16x16x32_bf16 v[8:11], v[172:175], v[206:209], v[8:11]
	v_mfma_f32_16x16x32_bf16 v[4:7], v[164:167], v[214:217], v[4:7]
	s_setprio 2
	s_barrier
	v_mfma_f32_16x16x32_bf16 v[0:3], v[172:175], v[214:217], v[0:3]
	s_setprio 0
	ds_read_b128 v[178:181], v143 offset:32768
	ds_read_b128 v[182:185], v143 offset:33792
	ds_read_b128 v[186:189], v143 offset:34816
	ds_read_b128 v[190:193], v143 offset:35840
	ds_read_b128 v[194:197], v143 offset:36864
	ds_read_b128 v[206:209], v143 offset:37888
	ds_read_b128 v[210:213], v143 offset:38912
	ds_read_b128 v[214:217], v143 offset:39936
	v_add_u32_e32 v156, s3, v140
	v_add_u32_e32 v172, s2, v140
	ds_read_b128 v[144:147], v156
	ds_read_b128 v[148:151], v156 offset:1024
	ds_read_b128 v[152:155], v156 offset:2048
	ds_read_b128 v[156:159], v156 offset:3072
	ds_read_b128 v[160:163], v172
	ds_read_b128 v[164:167], v172 offset:1024
	ds_read_b128 v[168:171], v172 offset:2048
	ds_read_b128 v[172:175], v172 offset:3072
	s_mov_b32 m0, s70
	v_lshl_add_u64 v[220:221], s[54:55], 0, v[128:129]
	global_load_lds_dwordx4 v[220:221], off
	s_mov_b32 m0, s71
	v_lshl_add_u64 v[220:221], s[54:55], 0, v[132:133]
	global_load_lds_dwordx4 v[220:221], off
	s_waitcnt vmcnt(8) lgkmcnt(0)
	s_setprio 1
	s_barrier
	v_mfma_f32_16x16x32_bf16 v[124:127], v[144:147], v[178:181], v[124:127]
	v_mfma_f32_16x16x32_bf16 v[120:123], v[152:155], v[178:181], v[120:123]
	v_mfma_f32_16x16x32_bf16 v[116:119], v[144:147], v[186:189], v[116:119]
	v_mfma_f32_16x16x32_bf16 v[108:111], v[152:155], v[186:189], v[108:111]
	v_mfma_f32_16x16x32_bf16 v[100:103], v[144:147], v[194:197], v[100:103]
	v_mfma_f32_16x16x32_bf16 v[92:95], v[152:155], v[194:197], v[92:95]
	v_mfma_f32_16x16x32_bf16 v[84:87], v[144:147], v[210:213], v[84:87]
	v_mfma_f32_16x16x32_bf16 v[76:79], v[152:155], v[210:213], v[76:79]
	v_mfma_f32_16x16x32_bf16 v[124:127], v[148:151], v[182:185], v[124:127]
	v_mfma_f32_16x16x32_bf16 v[120:123], v[156:159], v[182:185], v[120:123]
	v_mfma_f32_16x16x32_bf16 v[116:119], v[148:151], v[190:193], v[116:119]
	v_mfma_f32_16x16x32_bf16 v[108:111], v[156:159], v[190:193], v[108:111]
	v_mfma_f32_16x16x32_bf16 v[100:103], v[148:151], v[206:209], v[100:103]
	v_mfma_f32_16x16x32_bf16 v[92:95], v[156:159], v[206:209], v[92:95]
	v_mfma_f32_16x16x32_bf16 v[84:87], v[148:151], v[214:217], v[84:87]
	v_mfma_f32_16x16x32_bf16 v[76:79], v[156:159], v[214:217], v[76:79]
	v_mfma_f32_16x16x32_bf16 v[112:115], v[160:163], v[178:181], v[112:115]
	v_mfma_f32_16x16x32_bf16 v[104:107], v[168:171], v[178:181], v[104:107]
	v_mfma_f32_16x16x32_bf16 v[96:99], v[160:163], v[186:189], v[96:99]
	v_mfma_f32_16x16x32_bf16 v[88:91], v[168:171], v[186:189], v[88:91]
	v_mfma_f32_16x16x32_bf16 v[80:83], v[160:163], v[194:197], v[80:83]
	v_mfma_f32_16x16x32_bf16 v[72:75], v[168:171], v[194:197], v[72:75]
	v_mfma_f32_16x16x32_bf16 v[68:71], v[160:163], v[210:213], v[68:71]
	v_mfma_f32_16x16x32_bf16 v[64:67], v[168:171], v[210:213], v[64:67]
	v_mfma_f32_16x16x32_bf16 v[112:115], v[164:167], v[182:185], v[112:115]
	v_mfma_f32_16x16x32_bf16 v[104:107], v[172:175], v[182:185], v[104:107]
	v_mfma_f32_16x16x32_bf16 v[96:99], v[164:167], v[190:193], v[96:99]
	v_mfma_f32_16x16x32_bf16 v[88:91], v[172:175], v[190:193], v[88:91]
	v_mfma_f32_16x16x32_bf16 v[80:83], v[164:167], v[206:209], v[80:83]
	v_mfma_f32_16x16x32_bf16 v[72:75], v[172:175], v[206:209], v[72:75]
	v_mfma_f32_16x16x32_bf16 v[68:71], v[164:167], v[214:217], v[68:71]
	s_setprio 2
	s_barrier
	v_mfma_f32_16x16x32_bf16 v[64:67], v[172:175], v[214:217], v[64:67]
	s_setprio 0
	ds_read_b128 v[178:181], v143 offset:49152
	ds_read_b128 v[182:185], v143 offset:50176
	ds_read_b128 v[186:189], v143 offset:51200
	ds_read_b128 v[190:193], v143 offset:52224
	ds_read_b128 v[194:197], v143 offset:53248
	ds_read_b128 v[206:209], v143 offset:54272
	ds_read_b128 v[210:213], v143 offset:55296
	ds_read_b128 v[214:217], v143 offset:56320
	s_mov_b32 m0, s1
	v_lshl_add_u64 v[136:137], v[136:137], 0, s[10:11]
	global_load_lds_dwordx4 v[136:137], off
	s_mov_b32 m0, s89
	v_lshl_add_u64 v[136:137], v[198:199], 0, s[10:11]
	global_load_lds_dwordx4 v[136:137], off
	s_mov_b32 m0, s90
	v_lshl_add_u64 v[136:137], s[52:53], 0, v[130:131]
	global_load_lds_dwordx4 v[136:137], off
	s_mov_b32 m0, s88
	v_lshl_add_u64 v[136:137], s[52:53], 0, v[134:135]
	global_load_lds_dwordx4 v[136:137], off
	s_mov_b32 m0, s75
	v_lshl_add_u64 v[136:137], v[202:203], 0, s[10:11]
	global_load_lds_dwordx4 v[136:137], off
	s_mov_b32 m0, s77
	v_lshl_add_u64 v[136:137], v[218:219], 0, s[10:11]
	global_load_lds_dwordx4 v[136:137], off
	s_waitcnt vmcnt(8) lgkmcnt(0)
	s_setprio 1
	s_barrier
	v_mfma_f32_16x16x32_bf16 v[60:63], v[144:147], v[178:181], v[60:63]
	v_mfma_f32_16x16x32_bf16 v[56:59], v[152:155], v[178:181], v[56:59]
	v_mfma_f32_16x16x32_bf16 v[52:55], v[144:147], v[186:189], v[52:55]
	v_mfma_f32_16x16x32_bf16 v[44:47], v[152:155], v[186:189], v[44:47]
	v_mfma_f32_16x16x32_bf16 v[36:39], v[144:147], v[194:197], v[36:39]
	v_mfma_f32_16x16x32_bf16 v[28:31], v[152:155], v[194:197], v[28:31]
	v_mfma_f32_16x16x32_bf16 v[20:23], v[144:147], v[210:213], v[20:23]
	v_mfma_f32_16x16x32_bf16 v[12:15], v[152:155], v[210:213], v[12:15]
	v_mfma_f32_16x16x32_bf16 v[60:63], v[148:151], v[182:185], v[60:63]
	v_mfma_f32_16x16x32_bf16 v[56:59], v[156:159], v[182:185], v[56:59]
	v_mfma_f32_16x16x32_bf16 v[52:55], v[148:151], v[190:193], v[52:55]
	v_mfma_f32_16x16x32_bf16 v[44:47], v[156:159], v[190:193], v[44:47]
	v_mfma_f32_16x16x32_bf16 v[36:39], v[148:151], v[206:209], v[36:39]
	v_mfma_f32_16x16x32_bf16 v[28:31], v[156:159], v[206:209], v[28:31]
	v_mfma_f32_16x16x32_bf16 v[20:23], v[148:151], v[214:217], v[20:23]
	v_mfma_f32_16x16x32_bf16 v[12:15], v[156:159], v[214:217], v[12:15]
	v_mfma_f32_16x16x32_bf16 v[48:51], v[160:163], v[178:181], v[48:51]
	v_mfma_f32_16x16x32_bf16 v[40:43], v[168:171], v[178:181], v[40:43]
	v_mfma_f32_16x16x32_bf16 v[32:35], v[160:163], v[186:189], v[32:35]
	v_mfma_f32_16x16x32_bf16 v[24:27], v[168:171], v[186:189], v[24:27]
	v_mfma_f32_16x16x32_bf16 v[16:19], v[160:163], v[194:197], v[16:19]
	v_mfma_f32_16x16x32_bf16 v[8:11], v[168:171], v[194:197], v[8:11]
	v_mfma_f32_16x16x32_bf16 v[4:7], v[160:163], v[210:213], v[4:7]
	v_mfma_f32_16x16x32_bf16 v[0:3], v[168:171], v[210:213], v[0:3]
	v_mfma_f32_16x16x32_bf16 v[48:51], v[164:167], v[182:185], v[48:51]
	v_mfma_f32_16x16x32_bf16 v[40:43], v[172:175], v[182:185], v[40:43]
	v_mfma_f32_16x16x32_bf16 v[32:35], v[164:167], v[190:193], v[32:35]
	v_mfma_f32_16x16x32_bf16 v[24:27], v[172:175], v[190:193], v[24:27]
	v_mfma_f32_16x16x32_bf16 v[16:19], v[164:167], v[206:209], v[16:19]
	v_mfma_f32_16x16x32_bf16 v[8:11], v[172:175], v[206:209], v[8:11]
	v_mfma_f32_16x16x32_bf16 v[4:7], v[164:167], v[214:217], v[4:7]
	s_setprio 2
	s_barrier
	v_mfma_f32_16x16x32_bf16 v[0:3], v[172:175], v[214:217], v[0:3]
	s_setprio 0
	s_movk_i32 s58, 0x100
	s_mov_b64 s[54:55], 0
	s_mov_b64 s[52:53], -1
	s_cbranch_vccz .LBB0_979
	s_and_b64 vcc, exec, s[12:13]
	s_cbranch_vccz .LBB0_982
	s_barrier

.LBB0_1037:
	ds_read_b128 v[128:131], v157
	ds_read_b128 v[132:135], v157 offset:1024
	ds_read_b128 v[136:139], v157 offset:2048
	ds_read_b128 v[140:143], v157 offset:3072
	ds_read_b128 v[160:163], v158
	ds_read_b128 v[164:167], v158 offset:1024
	ds_read_b128 v[168:171], v158 offset:2048
	ds_read_b128 v[172:175], v158 offset:3072
	ds_read_b128 v[178:181], v159
	ds_read_b128 v[182:185], v159 offset:1024
	ds_read_b128 v[186:189], v159 offset:2048
	ds_read_b128 v[190:193], v159 offset:3072
	ds_read_b128 v[194:197], v159 offset:4096
	ds_read_b128 v[206:209], v159 offset:5120
	ds_read_b128 v[210:213], v159 offset:6144
	ds_read_b128 v[214:217], v159 offset:7168
	s_add_i32 m0, s68, 0xc000
	v_lshl_add_u64 v[152:153], s[58:59], 0, v[148:149]
	global_load_lds_dwordx4 v[152:153], off
	s_add_i32 m0, s68, 0xe000
	v_lshl_add_u64 v[152:153], s[58:59], 0, v[150:151]
	global_load_lds_dwordx4 v[152:153], off
	s_waitcnt vmcnt(8) lgkmcnt(0)
	s_setprio 1
	s_barrier
	v_mfma_f32_16x16x32_bf16 v[124:127], v[128:131], v[178:181], v[124:127]
	v_mfma_f32_16x16x32_bf16 v[120:123], v[136:139], v[178:181], v[120:123]
	v_mfma_f32_16x16x32_bf16 v[112:115], v[128:131], v[186:189], v[112:115]
	s_add_u32 s0, s58, 0xfff00080
	v_mfma_f32_16x16x32_bf16 v[108:111], v[136:139], v[186:189], v[108:111]
	s_addc_u32 s1, s59, -1
	v_mfma_f32_16x16x32_bf16 v[96:99], v[128:131], v[194:197], v[96:99]
	s_cmp_eq_u32 s87, 60
	v_mfma_f32_16x16x32_bf16 v[92:95], v[136:139], v[194:197], v[92:95]
	s_cselect_b32 s63, s12, s1
	v_mfma_f32_16x16x32_bf16 v[80:83], v[128:131], v[210:213], v[80:83]
	s_cselect_b32 s62, s29, s0
	v_mfma_f32_16x16x32_bf16 v[76:79], v[136:139], v[210:213], v[76:79]
	s_cselect_b32 s61, s57, s86
	v_mfma_f32_16x16x32_bf16 v[124:127], v[132:135], v[182:185], v[124:127]
	s_cselect_b32 s60, s64, s65
	v_mfma_f32_16x16x32_bf16 v[120:123], v[140:143], v[182:185], v[120:123]
	v_mfma_f32_16x16x32_bf16 v[112:115], v[132:135], v[190:193], v[112:115]
	v_mfma_f32_16x16x32_bf16 v[108:111], v[140:143], v[190:193], v[108:111]
	v_mfma_f32_16x16x32_bf16 v[96:99], v[132:135], v[206:209], v[96:99]
	v_mfma_f32_16x16x32_bf16 v[92:95], v[140:143], v[206:209], v[92:95]
	v_mfma_f32_16x16x32_bf16 v[80:83], v[132:135], v[214:217], v[80:83]
	v_mfma_f32_16x16x32_bf16 v[76:79], v[140:143], v[214:217], v[76:79]
	v_mfma_f32_16x16x32_bf16 v[116:119], v[160:163], v[178:181], v[116:119]
	v_mfma_f32_16x16x32_bf16 v[104:107], v[168:171], v[178:181], v[104:107]
	v_mfma_f32_16x16x32_bf16 v[100:103], v[160:163], v[186:189], v[100:103]
	v_mfma_f32_16x16x32_bf16 v[88:91], v[168:171], v[186:189], v[88:91]
	v_mfma_f32_16x16x32_bf16 v[84:87], v[160:163], v[194:197], v[84:87]
	v_mfma_f32_16x16x32_bf16 v[72:75], v[168:171], v[194:197], v[72:75]
	v_mfma_f32_16x16x32_bf16 v[68:71], v[160:163], v[210:213], v[68:71]
	v_mfma_f32_16x16x32_bf16 v[64:67], v[168:171], v[210:213], v[64:67]
	v_mfma_f32_16x16x32_bf16 v[116:119], v[164:167], v[182:185], v[116:119]
	v_mfma_f32_16x16x32_bf16 v[104:107], v[172:175], v[182:185], v[104:107]
	v_mfma_f32_16x16x32_bf16 v[100:103], v[164:167], v[190:193], v[100:103]
	v_mfma_f32_16x16x32_bf16 v[88:91], v[172:175], v[190:193], v[88:91]
	v_mfma_f32_16x16x32_bf16 v[84:87], v[164:167], v[206:209], v[84:87]
	v_mfma_f32_16x16x32_bf16 v[72:75], v[172:175], v[206:209], v[72:75]
	v_mfma_f32_16x16x32_bf16 v[68:71], v[164:167], v[214:217], v[68:71]
	s_setprio 2
	s_barrier
	v_mfma_f32_16x16x32_bf16 v[64:67], v[172:175], v[214:217], v[64:67]
	s_setprio 0
	ds_read_b128 v[178:181], v159 offset:16384
	ds_read_b128 v[182:185], v159 offset:17408
	ds_read_b128 v[186:189], v159 offset:18432
	ds_read_b128 v[190:193], v159 offset:19456
	ds_read_b128 v[194:197], v159 offset:20480
	ds_read_b128 v[206:209], v159 offset:21504
	ds_read_b128 v[210:213], v159 offset:22528
	ds_read_b128 v[214:217], v159 offset:23552
	s_add_i32 s0, s81, s67
	s_mov_b32 m0, s0
	v_lshl_add_u64 v[152:153], s[60:61], 0, v[146:147]
	global_load_lds_dwordx4 v[152:153], off
	s_add_i32 m0, s0, 0x2000
	s_add_u32 s0, s60, 0x100000
	v_lshl_add_u64 v[198:199], s[60:61], 0, v[144:145]
	s_addc_u32 s1, s61, 0
	s_add_i32 s2, s82, s67
	global_load_lds_dwordx4 v[198:199], off
	v_lshl_add_u64 v[202:203], s[0:1], 0, v[146:147]
	s_mov_b32 m0, s2
	v_lshl_add_u64 v[218:219], s[62:63], 0, v[144:145]
	global_load_lds_dwordx4 v[202:203], off
	s_add_i32 m0, s2, 0x2000
	v_lshl_add_u64 v[202:203], s[0:1], 0, v[144:145]
	global_load_lds_dwordx4 v[202:203], off
	s_mov_b32 m0, s68
	v_lshl_add_u64 v[202:203], s[62:63], 0, v[146:147]
	global_load_lds_dwordx4 v[202:203], off
	s_mov_b32 m0, s69
	s_nop 0
	global_load_lds_dwordx4 v[218:219], off
	s_waitcnt vmcnt(8) lgkmcnt(0)
	s_setprio 1
	s_barrier
	v_mfma_f32_16x16x32_bf16 v[60:63], v[128:131], v[178:181], v[60:63]
	v_mfma_f32_16x16x32_bf16 v[56:59], v[136:139], v[178:181], v[56:59]
	v_mfma_f32_16x16x32_bf16 v[48:51], v[128:131], v[186:189], v[48:51]
	v_mfma_f32_16x16x32_bf16 v[44:47], v[136:139], v[186:189], v[44:47]
	v_mfma_f32_16x16x32_bf16 v[32:35], v[128:131], v[194:197], v[32:35]
	v_mfma_f32_16x16x32_bf16 v[28:31], v[136:139], v[194:197], v[28:31]
	v_mfma_f32_16x16x32_bf16 v[16:19], v[128:131], v[210:213], v[16:19]
	v_mfma_f32_16x16x32_bf16 v[12:15], v[136:139], v[210:213], v[12:15]
	v_mfma_f32_16x16x32_bf16 v[60:63], v[132:135], v[182:185], v[60:63]
	v_mfma_f32_16x16x32_bf16 v[56:59], v[140:143], v[182:185], v[56:59]
	v_mfma_f32_16x16x32_bf16 v[48:51], v[132:135], v[190:193], v[48:51]
	v_mfma_f32_16x16x32_bf16 v[44:47], v[140:143], v[190:193], v[44:47]
	v_mfma_f32_16x16x32_bf16 v[32:35], v[132:135], v[206:209], v[32:35]
	v_mfma_f32_16x16x32_bf16 v[28:31], v[140:143], v[206:209], v[28:31]
	v_mfma_f32_16x16x32_bf16 v[16:19], v[132:135], v[214:217], v[16:19]
	v_mfma_f32_16x16x32_bf16 v[12:15], v[140:143], v[214:217], v[12:15]
	v_mfma_f32_16x16x32_bf16 v[52:55], v[160:163], v[178:181], v[52:55]
	v_mfma_f32_16x16x32_bf16 v[40:43], v[168:171], v[178:181], v[40:43]
	v_mfma_f32_16x16x32_bf16 v[36:39], v[160:163], v[186:189], v[36:39]
	v_mfma_f32_16x16x32_bf16 v[24:27], v[168:171], v[186:189], v[24:27]
	v_mfma_f32_16x16x32_bf16 v[20:23], v[160:163], v[194:197], v[20:23]
	v_mfma_f32_16x16x32_bf16 v[8:11], v[168:171], v[194:197], v[8:11]
	v_mfma_f32_16x16x32_bf16 v[4:7], v[160:163], v[210:213], v[4:7]
	v_mfma_f32_16x16x32_bf16 v[0:3], v[168:171], v[210:213], v[0:3]
	v_mfma_f32_16x16x32_bf16 v[52:55], v[164:167], v[182:185], v[52:55]
	v_mfma_f32_16x16x32_bf16 v[40:43], v[172:175], v[182:185], v[40:43]
	v_mfma_f32_16x16x32_bf16 v[36:39], v[164:167], v[190:193], v[36:39]
	v_mfma_f32_16x16x32_bf16 v[24:27], v[172:175], v[190:193], v[24:27]
	v_mfma_f32_16x16x32_bf16 v[20:23], v[164:167], v[206:209], v[20:23]
	v_mfma_f32_16x16x32_bf16 v[8:11], v[172:175], v[206:209], v[8:11]
	v_mfma_f32_16x16x32_bf16 v[4:7], v[164:167], v[214:217], v[4:7]
	s_setprio 2
	s_barrier
	v_mfma_f32_16x16x32_bf16 v[0:3], v[172:175], v[214:217], v[0:3]
	s_setprio 0
	ds_read_b128 v[178:181], v159 offset:32768
	ds_read_b128 v[182:185], v159 offset:33792
	ds_read_b128 v[186:189], v159 offset:34816
	ds_read_b128 v[190:193], v159 offset:35840
	ds_read_b128 v[194:197], v159 offset:36864
	ds_read_b128 v[206:209], v159 offset:37888
	ds_read_b128 v[210:213], v159 offset:38912
	ds_read_b128 v[214:217], v159 offset:39936
	s_add_i32 s2, 0, 0x18000
	s_add_i32 s3, 0, 0x1c000
	v_add_u32_e32 v140, s2, v156
	v_add_u32_e32 v172, s3, v156
	ds_read_b128 v[128:131], v140
	ds_read_b128 v[132:135], v140 offset:1024
	ds_read_b128 v[136:139], v140 offset:2048
	ds_read_b128 v[140:143], v140 offset:3072
	ds_read_b128 v[160:163], v172
	ds_read_b128 v[164:167], v172 offset:1024
	ds_read_b128 v[168:171], v172 offset:2048
	ds_read_b128 v[172:175], v172 offset:3072
	s_add_u32 s0, s62, 0x100000
	s_addc_u32 s1, s63, 0
	s_mov_b32 m0, s70
	v_lshl_add_u64 v[220:221], s[0:1], 0, v[146:147]
	global_load_lds_dwordx4 v[220:221], off
	s_mov_b32 m0, s71
	v_lshl_add_u64 v[220:221], s[0:1], 0, v[144:145]
	global_load_lds_dwordx4 v[220:221], off
	s_waitcnt vmcnt(8) lgkmcnt(0)
	s_setprio 1
	s_barrier
	v_mfma_f32_16x16x32_bf16 v[124:127], v[128:131], v[178:181], v[124:127]
	v_mfma_f32_16x16x32_bf16 v[120:123], v[136:139], v[178:181], v[120:123]
	v_mfma_f32_16x16x32_bf16 v[112:115], v[128:131], v[186:189], v[112:115]
	v_mfma_f32_16x16x32_bf16 v[108:111], v[136:139], v[186:189], v[108:111]
	v_mfma_f32_16x16x32_bf16 v[96:99], v[128:131], v[194:197], v[96:99]
	v_mfma_f32_16x16x32_bf16 v[92:95], v[136:139], v[194:197], v[92:95]
	v_mfma_f32_16x16x32_bf16 v[80:83], v[128:131], v[210:213], v[80:83]
	v_mfma_f32_16x16x32_bf16 v[76:79], v[136:139], v[210:213], v[76:79]
	v_mfma_f32_16x16x32_bf16 v[124:127], v[132:135], v[182:185], v[124:127]
	v_mfma_f32_16x16x32_bf16 v[120:123], v[140:143], v[182:185], v[120:123]
	v_mfma_f32_16x16x32_bf16 v[112:115], v[132:135], v[190:193], v[112:115]
	v_mfma_f32_16x16x32_bf16 v[108:111], v[140:143], v[190:193], v[108:111]
	v_mfma_f32_16x16x32_bf16 v[96:99], v[132:135], v[206:209], v[96:99]
	v_mfma_f32_16x16x32_bf16 v[92:95], v[140:143], v[206:209], v[92:95]
	v_mfma_f32_16x16x32_bf16 v[80:83], v[132:135], v[214:217], v[80:83]
	v_mfma_f32_16x16x32_bf16 v[76:79], v[140:143], v[214:217], v[76:79]
	v_mfma_f32_16x16x32_bf16 v[116:119], v[160:163], v[178:181], v[116:119]
	v_mfma_f32_16x16x32_bf16 v[104:107], v[168:171], v[178:181], v[104:107]
	v_mfma_f32_16x16x32_bf16 v[100:103], v[160:163], v[186:189], v[100:103]
	v_mfma_f32_16x16x32_bf16 v[88:91], v[168:171], v[186:189], v[88:91]
	v_mfma_f32_16x16x32_bf16 v[84:87], v[160:163], v[194:197], v[84:87]
	v_mfma_f32_16x16x32_bf16 v[72:75], v[168:171], v[194:197], v[72:75]
	v_mfma_f32_16x16x32_bf16 v[68:71], v[160:163], v[210:213], v[68:71]
	v_mfma_f32_16x16x32_bf16 v[64:67], v[168:171], v[210:213], v[64:67]
	v_mfma_f32_16x16x32_bf16 v[116:119], v[164:167], v[182:185], v[116:119]
	v_mfma_f32_16x16x32_bf16 v[104:107], v[172:175], v[182:185], v[104:107]
	v_mfma_f32_16x16x32_bf16 v[100:103], v[164:167], v[190:193], v[100:103]
	v_mfma_f32_16x16x32_bf16 v[88:91], v[172:175], v[190:193], v[88:91]
	v_mfma_f32_16x16x32_bf16 v[84:87], v[164:167], v[206:209], v[84:87]
	v_mfma_f32_16x16x32_bf16 v[72:75], v[172:175], v[206:209], v[72:75]
	v_mfma_f32_16x16x32_bf16 v[68:71], v[164:167], v[214:217], v[68:71]
	s_setprio 2
	s_barrier
	v_mfma_f32_16x16x32_bf16 v[64:67], v[172:175], v[214:217], v[64:67]
	s_setprio 0
	ds_read_b128 v[178:181], v159 offset:49152
	ds_read_b128 v[182:185], v159 offset:50176
	ds_read_b128 v[186:189], v159 offset:51200
	ds_read_b128 v[190:193], v159 offset:52224
	ds_read_b128 v[194:197], v159 offset:53248
	ds_read_b128 v[206:209], v159 offset:54272
	ds_read_b128 v[210:213], v159 offset:55296
	ds_read_b128 v[214:217], v159 offset:56320
	s_add_i32 s0, s2, s67
	s_mov_b32 m0, s0
	v_lshl_add_u64 v[152:153], v[152:153], 0, s[10:11]
	global_load_lds_dwordx4 v[152:153], off
	s_add_i32 m0, s0, 0x2000
	s_add_u32 s0, s60, 0x100080
	v_lshl_add_u64 v[152:153], v[198:199], 0, s[10:11]
	s_addc_u32 s1, s61, 0
	s_add_i32 s2, s3, s67
	global_load_lds_dwordx4 v[152:153], off
	s_mov_b32 m0, s2
	v_lshl_add_u64 v[152:153], s[0:1], 0, v[146:147]
	global_load_lds_dwordx4 v[152:153], off
	s_add_i32 m0, s2, 0x2000
	v_lshl_add_u64 v[152:153], s[0:1], 0, v[144:145]
	global_load_lds_dwordx4 v[152:153], off
	s_mov_b32 m0, s79
	v_lshl_add_u64 v[152:153], v[202:203], 0, s[10:11]
	global_load_lds_dwordx4 v[152:153], off
	s_mov_b32 m0, s80
	v_lshl_add_u64 v[152:153], v[218:219], 0, s[10:11]
	global_load_lds_dwordx4 v[152:153], off
	s_waitcnt vmcnt(8) lgkmcnt(0)
	s_setprio 1
	s_barrier
	v_mfma_f32_16x16x32_bf16 v[60:63], v[128:131], v[178:181], v[60:63]
	v_mfma_f32_16x16x32_bf16 v[56:59], v[136:139], v[178:181], v[56:59]
	v_mfma_f32_16x16x32_bf16 v[48:51], v[128:131], v[186:189], v[48:51]
	v_mfma_f32_16x16x32_bf16 v[44:47], v[136:139], v[186:189], v[44:47]
	v_mfma_f32_16x16x32_bf16 v[32:35], v[128:131], v[194:197], v[32:35]
	v_mfma_f32_16x16x32_bf16 v[28:31], v[136:139], v[194:197], v[28:31]
	v_mfma_f32_16x16x32_bf16 v[16:19], v[128:131], v[210:213], v[16:19]
	v_mfma_f32_16x16x32_bf16 v[12:15], v[136:139], v[210:213], v[12:15]
	v_mfma_f32_16x16x32_bf16 v[60:63], v[132:135], v[182:185], v[60:63]
	v_mfma_f32_16x16x32_bf16 v[56:59], v[140:143], v[182:185], v[56:59]
	v_mfma_f32_16x16x32_bf16 v[48:51], v[132:135], v[190:193], v[48:51]
	v_mfma_f32_16x16x32_bf16 v[44:47], v[140:143], v[190:193], v[44:47]
	v_mfma_f32_16x16x32_bf16 v[32:35], v[132:135], v[206:209], v[32:35]
	v_mfma_f32_16x16x32_bf16 v[28:31], v[140:143], v[206:209], v[28:31]
	v_mfma_f32_16x16x32_bf16 v[16:19], v[132:135], v[214:217], v[16:19]
	v_mfma_f32_16x16x32_bf16 v[12:15], v[140:143], v[214:217], v[12:15]
	v_mfma_f32_16x16x32_bf16 v[52:55], v[160:163], v[178:181], v[52:55]
	v_mfma_f32_16x16x32_bf16 v[40:43], v[168:171], v[178:181], v[40:43]
	v_mfma_f32_16x16x32_bf16 v[36:39], v[160:163], v[186:189], v[36:39]
	v_mfma_f32_16x16x32_bf16 v[24:27], v[168:171], v[186:189], v[24:27]
	v_mfma_f32_16x16x32_bf16 v[20:23], v[160:163], v[194:197], v[20:23]
	v_mfma_f32_16x16x32_bf16 v[8:11], v[168:171], v[194:197], v[8:11]
	v_mfma_f32_16x16x32_bf16 v[4:7], v[160:163], v[210:213], v[4:7]
	v_mfma_f32_16x16x32_bf16 v[0:3], v[168:171], v[210:213], v[0:3]
	v_mfma_f32_16x16x32_bf16 v[52:55], v[164:167], v[182:185], v[52:55]
	s_add_i32 s87, s87, 2
	v_mfma_f32_16x16x32_bf16 v[40:43], v[172:175], v[182:185], v[40:43]
	s_add_u32 s58, s58, 0x100
	v_mfma_f32_16x16x32_bf16 v[36:39], v[164:167], v[190:193], v[36:39]
	s_addc_u32 s59, s59, 0
	v_mfma_f32_16x16x32_bf16 v[24:27], v[172:175], v[190:193], v[24:27]
	s_add_u32 s65, s65, 0x100
	v_mfma_f32_16x16x32_bf16 v[20:23], v[164:167], v[206:209], v[20:23]
	s_addc_u32 s86, s86, 0
	v_mfma_f32_16x16x32_bf16 v[8:11], v[172:175], v[206:209], v[8:11]
	s_cmp_gt_u32 s87, 61
	v_mfma_f32_16x16x32_bf16 v[4:7], v[164:167], v[214:217], v[4:7]
	s_setprio 2
	s_barrier
	v_mfma_f32_16x16x32_bf16 v[0:3], v[172:175], v[214:217], v[0:3]
	s_setprio 0
	s_cbranch_scc0 .LBB0_1037
	s_and_b64 vcc, exec, s[14:15]
	s_cbranch_vccz .LBB0_1040
	s_barrier

.LBB0_1107:
	ds_read_b128 v[128:131], v203
	ds_read_b128 v[132:135], v203 offset:1024
	ds_read_b128 v[136:139], v203 offset:2048
	ds_read_b128 v[140:143], v203 offset:3072
	ds_read_b128 v[144:147], v204
	ds_read_b128 v[148:151], v204 offset:1024
	ds_read_b128 v[152:155], v204 offset:2048
	ds_read_b128 v[156:159], v204 offset:3072
	ds_read_b128 v[160:163], v205
	ds_read_b128 v[164:167], v205 offset:1024
	ds_read_b128 v[168:171], v205 offset:2048
	ds_read_b128 v[172:175], v205 offset:3072
	ds_read_b128 v[190:193], v205 offset:4096
	ds_read_b128 v[194:197], v205 offset:5120
	ds_read_b128 v[206:209], v205 offset:6144
	ds_read_b128 v[210:213], v205 offset:7168
	s_add_i32 m0, s77, 0xc000
	v_lshl_add_u64 v[198:199], s[4:5], 0, v[186:187]
	global_load_lds_dwordx4 v[198:199], off
	s_add_i32 m0, s77, 0xe000
	v_lshl_add_u64 v[198:199], s[4:5], 0, v[188:189]
	global_load_lds_dwordx4 v[198:199], off
	s_waitcnt vmcnt(8) lgkmcnt(0)
	s_setprio 1
	s_barrier
	v_mfma_f32_16x16x32_bf16 v[124:127], v[128:131], v[160:163], v[124:127]
	v_mfma_f32_16x16x32_bf16 v[56:59], v[136:139], v[160:163], v[56:59]
	v_mfma_f32_16x16x32_bf16 v[116:119], v[128:131], v[168:171], v[116:119]
	s_add_u32 s0, s4, 0xfff80080
	v_mfma_f32_16x16x32_bf16 v[52:55], v[136:139], v[168:171], v[52:55]
	s_addc_u32 s1, s5, -1
	v_mfma_f32_16x16x32_bf16 v[108:111], v[128:131], v[190:193], v[108:111]
	s_cmp_eq_u32 s96, 28
	v_mfma_f32_16x16x32_bf16 v[44:47], v[136:139], v[190:193], v[44:47]
	s_cselect_b32 s9, s13, s1
	v_mfma_f32_16x16x32_bf16 v[104:107], v[128:131], v[206:209], v[104:107]
	s_cselect_b32 s8, s15, s0
	v_mfma_f32_16x16x32_bf16 v[32:35], v[136:139], v[206:209], v[32:35]
	s_cselect_b32 s7, s37, s11
	v_mfma_f32_16x16x32_bf16 v[124:127], v[132:135], v[164:167], v[124:127]
	s_cselect_b32 s6, s63, s10
	v_mfma_f32_16x16x32_bf16 v[56:59], v[140:143], v[164:167], v[56:59]
	v_mfma_f32_16x16x32_bf16 v[116:119], v[132:135], v[172:175], v[116:119]
	v_mfma_f32_16x16x32_bf16 v[52:55], v[140:143], v[172:175], v[52:55]
	v_mfma_f32_16x16x32_bf16 v[108:111], v[132:135], v[194:197], v[108:111]
	v_mfma_f32_16x16x32_bf16 v[44:47], v[140:143], v[194:197], v[44:47]
	v_mfma_f32_16x16x32_bf16 v[104:107], v[132:135], v[210:213], v[104:107]
	v_mfma_f32_16x16x32_bf16 v[32:35], v[140:143], v[210:213], v[32:35]
	v_mfma_f32_16x16x32_bf16 v[120:123], v[144:147], v[160:163], v[120:123]
	v_mfma_f32_16x16x32_bf16 v[60:63], v[152:155], v[160:163], v[60:63]
	v_mfma_f32_16x16x32_bf16 v[112:115], v[144:147], v[168:171], v[112:115]
	v_mfma_f32_16x16x32_bf16 v[48:51], v[152:155], v[168:171], v[48:51]
	v_mfma_f32_16x16x32_bf16 v[100:103], v[144:147], v[190:193], v[100:103]
	v_mfma_f32_16x16x32_bf16 v[40:43], v[152:155], v[190:193], v[40:43]
	v_mfma_f32_16x16x32_bf16 v[96:99], v[144:147], v[206:209], v[96:99]
	v_mfma_f32_16x16x32_bf16 v[36:39], v[152:155], v[206:209], v[36:39]
	v_mfma_f32_16x16x32_bf16 v[120:123], v[148:151], v[164:167], v[120:123]
	v_mfma_f32_16x16x32_bf16 v[60:63], v[156:159], v[164:167], v[60:63]
	v_mfma_f32_16x16x32_bf16 v[112:115], v[148:151], v[172:175], v[112:115]
	v_mfma_f32_16x16x32_bf16 v[48:51], v[156:159], v[172:175], v[48:51]
	v_mfma_f32_16x16x32_bf16 v[100:103], v[148:151], v[194:197], v[100:103]
	v_mfma_f32_16x16x32_bf16 v[40:43], v[156:159], v[194:197], v[40:43]
	v_mfma_f32_16x16x32_bf16 v[96:99], v[148:151], v[210:213], v[96:99]
	s_setprio 2
	s_barrier
	v_mfma_f32_16x16x32_bf16 v[36:39], v[156:159], v[210:213], v[36:39]
	s_setprio 0
	ds_read_b128 v[160:163], v205 offset:16384
	ds_read_b128 v[164:167], v205 offset:17408
	ds_read_b128 v[168:171], v205 offset:18432
	ds_read_b128 v[172:175], v205 offset:19456
	ds_read_b128 v[190:193], v205 offset:20480
	ds_read_b128 v[194:197], v205 offset:21504
	ds_read_b128 v[206:209], v205 offset:22528
	ds_read_b128 v[210:213], v205 offset:23552
	s_add_i32 s0, s92, s76
	s_mov_b32 m0, s0
	v_lshl_add_u64 v[198:199], s[6:7], 0, v[180:181]
	global_load_lds_dwordx4 v[198:199], off
	s_add_i32 m0, s0, 0x2000
	s_add_u32 s0, s6, 0x80000
	v_lshl_add_u64 v[214:215], s[6:7], 0, v[184:185]
	s_addc_u32 s1, s7, 0
	s_add_i32 s2, s93, s76
	global_load_lds_dwordx4 v[214:215], off
	v_lshl_add_u64 v[216:217], s[0:1], 0, v[180:181]
	s_mov_b32 m0, s2
	v_lshl_add_u64 v[218:219], s[8:9], 0, v[182:183]
	global_load_lds_dwordx4 v[216:217], off
	s_add_i32 m0, s2, 0x2000
	v_lshl_add_u64 v[216:217], s[0:1], 0, v[184:185]
	global_load_lds_dwordx4 v[216:217], off
	s_mov_b32 m0, s77
	v_lshl_add_u64 v[216:217], s[8:9], 0, v[178:179]
	global_load_lds_dwordx4 v[216:217], off
	s_mov_b32 m0, s78
	s_nop 0
	global_load_lds_dwordx4 v[218:219], off
	s_waitcnt vmcnt(8) lgkmcnt(0)
	s_setprio 1
	s_barrier
	v_mfma_f32_16x16x32_bf16 v[92:95], v[128:131], v[160:163], v[92:95]
	v_mfma_f32_16x16x32_bf16 v[24:27], v[136:139], v[160:163], v[24:27]
	v_mfma_f32_16x16x32_bf16 v[84:87], v[128:131], v[168:171], v[84:87]
	v_mfma_f32_16x16x32_bf16 v[20:23], v[136:139], v[168:171], v[20:23]
	v_mfma_f32_16x16x32_bf16 v[76:79], v[128:131], v[190:193], v[76:79]
	v_mfma_f32_16x16x32_bf16 v[12:15], v[136:139], v[190:193], v[12:15]
	v_mfma_f32_16x16x32_bf16 v[72:75], v[128:131], v[206:209], v[72:75]
	v_mfma_f32_16x16x32_bf16 v[0:3], v[136:139], v[206:209], v[0:3]
	v_mfma_f32_16x16x32_bf16 v[92:95], v[132:135], v[164:167], v[92:95]
	v_mfma_f32_16x16x32_bf16 v[24:27], v[140:143], v[164:167], v[24:27]
	v_mfma_f32_16x16x32_bf16 v[84:87], v[132:135], v[172:175], v[84:87]
	v_mfma_f32_16x16x32_bf16 v[20:23], v[140:143], v[172:175], v[20:23]
	v_mfma_f32_16x16x32_bf16 v[76:79], v[132:135], v[194:197], v[76:79]
	v_mfma_f32_16x16x32_bf16 v[12:15], v[140:143], v[194:197], v[12:15]
	v_mfma_f32_16x16x32_bf16 v[72:75], v[132:135], v[210:213], v[72:75]
	v_mfma_f32_16x16x32_bf16 v[0:3], v[140:143], v[210:213], v[0:3]
	v_mfma_f32_16x16x32_bf16 v[88:91], v[144:147], v[160:163], v[88:91]
	v_mfma_f32_16x16x32_bf16 v[28:31], v[152:155], v[160:163], v[28:31]
	v_mfma_f32_16x16x32_bf16 v[80:83], v[144:147], v[168:171], v[80:83]
	v_mfma_f32_16x16x32_bf16 v[16:19], v[152:155], v[168:171], v[16:19]
	v_mfma_f32_16x16x32_bf16 v[68:71], v[144:147], v[190:193], v[68:71]
	v_mfma_f32_16x16x32_bf16 v[8:11], v[152:155], v[190:193], v[8:11]
	v_mfma_f32_16x16x32_bf16 v[64:67], v[144:147], v[206:209], v[64:67]
	v_mfma_f32_16x16x32_bf16 v[4:7], v[152:155], v[206:209], v[4:7]
	v_mfma_f32_16x16x32_bf16 v[88:91], v[148:151], v[164:167], v[88:91]
	v_mfma_f32_16x16x32_bf16 v[28:31], v[156:159], v[164:167], v[28:31]
	v_mfma_f32_16x16x32_bf16 v[80:83], v[148:151], v[172:175], v[80:83]
	v_mfma_f32_16x16x32_bf16 v[16:19], v[156:159], v[172:175], v[16:19]
	v_mfma_f32_16x16x32_bf16 v[68:71], v[148:151], v[194:197], v[68:71]
	v_mfma_f32_16x16x32_bf16 v[8:11], v[156:159], v[194:197], v[8:11]
	v_mfma_f32_16x16x32_bf16 v[64:67], v[148:151], v[210:213], v[64:67]
	s_setprio 2
	s_barrier
	v_mfma_f32_16x16x32_bf16 v[4:7], v[156:159], v[210:213], v[4:7]
	s_setprio 0
	ds_read_b128 v[160:163], v205 offset:32768
	ds_read_b128 v[164:167], v205 offset:33792
	ds_read_b128 v[168:171], v205 offset:34816
	ds_read_b128 v[172:175], v205 offset:35840
	ds_read_b128 v[190:193], v205 offset:36864
	ds_read_b128 v[194:197], v205 offset:37888
	ds_read_b128 v[206:209], v205 offset:38912
	ds_read_b128 v[210:213], v205 offset:39936
	s_add_i32 s2, 0, 0x18000
	s_add_i32 s38, 0, 0x1c000
	v_add_u32_e32 v140, s2, v202
	v_add_u32_e32 v156, s38, v202
	ds_read_b128 v[128:131], v140
	ds_read_b128 v[132:135], v140 offset:1024
	ds_read_b128 v[136:139], v140 offset:2048
	ds_read_b128 v[140:143], v140 offset:3072
	ds_read_b128 v[144:147], v156
	ds_read_b128 v[148:151], v156 offset:1024
	ds_read_b128 v[152:155], v156 offset:2048
	ds_read_b128 v[156:159], v156 offset:3072
	s_add_u32 s0, s8, 0x80000
	s_addc_u32 s1, s9, 0
	s_mov_b32 m0, s79
	v_lshl_add_u64 v[220:221], s[0:1], 0, v[178:179]
	global_load_lds_dwordx4 v[220:221], off
	s_mov_b32 m0, s80
	v_lshl_add_u64 v[220:221], s[0:1], 0, v[182:183]
	global_load_lds_dwordx4 v[220:221], off
	s_waitcnt vmcnt(8) lgkmcnt(0)
	s_setprio 1
	s_barrier
	v_mfma_f32_16x16x32_bf16 v[124:127], v[128:131], v[160:163], v[124:127]
	v_mfma_f32_16x16x32_bf16 v[56:59], v[136:139], v[160:163], v[56:59]
	v_mfma_f32_16x16x32_bf16 v[116:119], v[128:131], v[168:171], v[116:119]
	v_mfma_f32_16x16x32_bf16 v[52:55], v[136:139], v[168:171], v[52:55]
	v_mfma_f32_16x16x32_bf16 v[108:111], v[128:131], v[190:193], v[108:111]
	v_mfma_f32_16x16x32_bf16 v[44:47], v[136:139], v[190:193], v[44:47]
	v_mfma_f32_16x16x32_bf16 v[104:107], v[128:131], v[206:209], v[104:107]
	v_mfma_f32_16x16x32_bf16 v[32:35], v[136:139], v[206:209], v[32:35]
	v_mfma_f32_16x16x32_bf16 v[124:127], v[132:135], v[164:167], v[124:127]
	v_mfma_f32_16x16x32_bf16 v[56:59], v[140:143], v[164:167], v[56:59]
	v_mfma_f32_16x16x32_bf16 v[116:119], v[132:135], v[172:175], v[116:119]
	v_mfma_f32_16x16x32_bf16 v[52:55], v[140:143], v[172:175], v[52:55]
	v_mfma_f32_16x16x32_bf16 v[108:111], v[132:135], v[194:197], v[108:111]
	v_mfma_f32_16x16x32_bf16 v[44:47], v[140:143], v[194:197], v[44:47]
	v_mfma_f32_16x16x32_bf16 v[104:107], v[132:135], v[210:213], v[104:107]
	v_mfma_f32_16x16x32_bf16 v[32:35], v[140:143], v[210:213], v[32:35]
	v_mfma_f32_16x16x32_bf16 v[120:123], v[144:147], v[160:163], v[120:123]
	v_mfma_f32_16x16x32_bf16 v[60:63], v[152:155], v[160:163], v[60:63]
	v_mfma_f32_16x16x32_bf16 v[112:115], v[144:147], v[168:171], v[112:115]
	v_mfma_f32_16x16x32_bf16 v[48:51], v[152:155], v[168:171], v[48:51]
	v_mfma_f32_16x16x32_bf16 v[100:103], v[144:147], v[190:193], v[100:103]
	v_mfma_f32_16x16x32_bf16 v[40:43], v[152:155], v[190:193], v[40:43]
	v_mfma_f32_16x16x32_bf16 v[96:99], v[144:147], v[206:209], v[96:99]
	v_mfma_f32_16x16x32_bf16 v[36:39], v[152:155], v[206:209], v[36:39]
	v_mfma_f32_16x16x32_bf16 v[120:123], v[148:151], v[164:167], v[120:123]
	v_mfma_f32_16x16x32_bf16 v[60:63], v[156:159], v[164:167], v[60:63]
	v_mfma_f32_16x16x32_bf16 v[112:115], v[148:151], v[172:175], v[112:115]
	v_mfma_f32_16x16x32_bf16 v[48:51], v[156:159], v[172:175], v[48:51]
	v_mfma_f32_16x16x32_bf16 v[100:103], v[148:151], v[194:197], v[100:103]
	v_mfma_f32_16x16x32_bf16 v[40:43], v[156:159], v[194:197], v[40:43]
	v_mfma_f32_16x16x32_bf16 v[96:99], v[148:151], v[210:213], v[96:99]
	s_setprio 2
	s_barrier
	v_mfma_f32_16x16x32_bf16 v[36:39], v[156:159], v[210:213], v[36:39]
	s_setprio 0
	ds_read_b128 v[160:163], v205 offset:49152
	ds_read_b128 v[164:167], v205 offset:50176
	ds_read_b128 v[168:171], v205 offset:51200
	ds_read_b128 v[172:175], v205 offset:52224
	ds_read_b128 v[190:193], v205 offset:53248
	ds_read_b128 v[194:197], v205 offset:54272
	ds_read_b128 v[206:209], v205 offset:55296
	ds_read_b128 v[210:213], v205 offset:56320
	s_add_i32 s0, s2, s76
	s_mov_b32 m0, s0
	v_lshl_add_u64 v[198:199], v[198:199], 0, s[24:25]
	global_load_lds_dwordx4 v[198:199], off
	s_add_i32 m0, s0, 0x2000
	s_add_u32 s0, s6, 0x80080
	v_lshl_add_u64 v[198:199], v[214:215], 0, s[24:25]
	s_addc_u32 s1, s7, 0
	s_add_i32 s2, s38, s76
	global_load_lds_dwordx4 v[198:199], off
	s_mov_b32 m0, s2
	v_lshl_add_u64 v[198:199], s[0:1], 0, v[180:181]
	global_load_lds_dwordx4 v[198:199], off
	s_add_i32 m0, s2, 0x2000
	v_lshl_add_u64 v[198:199], s[0:1], 0, v[184:185]
	global_load_lds_dwordx4 v[198:199], off
	s_mov_b32 m0, s86
	v_lshl_add_u64 v[198:199], v[216:217], 0, s[24:25]
	global_load_lds_dwordx4 v[198:199], off
	s_mov_b32 m0, s87
	v_lshl_add_u64 v[198:199], v[218:219], 0, s[24:25]
	global_load_lds_dwordx4 v[198:199], off
	s_waitcnt vmcnt(8) lgkmcnt(0)
	s_setprio 1
	s_barrier
	v_mfma_f32_16x16x32_bf16 v[92:95], v[128:131], v[160:163], v[92:95]
	v_mfma_f32_16x16x32_bf16 v[24:27], v[136:139], v[160:163], v[24:27]
	v_mfma_f32_16x16x32_bf16 v[84:87], v[128:131], v[168:171], v[84:87]
	v_mfma_f32_16x16x32_bf16 v[20:23], v[136:139], v[168:171], v[20:23]
	v_mfma_f32_16x16x32_bf16 v[76:79], v[128:131], v[190:193], v[76:79]
	v_mfma_f32_16x16x32_bf16 v[12:15], v[136:139], v[190:193], v[12:15]
	v_mfma_f32_16x16x32_bf16 v[72:75], v[128:131], v[206:209], v[72:75]
	v_mfma_f32_16x16x32_bf16 v[0:3], v[136:139], v[206:209], v[0:3]
	v_mfma_f32_16x16x32_bf16 v[92:95], v[132:135], v[164:167], v[92:95]
	v_mfma_f32_16x16x32_bf16 v[24:27], v[140:143], v[164:167], v[24:27]
	v_mfma_f32_16x16x32_bf16 v[84:87], v[132:135], v[172:175], v[84:87]
	v_mfma_f32_16x16x32_bf16 v[20:23], v[140:143], v[172:175], v[20:23]
	v_mfma_f32_16x16x32_bf16 v[76:79], v[132:135], v[194:197], v[76:79]
	v_mfma_f32_16x16x32_bf16 v[12:15], v[140:143], v[194:197], v[12:15]
	v_mfma_f32_16x16x32_bf16 v[72:75], v[132:135], v[210:213], v[72:75]
	v_mfma_f32_16x16x32_bf16 v[0:3], v[140:143], v[210:213], v[0:3]
	v_mfma_f32_16x16x32_bf16 v[88:91], v[144:147], v[160:163], v[88:91]
	v_mfma_f32_16x16x32_bf16 v[28:31], v[152:155], v[160:163], v[28:31]
	v_mfma_f32_16x16x32_bf16 v[80:83], v[144:147], v[168:171], v[80:83]
	v_mfma_f32_16x16x32_bf16 v[16:19], v[152:155], v[168:171], v[16:19]
	v_mfma_f32_16x16x32_bf16 v[68:71], v[144:147], v[190:193], v[68:71]
	v_mfma_f32_16x16x32_bf16 v[8:11], v[152:155], v[190:193], v[8:11]
	v_mfma_f32_16x16x32_bf16 v[64:67], v[144:147], v[206:209], v[64:67]
	v_mfma_f32_16x16x32_bf16 v[4:7], v[152:155], v[206:209], v[4:7]
	v_mfma_f32_16x16x32_bf16 v[88:91], v[148:151], v[164:167], v[88:91]
	s_add_i32 s96, s96, 2
	v_mfma_f32_16x16x32_bf16 v[28:31], v[156:159], v[164:167], v[28:31]
	s_add_u32 s4, s4, 0x100
	v_mfma_f32_16x16x32_bf16 v[80:83], v[148:151], v[172:175], v[80:83]
	s_addc_u32 s5, s5, 0
	v_mfma_f32_16x16x32_bf16 v[16:19], v[156:159], v[172:175], v[16:19]
	s_add_u32 s10, s10, 0x100
	v_mfma_f32_16x16x32_bf16 v[68:71], v[148:151], v[194:197], v[68:71]
	s_addc_u32 s11, s11, 0
	v_mfma_f32_16x16x32_bf16 v[8:11], v[156:159], v[194:197], v[8:11]
	s_cmp_gt_u32 s96, 29
	v_mfma_f32_16x16x32_bf16 v[64:67], v[148:151], v[210:213], v[64:67]
	s_setprio 2
	s_barrier
	v_mfma_f32_16x16x32_bf16 v[4:7], v[156:159], v[210:213], v[4:7]
	s_setprio 0
	s_cbranch_scc0 .LBB0_1107
	s_and_b64 vcc, exec, s[26:27]
	s_cbranch_vccz .LBB0_1110
	s_barrier

.LBB0_1249:
	ds_read_b128 v[128:131], v157
	ds_read_b128 v[132:135], v157 offset:1024
	ds_read_b128 v[136:139], v157 offset:2048
	ds_read_b128 v[140:143], v157 offset:3072
	ds_read_b128 v[160:163], v158
	ds_read_b128 v[164:167], v158 offset:1024
	ds_read_b128 v[168:171], v158 offset:2048
	ds_read_b128 v[172:175], v158 offset:3072
	ds_read_b128 v[176:179], v159
	ds_read_b128 v[180:183], v159 offset:1024
	ds_read_b128 v[184:187], v159 offset:2048
	ds_read_b128 v[188:191], v159 offset:3072
	ds_read_b128 v[192:195], v159 offset:4096
	ds_read_b128 v[196:199], v159 offset:5120
	ds_read_b128 v[200:203], v159 offset:6144
	ds_read_b128 v[204:207], v159 offset:7168
	s_add_i32 m0, s52, 0xc000
	v_lshl_add_u64 v[152:153], s[36:37], 0, v[148:149]
	global_load_lds_dwordx4 v[152:153], off
	s_add_i32 m0, s52, 0xe000
	v_lshl_add_u64 v[152:153], s[36:37], 0, v[150:151]
	global_load_lds_dwordx4 v[152:153], off
	s_waitcnt vmcnt(8) lgkmcnt(0)
	s_setprio 1
	s_barrier
	v_mfma_f32_16x16x32_bf16 v[124:127], v[128:131], v[176:179], v[124:127]
	v_mfma_f32_16x16x32_bf16 v[120:123], v[136:139], v[176:179], v[120:123]
	v_mfma_f32_16x16x32_bf16 v[112:115], v[128:131], v[184:187], v[112:115]
	s_add_u32 s38, s36, 0x100
	v_mfma_f32_16x16x32_bf16 v[108:111], v[136:139], v[184:187], v[108:111]
	s_addc_u32 s39, s37, 0
	v_mfma_f32_16x16x32_bf16 v[96:99], v[128:131], v[192:195], v[96:99]
	s_cmpk_eq_i32 s74, 0x54
	v_mfma_f32_16x16x32_bf16 v[92:95], v[136:139], v[192:195], v[92:95]
	s_cselect_b32 s45, s6, s39
	v_mfma_f32_16x16x32_bf16 v[80:83], v[128:131], v[200:203], v[80:83]
	s_cselect_b32 s44, s35, s38
	v_mfma_f32_16x16x32_bf16 v[76:79], v[136:139], v[200:203], v[76:79]
	s_cselect_b32 s43, s70, s73
	v_mfma_f32_16x16x32_bf16 v[124:127], v[132:135], v[180:183], v[124:127]
	s_cselect_b32 s42, s71, s72
	v_mfma_f32_16x16x32_bf16 v[120:123], v[140:143], v[180:183], v[120:123]
	v_mfma_f32_16x16x32_bf16 v[112:115], v[132:135], v[188:191], v[112:115]
	v_mfma_f32_16x16x32_bf16 v[108:111], v[140:143], v[188:191], v[108:111]
	v_mfma_f32_16x16x32_bf16 v[96:99], v[132:135], v[196:199], v[96:99]
	v_mfma_f32_16x16x32_bf16 v[92:95], v[140:143], v[196:199], v[92:95]
	v_mfma_f32_16x16x32_bf16 v[80:83], v[132:135], v[204:207], v[80:83]
	v_mfma_f32_16x16x32_bf16 v[76:79], v[140:143], v[204:207], v[76:79]
	v_mfma_f32_16x16x32_bf16 v[116:119], v[160:163], v[176:179], v[116:119]
	v_mfma_f32_16x16x32_bf16 v[104:107], v[168:171], v[176:179], v[104:107]
	v_mfma_f32_16x16x32_bf16 v[100:103], v[160:163], v[184:187], v[100:103]
	v_mfma_f32_16x16x32_bf16 v[88:91], v[168:171], v[184:187], v[88:91]
	v_mfma_f32_16x16x32_bf16 v[84:87], v[160:163], v[192:195], v[84:87]
	v_mfma_f32_16x16x32_bf16 v[72:75], v[168:171], v[192:195], v[72:75]
	v_mfma_f32_16x16x32_bf16 v[68:71], v[160:163], v[200:203], v[68:71]
	v_mfma_f32_16x16x32_bf16 v[64:67], v[168:171], v[200:203], v[64:67]
	v_mfma_f32_16x16x32_bf16 v[116:119], v[164:167], v[180:183], v[116:119]
	v_mfma_f32_16x16x32_bf16 v[104:107], v[172:175], v[180:183], v[104:107]
	v_mfma_f32_16x16x32_bf16 v[100:103], v[164:167], v[188:191], v[100:103]
	v_mfma_f32_16x16x32_bf16 v[88:91], v[172:175], v[188:191], v[88:91]
	v_mfma_f32_16x16x32_bf16 v[84:87], v[164:167], v[196:199], v[84:87]
	v_mfma_f32_16x16x32_bf16 v[72:75], v[172:175], v[196:199], v[72:75]
	v_mfma_f32_16x16x32_bf16 v[68:71], v[164:167], v[204:207], v[68:71]
	s_setprio 2
	s_barrier
	v_mfma_f32_16x16x32_bf16 v[64:67], v[172:175], v[204:207], v[64:67]
	s_setprio 0
	ds_read_b128 v[176:179], v159 offset:16384
	ds_read_b128 v[180:183], v159 offset:17408
	ds_read_b128 v[184:187], v159 offset:18432
	ds_read_b128 v[188:191], v159 offset:19456
	ds_read_b128 v[192:195], v159 offset:20480
	ds_read_b128 v[196:199], v159 offset:21504
	ds_read_b128 v[200:203], v159 offset:22528
	ds_read_b128 v[204:207], v159 offset:23552
	s_add_i32 s36, s64, s51
	s_mov_b32 m0, s36
	v_lshl_add_u64 v[152:153], s[42:43], 0, v[146:147]
	global_load_lds_dwordx4 v[152:153], off
	s_add_i32 m0, s36, 0x2000
	s_add_u32 s36, s42, 0x160000
	v_lshl_add_u64 v[208:209], s[42:43], 0, v[144:145]
	s_addc_u32 s37, s43, 0
	s_add_i32 s75, s65, s51
	global_load_lds_dwordx4 v[208:209], off
	v_lshl_add_u64 v[210:211], s[36:37], 0, v[146:147]
	s_mov_b32 m0, s75
	v_lshl_add_u64 v[212:213], s[44:45], 0, v[144:145]
	global_load_lds_dwordx4 v[210:211], off
	s_add_i32 m0, s75, 0x2000
	v_lshl_add_u64 v[210:211], s[36:37], 0, v[144:145]
	global_load_lds_dwordx4 v[210:211], off
	s_mov_b32 m0, s52
	v_lshl_add_u64 v[210:211], s[44:45], 0, v[146:147]
	global_load_lds_dwordx4 v[210:211], off
	s_mov_b32 m0, s53
	s_nop 0
	global_load_lds_dwordx4 v[212:213], off
	s_waitcnt vmcnt(8) lgkmcnt(0)
	s_setprio 1
	s_barrier
	v_mfma_f32_16x16x32_bf16 v[60:63], v[128:131], v[176:179], v[60:63]
	v_mfma_f32_16x16x32_bf16 v[56:59], v[136:139], v[176:179], v[56:59]
	v_mfma_f32_16x16x32_bf16 v[48:51], v[128:131], v[184:187], v[48:51]
	v_mfma_f32_16x16x32_bf16 v[44:47], v[136:139], v[184:187], v[44:47]
	v_mfma_f32_16x16x32_bf16 v[32:35], v[128:131], v[192:195], v[32:35]
	v_mfma_f32_16x16x32_bf16 v[28:31], v[136:139], v[192:195], v[28:31]
	v_mfma_f32_16x16x32_bf16 v[16:19], v[128:131], v[200:203], v[16:19]
	v_mfma_f32_16x16x32_bf16 v[12:15], v[136:139], v[200:203], v[12:15]
	v_mfma_f32_16x16x32_bf16 v[60:63], v[132:135], v[180:183], v[60:63]
	v_mfma_f32_16x16x32_bf16 v[56:59], v[140:143], v[180:183], v[56:59]
	v_mfma_f32_16x16x32_bf16 v[48:51], v[132:135], v[188:191], v[48:51]
	v_mfma_f32_16x16x32_bf16 v[44:47], v[140:143], v[188:191], v[44:47]
	v_mfma_f32_16x16x32_bf16 v[32:35], v[132:135], v[196:199], v[32:35]
	v_mfma_f32_16x16x32_bf16 v[28:31], v[140:143], v[196:199], v[28:31]
	v_mfma_f32_16x16x32_bf16 v[16:19], v[132:135], v[204:207], v[16:19]
	v_mfma_f32_16x16x32_bf16 v[12:15], v[140:143], v[204:207], v[12:15]
	v_mfma_f32_16x16x32_bf16 v[52:55], v[160:163], v[176:179], v[52:55]
	v_mfma_f32_16x16x32_bf16 v[40:43], v[168:171], v[176:179], v[40:43]
	v_mfma_f32_16x16x32_bf16 v[36:39], v[160:163], v[184:187], v[36:39]
	v_mfma_f32_16x16x32_bf16 v[24:27], v[168:171], v[184:187], v[24:27]
	v_mfma_f32_16x16x32_bf16 v[20:23], v[160:163], v[192:195], v[20:23]
	v_mfma_f32_16x16x32_bf16 v[8:11], v[168:171], v[192:195], v[8:11]
	v_mfma_f32_16x16x32_bf16 v[4:7], v[160:163], v[200:203], v[4:7]
	v_mfma_f32_16x16x32_bf16 v[0:3], v[168:171], v[200:203], v[0:3]
	v_mfma_f32_16x16x32_bf16 v[52:55], v[164:167], v[180:183], v[52:55]
	v_mfma_f32_16x16x32_bf16 v[40:43], v[172:175], v[180:183], v[40:43]
	v_mfma_f32_16x16x32_bf16 v[36:39], v[164:167], v[188:191], v[36:39]
	v_mfma_f32_16x16x32_bf16 v[24:27], v[172:175], v[188:191], v[24:27]
	v_mfma_f32_16x16x32_bf16 v[20:23], v[164:167], v[196:199], v[20:23]
	v_mfma_f32_16x16x32_bf16 v[8:11], v[172:175], v[196:199], v[8:11]
	v_mfma_f32_16x16x32_bf16 v[4:7], v[164:167], v[204:207], v[4:7]
	s_setprio 2
	s_barrier
	v_mfma_f32_16x16x32_bf16 v[0:3], v[172:175], v[204:207], v[0:3]
	s_setprio 0
	ds_read_b128 v[176:179], v159 offset:32768
	ds_read_b128 v[180:183], v159 offset:33792
	ds_read_b128 v[184:187], v159 offset:34816
	ds_read_b128 v[188:191], v159 offset:35840
	ds_read_b128 v[192:195], v159 offset:36864
	ds_read_b128 v[196:199], v159 offset:37888
	ds_read_b128 v[200:203], v159 offset:38912
	ds_read_b128 v[204:207], v159 offset:39936
	s_add_i32 s75, 0, 0x18000
	s_add_i32 s76, 0, 0x1c000
	v_add_u32_e32 v140, s75, v156
	v_add_u32_e32 v172, s76, v156
	ds_read_b128 v[128:131], v140
	ds_read_b128 v[132:135], v140 offset:1024
	ds_read_b128 v[136:139], v140 offset:2048
	ds_read_b128 v[140:143], v140 offset:3072
	ds_read_b128 v[160:163], v172
	ds_read_b128 v[164:167], v172 offset:1024
	ds_read_b128 v[168:171], v172 offset:2048
	ds_read_b128 v[172:175], v172 offset:3072
	s_add_u32 s36, s44, 0x160000
	s_addc_u32 s37, s45, 0
	s_mov_b32 m0, s54
	v_lshl_add_u64 v[214:215], s[36:37], 0, v[146:147]
	global_load_lds_dwordx4 v[214:215], off
	s_mov_b32 m0, s55
	v_lshl_add_u64 v[214:215], s[36:37], 0, v[144:145]
	global_load_lds_dwordx4 v[214:215], off
	s_waitcnt vmcnt(8) lgkmcnt(0)
	s_setprio 1
	s_barrier
	v_mfma_f32_16x16x32_bf16 v[124:127], v[128:131], v[176:179], v[124:127]
	v_mfma_f32_16x16x32_bf16 v[120:123], v[136:139], v[176:179], v[120:123]
	v_mfma_f32_16x16x32_bf16 v[112:115], v[128:131], v[184:187], v[112:115]
	v_mfma_f32_16x16x32_bf16 v[108:111], v[136:139], v[184:187], v[108:111]
	v_mfma_f32_16x16x32_bf16 v[96:99], v[128:131], v[192:195], v[96:99]
	v_mfma_f32_16x16x32_bf16 v[92:95], v[136:139], v[192:195], v[92:95]
	v_mfma_f32_16x16x32_bf16 v[80:83], v[128:131], v[200:203], v[80:83]
	v_mfma_f32_16x16x32_bf16 v[76:79], v[136:139], v[200:203], v[76:79]
	v_mfma_f32_16x16x32_bf16 v[124:127], v[132:135], v[180:183], v[124:127]
	v_mfma_f32_16x16x32_bf16 v[120:123], v[140:143], v[180:183], v[120:123]
	v_mfma_f32_16x16x32_bf16 v[112:115], v[132:135], v[188:191], v[112:115]
	v_mfma_f32_16x16x32_bf16 v[108:111], v[140:143], v[188:191], v[108:111]
	v_mfma_f32_16x16x32_bf16 v[96:99], v[132:135], v[196:199], v[96:99]
	v_mfma_f32_16x16x32_bf16 v[92:95], v[140:143], v[196:199], v[92:95]
	v_mfma_f32_16x16x32_bf16 v[80:83], v[132:135], v[204:207], v[80:83]
	v_mfma_f32_16x16x32_bf16 v[76:79], v[140:143], v[204:207], v[76:79]
	v_mfma_f32_16x16x32_bf16 v[116:119], v[160:163], v[176:179], v[116:119]
	v_mfma_f32_16x16x32_bf16 v[104:107], v[168:171], v[176:179], v[104:107]
	v_mfma_f32_16x16x32_bf16 v[100:103], v[160:163], v[184:187], v[100:103]
	v_mfma_f32_16x16x32_bf16 v[88:91], v[168:171], v[184:187], v[88:91]
	v_mfma_f32_16x16x32_bf16 v[84:87], v[160:163], v[192:195], v[84:87]
	v_mfma_f32_16x16x32_bf16 v[72:75], v[168:171], v[192:195], v[72:75]
	v_mfma_f32_16x16x32_bf16 v[68:71], v[160:163], v[200:203], v[68:71]
	v_mfma_f32_16x16x32_bf16 v[64:67], v[168:171], v[200:203], v[64:67]
	v_mfma_f32_16x16x32_bf16 v[116:119], v[164:167], v[180:183], v[116:119]
	v_mfma_f32_16x16x32_bf16 v[104:107], v[172:175], v[180:183], v[104:107]
	v_mfma_f32_16x16x32_bf16 v[100:103], v[164:167], v[188:191], v[100:103]
	v_mfma_f32_16x16x32_bf16 v[88:91], v[172:175], v[188:191], v[88:91]
	v_mfma_f32_16x16x32_bf16 v[84:87], v[164:167], v[196:199], v[84:87]
	v_mfma_f32_16x16x32_bf16 v[72:75], v[172:175], v[196:199], v[72:75]
	v_mfma_f32_16x16x32_bf16 v[68:71], v[164:167], v[204:207], v[68:71]
	s_setprio 2
	s_barrier
	v_mfma_f32_16x16x32_bf16 v[64:67], v[172:175], v[204:207], v[64:67]
	s_setprio 0
	ds_read_b128 v[176:179], v159 offset:49152
	ds_read_b128 v[180:183], v159 offset:50176
	ds_read_b128 v[184:187], v159 offset:51200
	ds_read_b128 v[188:191], v159 offset:52224
	ds_read_b128 v[192:195], v159 offset:53248
	ds_read_b128 v[196:199], v159 offset:54272
	ds_read_b128 v[200:203], v159 offset:55296
	ds_read_b128 v[204:207], v159 offset:56320
	s_add_i32 s36, s75, s51
	s_mov_b32 m0, s36
	v_lshl_add_u64 v[152:153], v[152:153], 0, s[4:5]
	global_load_lds_dwordx4 v[152:153], off
	s_add_i32 m0, s36, 0x2000
	s_add_u32 s36, s42, 0x160080
	v_lshl_add_u64 v[152:153], v[208:209], 0, s[4:5]
	s_addc_u32 s37, s43, 0
	s_add_i32 s42, s76, s51
	global_load_lds_dwordx4 v[152:153], off
	s_mov_b32 m0, s42
	v_lshl_add_u64 v[152:153], s[36:37], 0, v[146:147]
	global_load_lds_dwordx4 v[152:153], off
	s_add_i32 m0, s42, 0x2000
	v_lshl_add_u64 v[152:153], s[36:37], 0, v[144:145]
	global_load_lds_dwordx4 v[152:153], off
	s_mov_b32 m0, s62
	v_lshl_add_u64 v[152:153], v[210:211], 0, s[4:5]
	global_load_lds_dwordx4 v[152:153], off
	s_mov_b32 m0, s63
	v_lshl_add_u64 v[152:153], v[212:213], 0, s[4:5]
	global_load_lds_dwordx4 v[152:153], off
	s_waitcnt vmcnt(8) lgkmcnt(0)
	s_setprio 1
	s_barrier
	v_mfma_f32_16x16x32_bf16 v[60:63], v[128:131], v[176:179], v[60:63]
	v_mfma_f32_16x16x32_bf16 v[56:59], v[136:139], v[176:179], v[56:59]
	v_mfma_f32_16x16x32_bf16 v[48:51], v[128:131], v[184:187], v[48:51]
	v_mfma_f32_16x16x32_bf16 v[44:47], v[136:139], v[184:187], v[44:47]
	v_mfma_f32_16x16x32_bf16 v[32:35], v[128:131], v[192:195], v[32:35]
	v_mfma_f32_16x16x32_bf16 v[28:31], v[136:139], v[192:195], v[28:31]
	v_mfma_f32_16x16x32_bf16 v[16:19], v[128:131], v[200:203], v[16:19]
	v_mfma_f32_16x16x32_bf16 v[12:15], v[136:139], v[200:203], v[12:15]
	v_mfma_f32_16x16x32_bf16 v[60:63], v[132:135], v[180:183], v[60:63]
	v_mfma_f32_16x16x32_bf16 v[56:59], v[140:143], v[180:183], v[56:59]
	v_mfma_f32_16x16x32_bf16 v[48:51], v[132:135], v[188:191], v[48:51]
	v_mfma_f32_16x16x32_bf16 v[44:47], v[140:143], v[188:191], v[44:47]
	v_mfma_f32_16x16x32_bf16 v[32:35], v[132:135], v[196:199], v[32:35]
	v_mfma_f32_16x16x32_bf16 v[28:31], v[140:143], v[196:199], v[28:31]
	v_mfma_f32_16x16x32_bf16 v[16:19], v[132:135], v[204:207], v[16:19]
	v_mfma_f32_16x16x32_bf16 v[12:15], v[140:143], v[204:207], v[12:15]
	v_mfma_f32_16x16x32_bf16 v[52:55], v[160:163], v[176:179], v[52:55]
	v_mfma_f32_16x16x32_bf16 v[40:43], v[168:171], v[176:179], v[40:43]
	v_mfma_f32_16x16x32_bf16 v[36:39], v[160:163], v[184:187], v[36:39]
	v_mfma_f32_16x16x32_bf16 v[24:27], v[168:171], v[184:187], v[24:27]
	v_mfma_f32_16x16x32_bf16 v[20:23], v[160:163], v[192:195], v[20:23]
	v_mfma_f32_16x16x32_bf16 v[8:11], v[168:171], v[192:195], v[8:11]
	v_mfma_f32_16x16x32_bf16 v[4:7], v[160:163], v[200:203], v[4:7]
	v_mfma_f32_16x16x32_bf16 v[0:3], v[168:171], v[200:203], v[0:3]
	v_mfma_f32_16x16x32_bf16 v[52:55], v[164:167], v[180:183], v[52:55]
	v_mfma_f32_16x16x32_bf16 v[40:43], v[172:175], v[180:183], v[40:43]
	s_add_i32 s74, s74, 2
	v_mfma_f32_16x16x32_bf16 v[36:39], v[164:167], v[188:191], v[36:39]
	s_add_u32 s72, s72, 0x100
	v_mfma_f32_16x16x32_bf16 v[24:27], v[172:175], v[188:191], v[24:27]
	s_addc_u32 s73, s73, 0
	v_mfma_f32_16x16x32_bf16 v[20:23], v[164:167], v[196:199], v[20:23]
	s_cmpk_gt_u32 s74, 0x55
	v_mfma_f32_16x16x32_bf16 v[8:11], v[172:175], v[196:199], v[8:11]
	s_mov_b64 s[36:37], s[38:39]
	v_mfma_f32_16x16x32_bf16 v[4:7], v[164:167], v[204:207], v[4:7]
	s_setprio 2
	s_barrier
	v_mfma_f32_16x16x32_bf16 v[0:3], v[172:175], v[204:207], v[0:3]
	s_setprio 0
	s_cbranch_scc0 .LBB0_1249
	s_and_b64 vcc, exec, s[8:9]
	s_cbranch_vccz .LBB0_1252
	s_barrier
